# GEMM K-loops: first iteration peeled so the first MFMA per accumulator takes SrcC=0; the 64 accumulator clears per tile header removed (8 loops); on top of v_p14_wc
# speedup vs baseline: 1.0174x; 1.0092x over previous
; #define PG8_STAGE(bufoff, gbase, voff) do { _Pragma("unroll") for (int _i = 0; _i < 2; ++_i) \
;         __builtin_amdgcn_global_load_lds((const unsigned*)((const char*)(gbase) + (voff)[_i]), (PG8_LAS unsigned*)(lds + (bufoff) + ldsw + _i * 8192), 16, 0, 0); } while (0)
; #define PG8_LDA(dst, b, h) do { _Pragma("unroll") for (int m = 0; m < 4; ++m) _Pragma("unroll") for (int k = 0; k < 2; ++k) dst[m][k] = *(const PG8_LAS bf16x8*)(lds + PG8_SA(b, h) + aoff + m * 2048 + k * 1024); } while (0)
; #define PG8_LDB(dst, b, h) do { _Pragma("unroll") for (int n = 0; n < 2; ++n) _Pragma("unroll") for (int k = 0; k < 2; ++k) dst[n][k] = *(const PG8_LAS bf16x8*)(lds + PG8_SB(b, h) + boff + n * 2048 + k * 1024); } while (0)
; #define PG8_WAIT_V(n) asm volatile("s_waitcnt vmcnt(" #n ")" ::: "memory")
; #define PG8_WAIT_L(n) asm volatile("s_waitcnt lgkmcnt(" #n ")" ::: "memory")
; #define PG8_BAR __builtin_amdgcn_s_barrier()
; #define PG8_SCHED __builtin_amdgcn_sched_barrier(0)
; template <class Epi, class Sched, bool ALIGN_EPI = false, bool SP2 = false>
; __device__ __forceinline__ void gemm_phase(PG8_LAS unsigned char* lds, const Gemm g, const Sched& S, const Epi& E) {
;     ...
;         const bool has_next = S.next(ui + 1, nxt);
;         const char* nA = has_next ? (const char*)g.A + (size_t)nxt.pm * tstep : cA; const char* nB = has_next ? (const char*)g.Bt + (size_t)nxt.pn * tstep : cB;
;         for (int t = 0; t < nt; t += 2) {
;             const bool last = (t == nt - 2);
;             const char* a1 = cA + (size_t)(t + 1) * kstep;
;             const char* a2 = last ? nA : cA + (size_t)(t + 2) * kstep; const char* b2 = last ? nB : cB + (size_t)(t + 2) * kstep;
;             const char* a3 = a2 + kstep; const char* b3 = b2 + kstep;
;             if (last && has_next) S.a_ready(nxt);
;             if constexpr (SP2) {
;             PG8_LDB(B0, 0, 0); PG8_LDB(B1, 0, 1); PG8_SCHED; PG8_LDA(At, 0, 0); PG8_STAGE(PG8_SA(1, 1), a1 + hstep, voffA);
;             PG8_WAIT_V(8); PG8_WAIT_L(0); PG8_BAR; PG8_MMA(0, 0, At, B0); PG8_MMA(0, 1, At, B1); PG8_BAR; PG8_SCHED;
;             PG8_LDA(At, 0, 1); PG8_STAGE(PG8_SB(0, 0), b2, voffB); PG8_STAGE(PG8_SB(0, 1), b2 + hstep, voffB); PG8_STAGE(PG8_SA(0, 0), a2, voffA);
;             PG8_WAIT_V(8); PG8_WAIT_L(0); PG8_BAR; PG8_MMA(1, 0, At, B0); PG8_MMA(1, 1, At, B1); PG8_BAR; PG8_SCHED;
.LBB0_340:
	s_ashr_i32 s69, s68, 31
	s_lshl_b64 s[0:1], s[68:69], 20
	s_add_u32 s72, s17, s0
	s_addc_u32 s73, s19, s1
	s_and_b64 s[0:1], s[4:5], exec
	s_cselect_b32 s7, s73, s11
	s_cselect_b32 s9, s72, s10
	s_ashr_i32 s71, s70, 31
	s_lshl_b64 s[0:1], s[70:71], 20
	s_add_u32 s0, s28, s0
	s_addc_u32 s1, s29, s1
	s_and_b64 s[46:47], s[4:5], exec
	s_cselect_b32 s12, s1, s15
	s_cselect_b32 s45, s0, s14
	s_add_u32 s10, s10, 0x80080
	s_addc_u32 s11, s11, 0
	s_add_u32 s46, s14, 0x100
	s_addc_u32 s47, s15, 0
	s_mov_b32 s48, -2
	s_waitcnt lgkmcnt(0)
	ds_read_b128 v[146:149], v159
	ds_read_b128 v[150:153], v159 offset:1024
	ds_read_b128 v[164:167], v159 offset:2048
	ds_read_b128 v[168:171], v159 offset:3072
	ds_read_b128 v[172:175], v160
	ds_read_b128 v[176:179], v160 offset:1024
	ds_read_b128 v[180:183], v160 offset:2048
	ds_read_b128 v[184:187], v160 offset:3072
	s_add_u32 s14, s10, 0xfff80080
	s_addc_u32 s15, s11, -1
	s_cmp_eq_u32 s48, 28
	s_cselect_b32 s87, s7, s15
	s_cselect_b32 s86, s9, s14
	s_cselect_b32 s15, s12, s47
	s_cselect_b32 s14, s45, s46
	v_lshl_add_u64 v[154:155], s[10:11], 0, v[136:137]
	s_add_i32 m0, s91, 0xc000
	ds_read_b128 v[188:191], v161
	ds_read_b128 v[192:195], v161 offset:1024
	ds_read_b128 v[196:199], v161 offset:2048
	ds_read_b128 v[200:203], v161 offset:3072
	ds_read_b128 v[204:207], v161 offset:4096
	ds_read_b128 v[208:211], v161 offset:5120
	ds_read_b128 v[212:215], v161 offset:6144
	ds_read_b128 v[216:219], v161 offset:7168
	global_load_lds_dwordx4 v[154:155], off
	v_lshl_add_u64 v[154:155], s[10:11], 0, v[138:139]
	s_add_i32 m0, s91, 0xe000
	s_nop 0
	global_load_lds_dwordx4 v[154:155], off
	s_waitcnt vmcnt(8)
	s_waitcnt lgkmcnt(0)
	s_barrier
	s_setprio 1
	v_mfma_f32_16x16x32_bf16 v[124:127], v[146:149], v[188:191], 0
	v_mfma_f32_16x16x32_bf16 v[120:123], v[164:167], v[188:191], 0
	v_mfma_f32_16x16x32_bf16 v[108:111], v[146:149], v[196:199], 0
	v_mfma_f32_16x16x32_bf16 v[104:107], v[164:167], v[196:199], 0
	v_mfma_f32_16x16x32_bf16 v[92:95], v[146:149], v[204:207], 0
	v_mfma_f32_16x16x32_bf16 v[88:91], v[164:167], v[204:207], 0
	v_mfma_f32_16x16x32_bf16 v[76:79], v[146:149], v[212:215], 0
	v_mfma_f32_16x16x32_bf16 v[72:75], v[164:167], v[212:215], 0
	v_mfma_f32_16x16x32_bf16 v[124:127], v[150:153], v[192:195], v[124:127]
	v_mfma_f32_16x16x32_bf16 v[120:123], v[168:171], v[192:195], v[120:123]
	v_mfma_f32_16x16x32_bf16 v[108:111], v[150:153], v[200:203], v[108:111]
	v_mfma_f32_16x16x32_bf16 v[104:107], v[168:171], v[200:203], v[104:107]
	v_mfma_f32_16x16x32_bf16 v[92:95], v[150:153], v[208:211], v[92:95]
	v_mfma_f32_16x16x32_bf16 v[88:91], v[168:171], v[208:211], v[88:91]
	v_mfma_f32_16x16x32_bf16 v[76:79], v[150:153], v[216:219], v[76:79]
	v_mfma_f32_16x16x32_bf16 v[72:75], v[168:171], v[216:219], v[72:75]
	s_setprio 0
	s_setprio 1
	v_mfma_f32_16x16x32_bf16 v[116:119], v[172:175], v[188:191], 0
	v_mfma_f32_16x16x32_bf16 v[112:115], v[180:183], v[188:191], 0
	v_mfma_f32_16x16x32_bf16 v[100:103], v[172:175], v[196:199], 0
	v_mfma_f32_16x16x32_bf16 v[96:99], v[180:183], v[196:199], 0
	v_mfma_f32_16x16x32_bf16 v[84:87], v[172:175], v[204:207], 0
	v_mfma_f32_16x16x32_bf16 v[80:83], v[180:183], v[204:207], 0
	v_mfma_f32_16x16x32_bf16 v[68:71], v[172:175], v[212:215], 0
	v_mfma_f32_16x16x32_bf16 v[64:67], v[180:183], v[212:215], 0
	v_mfma_f32_16x16x32_bf16 v[116:119], v[176:179], v[192:195], v[116:119]
	v_mfma_f32_16x16x32_bf16 v[112:115], v[184:187], v[192:195], v[112:115]
	v_mfma_f32_16x16x32_bf16 v[100:103], v[176:179], v[200:203], v[100:103]
	v_mfma_f32_16x16x32_bf16 v[96:99], v[184:187], v[200:203], v[96:99]
	v_mfma_f32_16x16x32_bf16 v[84:87], v[176:179], v[208:211], v[84:87]
	v_mfma_f32_16x16x32_bf16 v[80:83], v[184:187], v[208:211], v[80:83]
	v_mfma_f32_16x16x32_bf16 v[68:71], v[176:179], v[216:219], v[68:71]
	v_mfma_f32_16x16x32_bf16 v[64:67], v[184:187], v[216:219], v[64:67]
	s_setprio 0
	s_barrier
	s_add_i32 s49, s42, s85
	v_lshl_add_u64 v[154:155], s[14:15], 0, v[130:131]
	s_mov_b32 m0, s49
	ds_read_b128 v[188:191], v161 offset:16384
	ds_read_b128 v[192:195], v161 offset:17408
	ds_read_b128 v[196:199], v161 offset:18432
	ds_read_b128 v[200:203], v161 offset:19456
	ds_read_b128 v[204:207], v161 offset:20480
	ds_read_b128 v[208:211], v161 offset:21504
	ds_read_b128 v[212:215], v161 offset:22528
	ds_read_b128 v[216:219], v161 offset:23552
	global_load_lds_dwordx4 v[154:155], off
	s_add_i32 m0, s49, 0x2000
	s_add_u32 s50, s14, 0x80000
	v_lshl_add_u64 v[220:221], s[14:15], 0, v[134:135]
	s_addc_u32 s51, s15, 0
	s_add_i32 s49, s43, s85
	global_load_lds_dwordx4 v[220:221], off
	v_lshl_add_u64 v[222:223], s[50:51], 0, v[130:131]
	s_mov_b32 m0, s49
	v_lshl_add_u64 v[224:225], s[86:87], 0, v[132:133]
	global_load_lds_dwordx4 v[222:223], off
	v_lshl_add_u64 v[222:223], s[50:51], 0, v[134:135]
	s_add_i32 m0, s49, 0x2000
	s_nop 0
	global_load_lds_dwordx4 v[222:223], off
	v_lshl_add_u64 v[222:223], s[86:87], 0, v[128:129]
	s_mov_b32 m0, s91
	s_nop 0
	global_load_lds_dwordx4 v[222:223], off
	s_mov_b32 m0, s93
	s_nop 0
	global_load_lds_dwordx4 v[224:225], off
	s_waitcnt vmcnt(8)
	s_waitcnt lgkmcnt(0)
	s_barrier
; #define PG8_STAGE(bufoff, gbase, voff) do { _Pragma("unroll") for (int _i = 0; _i < 2; ++_i) \
;         __builtin_amdgcn_global_load_lds((const unsigned*)((const char*)(gbase) + (voff)[_i]), (PG8_LAS unsigned*)(lds + (bufoff) + ldsw + _i * 8192), 16, 0, 0); } while (0)
; #define PG8_LDA(dst, b, h) do { _Pragma("unroll") for (int m = 0; m < 4; ++m) _Pragma("unroll") for (int k = 0; k < 2; ++k) dst[m][k] = *(const PG8_LAS bf16x8*)(lds + PG8_SA(b, h) + aoff + m * 2048 + k * 1024); } while (0)
; #define PG8_LDB(dst, b, h) do { _Pragma("unroll") for (int n = 0; n < 2; ++n) _Pragma("unroll") for (int k = 0; k < 2; ++k) dst[n][k] = *(const PG8_LAS bf16x8*)(lds + PG8_SB(b, h) + boff + n * 2048 + k * 1024); } while (0)
; #define PG8_MMA(ai, bj, At, Bt) do { __builtin_amdgcn_s_setprio(1); _Pragma("unroll") for (int m = 0; m < 4; ++m) _Pragma("unroll") for (int n = 0; n < 2; ++n) _Pragma("unroll") for (int k = 0; k < 2; ++k) \
;         acc[ai][bj][m][n] = __builtin_amdgcn_mfma_f32_16x16x32_bf16(Bt[n][k], At[m][k], acc[ai][bj][m][n], 0, 0, 0); __builtin_amdgcn_s_setprio(0); } while (0)
; #define PG8_WAIT_V(n) asm volatile("s_waitcnt vmcnt(" #n ")" ::: "memory")
; #define PG8_WAIT_L(n) asm volatile("s_waitcnt lgkmcnt(" #n ")" ::: "memory")
; #define PG8_BAR __builtin_amdgcn_s_barrier()
; #define PG8_SCHED __builtin_amdgcn_sched_barrier(0)
; template <class Epi, class Sched, bool ALIGN_EPI = false, bool SP2 = false>
; __device__ __forceinline__ void gemm_phase(PG8_LAS unsigned char* lds, const Gemm g, const Sched& S, const Epi& E) {
;     ...
;             PG8_WAIT_V(8); PG8_WAIT_L(0); PG8_BAR; PG8_MMA(1, 0, At, B0); PG8_MMA(1, 1, At, B1); PG8_BAR; PG8_SCHED;
;             PG8_LDB(B0, 1, 0); PG8_LDB(B1, 1, 1); PG8_SCHED; PG8_LDA(At, 1, 0); PG8_STAGE(PG8_SA(0, 1), a2 + hstep, voffA);
;             PG8_WAIT_V(8); PG8_WAIT_L(0); PG8_BAR; PG8_MMA(0, 0, At, B0); PG8_MMA(0, 1, At, B1); PG8_BAR; PG8_SCHED;
	s_setprio 1
	v_mfma_f32_16x16x32_bf16 v[60:63], v[146:149], v[188:191], 0
	v_mfma_f32_16x16x32_bf16 v[56:59], v[164:167], v[188:191], 0
	v_mfma_f32_16x16x32_bf16 v[44:47], v[146:149], v[196:199], 0
	v_mfma_f32_16x16x32_bf16 v[40:43], v[164:167], v[196:199], 0
	v_mfma_f32_16x16x32_bf16 v[28:31], v[146:149], v[204:207], 0
	v_mfma_f32_16x16x32_bf16 v[24:27], v[164:167], v[204:207], 0
	v_mfma_f32_16x16x32_bf16 v[12:15], v[146:149], v[212:215], 0
	v_mfma_f32_16x16x32_bf16 v[8:11], v[164:167], v[212:215], 0
	v_mfma_f32_16x16x32_bf16 v[60:63], v[150:153], v[192:195], v[60:63]
	v_mfma_f32_16x16x32_bf16 v[56:59], v[168:171], v[192:195], v[56:59]
	v_mfma_f32_16x16x32_bf16 v[44:47], v[150:153], v[200:203], v[44:47]
	v_mfma_f32_16x16x32_bf16 v[40:43], v[168:171], v[200:203], v[40:43]
	v_mfma_f32_16x16x32_bf16 v[28:31], v[150:153], v[208:211], v[28:31]
	v_mfma_f32_16x16x32_bf16 v[24:27], v[168:171], v[208:211], v[24:27]
	v_mfma_f32_16x16x32_bf16 v[12:15], v[150:153], v[216:219], v[12:15]
	v_mfma_f32_16x16x32_bf16 v[8:11], v[168:171], v[216:219], v[8:11]
	s_setprio 0
	s_setprio 1
	v_mfma_f32_16x16x32_bf16 v[52:55], v[172:175], v[188:191], 0
	v_mfma_f32_16x16x32_bf16 v[48:51], v[180:183], v[188:191], 0
	v_mfma_f32_16x16x32_bf16 v[36:39], v[172:175], v[196:199], 0
	v_mfma_f32_16x16x32_bf16 v[32:35], v[180:183], v[196:199], 0
	v_mfma_f32_16x16x32_bf16 v[20:23], v[172:175], v[204:207], 0
	v_mfma_f32_16x16x32_bf16 v[16:19], v[180:183], v[204:207], 0
	v_mfma_f32_16x16x32_bf16 v[4:7], v[172:175], v[212:215], 0
	v_mfma_f32_16x16x32_bf16 v[0:3], v[180:183], v[212:215], 0
	v_mfma_f32_16x16x32_bf16 v[52:55], v[176:179], v[192:195], v[52:55]
	v_mfma_f32_16x16x32_bf16 v[48:51], v[184:187], v[192:195], v[48:51]
	v_mfma_f32_16x16x32_bf16 v[36:39], v[176:179], v[200:203], v[36:39]
	v_mfma_f32_16x16x32_bf16 v[32:35], v[184:187], v[200:203], v[32:35]
	v_mfma_f32_16x16x32_bf16 v[20:23], v[176:179], v[208:211], v[20:23]
	v_mfma_f32_16x16x32_bf16 v[16:19], v[184:187], v[208:211], v[16:19]
	v_mfma_f32_16x16x32_bf16 v[4:7], v[176:179], v[216:219], v[4:7]
	v_mfma_f32_16x16x32_bf16 v[0:3], v[184:187], v[216:219], v[0:3]
	s_setprio 0
	s_barrier
	s_add_i32 s49, 0, 0x18000
	v_add_u32_e32 v163, s49, v158
	s_add_i32 s69, 0, 0x1c000
	ds_read_b128 v[146:149], v163
	ds_read_b128 v[150:153], v163 offset:1024
	ds_read_b128 v[164:167], v163 offset:2048
	ds_read_b128 v[168:171], v163 offset:3072
	v_add_u32_e32 v163, s69, v158
	ds_read_b128 v[172:175], v163
	ds_read_b128 v[176:179], v163 offset:1024
	ds_read_b128 v[180:183], v163 offset:2048
	ds_read_b128 v[184:187], v163 offset:3072
	s_add_u32 s50, s86, 0x80000
	s_addc_u32 s51, s87, 0
	s_mov_b32 m0, s95
	v_lshl_add_u64 v[226:227], s[50:51], 0, v[128:129]
	ds_read_b128 v[188:191], v161 offset:32768
	ds_read_b128 v[192:195], v161 offset:33792
	ds_read_b128 v[196:199], v161 offset:34816
	ds_read_b128 v[200:203], v161 offset:35840
	ds_read_b128 v[204:207], v161 offset:36864
	ds_read_b128 v[208:211], v161 offset:37888
	ds_read_b128 v[212:215], v161 offset:38912
	ds_read_b128 v[216:219], v161 offset:39936
	global_load_lds_dwordx4 v[226:227], off
	v_lshl_add_u64 v[226:227], s[50:51], 0, v[132:133]
	s_mov_b32 m0, s97
	s_nop 0
	global_load_lds_dwordx4 v[226:227], off
	s_waitcnt vmcnt(8)
	s_waitcnt lgkmcnt(0)
	s_barrier
	s_setprio 1
	v_mfma_f32_16x16x32_bf16 v[124:127], v[146:149], v[188:191], v[124:127]
	v_mfma_f32_16x16x32_bf16 v[120:123], v[164:167], v[188:191], v[120:123]
	v_mfma_f32_16x16x32_bf16 v[108:111], v[146:149], v[196:199], v[108:111]
	v_mfma_f32_16x16x32_bf16 v[104:107], v[164:167], v[196:199], v[104:107]
	v_mfma_f32_16x16x32_bf16 v[92:95], v[146:149], v[204:207], v[92:95]
	v_mfma_f32_16x16x32_bf16 v[88:91], v[164:167], v[204:207], v[88:91]
	v_mfma_f32_16x16x32_bf16 v[76:79], v[146:149], v[212:215], v[76:79]
	v_mfma_f32_16x16x32_bf16 v[72:75], v[164:167], v[212:215], v[72:75]
	v_mfma_f32_16x16x32_bf16 v[124:127], v[150:153], v[192:195], v[124:127]
	v_mfma_f32_16x16x32_bf16 v[120:123], v[168:171], v[192:195], v[120:123]
	v_mfma_f32_16x16x32_bf16 v[108:111], v[150:153], v[200:203], v[108:111]
	v_mfma_f32_16x16x32_bf16 v[104:107], v[168:171], v[200:203], v[104:107]
	v_mfma_f32_16x16x32_bf16 v[92:95], v[150:153], v[208:211], v[92:95]
	v_mfma_f32_16x16x32_bf16 v[88:91], v[168:171], v[208:211], v[88:91]
	v_mfma_f32_16x16x32_bf16 v[76:79], v[150:153], v[216:219], v[76:79]
	v_mfma_f32_16x16x32_bf16 v[72:75], v[168:171], v[216:219], v[72:75]
	s_setprio 0
	s_setprio 1
	v_mfma_f32_16x16x32_bf16 v[116:119], v[172:175], v[188:191], v[116:119]
	v_mfma_f32_16x16x32_bf16 v[112:115], v[180:183], v[188:191], v[112:115]
	v_mfma_f32_16x16x32_bf16 v[100:103], v[172:175], v[196:199], v[100:103]
	v_mfma_f32_16x16x32_bf16 v[96:99], v[180:183], v[196:199], v[96:99]
	v_mfma_f32_16x16x32_bf16 v[84:87], v[172:175], v[204:207], v[84:87]
	v_mfma_f32_16x16x32_bf16 v[80:83], v[180:183], v[204:207], v[80:83]
	v_mfma_f32_16x16x32_bf16 v[68:71], v[172:175], v[212:215], v[68:71]
	v_mfma_f32_16x16x32_bf16 v[64:67], v[180:183], v[212:215], v[64:67]
	v_mfma_f32_16x16x32_bf16 v[116:119], v[176:179], v[192:195], v[116:119]
	v_mfma_f32_16x16x32_bf16 v[112:115], v[184:187], v[192:195], v[112:115]
	v_mfma_f32_16x16x32_bf16 v[100:103], v[176:179], v[200:203], v[100:103]
	v_mfma_f32_16x16x32_bf16 v[96:99], v[184:187], v[200:203], v[96:99]
	v_mfma_f32_16x16x32_bf16 v[84:87], v[176:179], v[208:211], v[84:87]
	v_mfma_f32_16x16x32_bf16 v[80:83], v[184:187], v[208:211], v[80:83]
	v_mfma_f32_16x16x32_bf16 v[68:71], v[176:179], v[216:219], v[68:71]
	v_mfma_f32_16x16x32_bf16 v[64:67], v[184:187], v[216:219], v[64:67]
	s_setprio 0
	s_barrier
; #define PG8_STAGE(bufoff, gbase, voff) do { _Pragma("unroll") for (int _i = 0; _i < 2; ++_i) \
;         __builtin_amdgcn_global_load_lds((const unsigned*)((const char*)(gbase) + (voff)[_i]), (PG8_LAS unsigned*)(lds + (bufoff) + ldsw + _i * 8192), 16, 0, 0); } while (0)
; #define PG8_LDA(dst, b, h) do { _Pragma("unroll") for (int m = 0; m < 4; ++m) _Pragma("unroll") for (int k = 0; k < 2; ++k) dst[m][k] = *(const PG8_LAS bf16x8*)(lds + PG8_SA(b, h) + aoff + m * 2048 + k * 1024); } while (0)
; #define PG8_MMA(ai, bj, At, Bt) do { __builtin_amdgcn_s_setprio(1); _Pragma("unroll") for (int m = 0; m < 4; ++m) _Pragma("unroll") for (int n = 0; n < 2; ++n) _Pragma("unroll") for (int k = 0; k < 2; ++k) \
;         acc[ai][bj][m][n] = __builtin_amdgcn_mfma_f32_16x16x32_bf16(Bt[n][k], At[m][k], acc[ai][bj][m][n], 0, 0, 0); __builtin_amdgcn_s_setprio(0); } while (0)
; #define PG8_WAIT_V(n) asm volatile("s_waitcnt vmcnt(" #n ")" ::: "memory")
; #define PG8_WAIT_L(n) asm volatile("s_waitcnt lgkmcnt(" #n ")" ::: "memory")
; #define PG8_BAR __builtin_amdgcn_s_barrier()
; #define PG8_SCHED __builtin_amdgcn_sched_barrier(0)
; template <class Epi, class Sched, bool ALIGN_EPI = false, bool SP2 = false>
; __device__ __forceinline__ void gemm_phase(PG8_LAS unsigned char* lds, const Gemm g, const Sched& S, const Epi& E) {
;     ...
;         for (int t = 0; t < nt; t += 2) {
;     ...
;             PG8_LDA(At, 1, 1); PG8_STAGE(PG8_SB(1, 0), b3, voffB); PG8_STAGE(PG8_SB(1, 1), b3 + hstep, voffB); PG8_STAGE(PG8_SA(1, 0), a3, voffA);
;             PG8_WAIT_V(8); PG8_WAIT_L(0); PG8_BAR; PG8_MMA(1, 0, At, B0); PG8_MMA(1, 1, At, B1); PG8_BAR; PG8_SCHED;
	s_add_i32 s49, s49, s85
	v_lshl_add_u64 v[154:155], v[154:155], 0, s[82:83]
	s_mov_b32 m0, s49
	ds_read_b128 v[188:191], v161 offset:49152
	ds_read_b128 v[192:195], v161 offset:50176
	ds_read_b128 v[196:199], v161 offset:51200
	ds_read_b128 v[200:203], v161 offset:52224
	ds_read_b128 v[204:207], v161 offset:53248
	ds_read_b128 v[208:211], v161 offset:54272
	ds_read_b128 v[212:215], v161 offset:55296
	ds_read_b128 v[216:219], v161 offset:56320
	global_load_lds_dwordx4 v[154:155], off
	s_add_i32 m0, s49, 0x2000
	s_add_u32 s14, s14, 0x80080
	v_lshl_add_u64 v[154:155], v[220:221], 0, s[82:83]
	s_addc_u32 s15, s15, 0
	s_add_i32 s49, s69, s85
	global_load_lds_dwordx4 v[154:155], off
	v_lshl_add_u64 v[154:155], s[14:15], 0, v[130:131]
	s_mov_b32 m0, s49
	s_nop 0
	global_load_lds_dwordx4 v[154:155], off
	v_lshl_add_u64 v[154:155], s[14:15], 0, v[134:135]
	s_add_i32 m0, s49, 0x2000
	s_nop 0
	global_load_lds_dwordx4 v[154:155], off
	v_lshl_add_u64 v[154:155], v[222:223], 0, s[82:83]
	s_mov_b32 m0, s39
	s_nop 0
	global_load_lds_dwordx4 v[154:155], off
	v_lshl_add_u64 v[154:155], v[224:225], 0, s[82:83]
	s_mov_b32 m0, s40
	s_nop 0
	global_load_lds_dwordx4 v[154:155], off
	s_waitcnt vmcnt(8)
	s_waitcnt lgkmcnt(0)
	s_barrier
	s_setprio 1
	v_mfma_f32_16x16x32_bf16 v[60:63], v[146:149], v[188:191], v[60:63]
	v_mfma_f32_16x16x32_bf16 v[56:59], v[164:167], v[188:191], v[56:59]
	v_mfma_f32_16x16x32_bf16 v[44:47], v[146:149], v[196:199], v[44:47]
	v_mfma_f32_16x16x32_bf16 v[40:43], v[164:167], v[196:199], v[40:43]
	v_mfma_f32_16x16x32_bf16 v[28:31], v[146:149], v[204:207], v[28:31]
	v_mfma_f32_16x16x32_bf16 v[24:27], v[164:167], v[204:207], v[24:27]
	v_mfma_f32_16x16x32_bf16 v[12:15], v[146:149], v[212:215], v[12:15]
	v_mfma_f32_16x16x32_bf16 v[8:11], v[164:167], v[212:215], v[8:11]
	v_mfma_f32_16x16x32_bf16 v[60:63], v[150:153], v[192:195], v[60:63]
	v_mfma_f32_16x16x32_bf16 v[56:59], v[168:171], v[192:195], v[56:59]
	v_mfma_f32_16x16x32_bf16 v[44:47], v[150:153], v[200:203], v[44:47]
	v_mfma_f32_16x16x32_bf16 v[40:43], v[168:171], v[200:203], v[40:43]
	v_mfma_f32_16x16x32_bf16 v[28:31], v[150:153], v[208:211], v[28:31]
	v_mfma_f32_16x16x32_bf16 v[24:27], v[168:171], v[208:211], v[24:27]
	v_mfma_f32_16x16x32_bf16 v[12:15], v[150:153], v[216:219], v[12:15]
	v_mfma_f32_16x16x32_bf16 v[8:11], v[168:171], v[216:219], v[8:11]
	s_setprio 0
	s_setprio 1
	v_mfma_f32_16x16x32_bf16 v[52:55], v[172:175], v[188:191], v[52:55]
	v_mfma_f32_16x16x32_bf16 v[48:51], v[180:183], v[188:191], v[48:51]
	v_mfma_f32_16x16x32_bf16 v[36:39], v[172:175], v[196:199], v[36:39]
	v_mfma_f32_16x16x32_bf16 v[32:35], v[180:183], v[196:199], v[32:35]
	v_mfma_f32_16x16x32_bf16 v[20:23], v[172:175], v[204:207], v[20:23]
	v_mfma_f32_16x16x32_bf16 v[16:19], v[180:183], v[204:207], v[16:19]
	v_mfma_f32_16x16x32_bf16 v[4:7], v[172:175], v[212:215], v[4:7]
	v_mfma_f32_16x16x32_bf16 v[0:3], v[180:183], v[212:215], v[0:3]
	v_mfma_f32_16x16x32_bf16 v[52:55], v[176:179], v[192:195], v[52:55]
	v_mfma_f32_16x16x32_bf16 v[48:51], v[184:187], v[192:195], v[48:51]
	v_mfma_f32_16x16x32_bf16 v[36:39], v[176:179], v[200:203], v[36:39]
	v_mfma_f32_16x16x32_bf16 v[32:35], v[184:187], v[200:203], v[32:35]
	v_mfma_f32_16x16x32_bf16 v[20:23], v[176:179], v[208:211], v[20:23]
	v_mfma_f32_16x16x32_bf16 v[16:19], v[184:187], v[208:211], v[16:19]
	v_mfma_f32_16x16x32_bf16 v[4:7], v[176:179], v[216:219], v[4:7]
	v_mfma_f32_16x16x32_bf16 v[0:3], v[184:187], v[216:219], v[0:3]
	s_setprio 0
	s_barrier
	s_add_i32 s48, s48, 2
	s_add_u32 s10, s10, 0x100
	s_addc_u32 s11, s11, 0
	s_add_u32 s46, s46, 0x100
	s_addc_u32 s47, s47, 0
	s_cmp_gt_u32 s48, 29

; #define PG8_STAGE(bufoff, gbase, voff) do { _Pragma("unroll") for (int _i = 0; _i < 2; ++_i) \
;         __builtin_amdgcn_global_load_lds((const unsigned*)((const char*)(gbase) + (voff)[_i]), (PG8_LAS unsigned*)(lds + (bufoff) + ldsw + _i * 8192), 16, 0, 0); } while (0)
; #define PG8_LDA(dst, b, h) do { _Pragma("unroll") for (int m = 0; m < 4; ++m) _Pragma("unroll") for (int k = 0; k < 2; ++k) dst[m][k] = *(const PG8_LAS bf16x8*)(lds + PG8_SA(b, h) + aoff + m * 2048 + k * 1024); } while (0)
; #define PG8_LDB(dst, b, h) do { _Pragma("unroll") for (int n = 0; n < 2; ++n) _Pragma("unroll") for (int k = 0; k < 2; ++k) dst[n][k] = *(const PG8_LAS bf16x8*)(lds + PG8_SB(b, h) + boff + n * 2048 + k * 1024); } while (0)
; #define PG8_MMA(ai, bj, At, Bt) do { __builtin_amdgcn_s_setprio(1); _Pragma("unroll") for (int m = 0; m < 4; ++m) _Pragma("unroll") for (int n = 0; n < 2; ++n) _Pragma("unroll") for (int k = 0; k < 2; ++k) \
;         acc[ai][bj][m][n] = __builtin_amdgcn_mfma_f32_16x16x32_bf16(Bt[n][k], At[m][k], acc[ai][bj][m][n], 0, 0, 0); __builtin_amdgcn_s_setprio(0); } while (0)
; #define PG8_WAIT_V(n) asm volatile("s_waitcnt vmcnt(" #n ")" ::: "memory")
; #define PG8_WAIT_L(n) asm volatile("s_waitcnt lgkmcnt(" #n ")" ::: "memory")
; #define PG8_BAR __builtin_amdgcn_s_barrier()
; template <class Epi, class Sched, bool ALIGN_EPI = false, bool SP2 = false>
; __device__ __forceinline__ void gemm_phase(PG8_LAS unsigned char* lds, const Gemm g, const Sched& S, const Epi& E) {
;     ...
;             const char* a1 = cA + (size_t)(t + 1) * kstep;
;             const char* a2 = last ? nA : cA + (size_t)(t + 2) * kstep; const char* b2 = last ? nB : cB + (size_t)(t + 2) * kstep;
;             const char* a3 = a2 + kstep; const char* b3 = b2 + kstep;
;             if (last && has_next) S.a_ready(nxt);
;             if constexpr (SP2) {
;             PG8_LDB(B0, 0, 0); PG8_LDB(B1, 0, 1); PG8_SCHED; PG8_LDA(At, 0, 0); PG8_STAGE(PG8_SA(1, 1), a1 + hstep, voffA);
;             PG8_WAIT_V(8); PG8_WAIT_L(0); PG8_BAR; PG8_MMA(0, 0, At, B0); PG8_MMA(0, 1, At, B1); PG8_BAR; PG8_SCHED;
;     ...
;         for (int a = 0; a < 2; ++a)
; #pragma unroll
;             for (int b = 0; b < 2; ++b)
; #pragma unroll
;                 for (int m = 0; m < 4; ++m)
; #pragma unroll
;                     for (int n = 0; n < 2; ++n) acc[a][b][m][n] = (f32x4){0.f, 0.f, 0.f, 0.f};
.LBB0_917:
	v_mov_b32_e32 v123, 0
	s_andn2_b64 vcc, exec, s[66:67]
	v_mov_b32_e32 v122, v123
	v_mov_b32_e32 v121, v123
	v_mov_b32_e32 v120, v123
	v_mov_b32_e32 v127, v123
	v_mov_b32_e32 v126, v123
	v_mov_b32_e32 v125, v123
	v_mov_b32_e32 v124, v123
	v_mov_b32_e32 v111, v123
	v_mov_b32_e32 v110, v123
	v_mov_b32_e32 v109, v123
	v_mov_b32_e32 v108, v123
	v_mov_b32_e32 v107, v123
	v_mov_b32_e32 v106, v123
	v_mov_b32_e32 v105, v123
	v_mov_b32_e32 v104, v123
	v_mov_b32_e32 v95, v123
	v_mov_b32_e32 v94, v123
	v_mov_b32_e32 v93, v123
	v_mov_b32_e32 v92, v123
	v_mov_b32_e32 v91, v123
	v_mov_b32_e32 v90, v123
	v_mov_b32_e32 v89, v123
	v_mov_b32_e32 v88, v123
	v_mov_b32_e32 v79, v123
	v_mov_b32_e32 v78, v123
	v_mov_b32_e32 v77, v123
	v_mov_b32_e32 v76, v123
	v_mov_b32_e32 v75, v123
	v_mov_b32_e32 v74, v123
	v_mov_b32_e32 v73, v123
	v_mov_b32_e32 v72, v123
	v_mov_b32_e32 v119, v123
	v_mov_b32_e32 v118, v123
	v_mov_b32_e32 v117, v123
	v_mov_b32_e32 v116, v123
	v_mov_b32_e32 v115, v123
	v_mov_b32_e32 v114, v123
	v_mov_b32_e32 v113, v123
	v_mov_b32_e32 v112, v123
	v_mov_b32_e32 v103, v123
	v_mov_b32_e32 v102, v123
	v_mov_b32_e32 v101, v123
	v_mov_b32_e32 v100, v123
	v_mov_b32_e32 v99, v123
	v_mov_b32_e32 v98, v123
	v_mov_b32_e32 v97, v123
	v_mov_b32_e32 v96, v123
	v_mov_b32_e32 v87, v123
	v_mov_b32_e32 v86, v123
	v_mov_b32_e32 v85, v123
	v_mov_b32_e32 v84, v123
	v_mov_b32_e32 v83, v123
	v_mov_b32_e32 v82, v123
	v_mov_b32_e32 v81, v123
	v_mov_b32_e32 v80, v123
	v_mov_b32_e32 v71, v123
	v_mov_b32_e32 v70, v123
	v_mov_b32_e32 v69, v123
	v_mov_b32_e32 v68, v123
	v_mov_b32_e32 v67, v123
	v_mov_b32_e32 v66, v123
	v_mov_b32_e32 v65, v123
	v_mov_b32_e32 v64, v123
	v_mov_b32_e32 v63, v123
	v_mov_b32_e32 v62, v123
	v_mov_b32_e32 v61, v123
	v_mov_b32_e32 v60, v123
	v_mov_b32_e32 v59, v123
	v_mov_b32_e32 v58, v123
	v_mov_b32_e32 v57, v123
	v_mov_b32_e32 v56, v123
	v_mov_b32_e32 v47, v123
	v_mov_b32_e32 v46, v123
	v_mov_b32_e32 v45, v123
	v_mov_b32_e32 v44, v123
	v_mov_b32_e32 v43, v123
	v_mov_b32_e32 v42, v123
	v_mov_b32_e32 v41, v123
	v_mov_b32_e32 v40, v123
	v_mov_b32_e32 v31, v123
	v_mov_b32_e32 v30, v123
	v_mov_b32_e32 v29, v123
	v_mov_b32_e32 v28, v123
	v_mov_b32_e32 v27, v123
	v_mov_b32_e32 v26, v123
	v_mov_b32_e32 v25, v123
	v_mov_b32_e32 v24, v123
	v_mov_b32_e32 v15, v123
	v_mov_b32_e32 v14, v123
	v_mov_b32_e32 v13, v123
	v_mov_b32_e32 v12, v123
	v_mov_b32_e32 v11, v123
	v_mov_b32_e32 v10, v123
	v_mov_b32_e32 v9, v123
	v_mov_b32_e32 v8, v123
	v_mov_b32_e32 v55, v123
	v_mov_b32_e32 v54, v123
	v_mov_b32_e32 v53, v123
	v_mov_b32_e32 v52, v123
	v_mov_b32_e32 v51, v123
	v_mov_b32_e32 v50, v123
	v_mov_b32_e32 v49, v123
	v_mov_b32_e32 v48, v123
	v_mov_b32_e32 v39, v123
	v_mov_b32_e32 v38, v123
	v_mov_b32_e32 v37, v123
	v_mov_b32_e32 v36, v123
	v_mov_b32_e32 v35, v123
	v_mov_b32_e32 v34, v123
	v_mov_b32_e32 v33, v123
	v_mov_b32_e32 v32, v123
	v_mov_b32_e32 v23, v123
	v_mov_b32_e32 v22, v123
	v_mov_b32_e32 v21, v123
	v_mov_b32_e32 v20, v123
	v_mov_b32_e32 v19, v123
	v_mov_b32_e32 v18, v123
	v_mov_b32_e32 v17, v123
	v_mov_b32_e32 v16, v123
	v_mov_b32_e32 v7, v123
	v_mov_b32_e32 v6, v123
	v_mov_b32_e32 v5, v123
	v_mov_b32_e32 v4, v123
	v_mov_b32_e32 v3, v123
	v_mov_b32_e32 v2, v123
	v_mov_b32_e32 v1, v123
	v_mov_b32_e32 v0, v123
	s_cbranch_vccnz .LBB0_920
	s_add_u32 s0, s0, 0x80
	s_addc_u32 s1, s1, 0
	s_add_u32 s44, s72, 0x100
	s_addc_u32 s45, s73, 0
	s_mov_b32 s6, 0
	ds_read_b128 v[128:131], v187
	ds_read_b128 v[132:135], v187 offset:1024
	ds_read_b128 v[154:157], v187 offset:2048
	ds_read_b128 v[158:161], v187 offset:3072
	ds_read_b128 v[162:165], v188
	ds_read_b128 v[166:169], v188 offset:1024
	ds_read_b128 v[170:173], v188 offset:2048
	ds_read_b128 v[174:177], v188 offset:3072
	s_add_i32 s46, s6, 2
	s_add_u32 s47, s0, 0x80
	s_addc_u32 s7, s1, 0
	s_cmp_eq_u32 s93, s6
	s_cselect_b32 s6, s16, s47
	s_cselect_b32 s7, s17, s7
	s_cselect_b32 s49, s19, s45
	s_cselect_b32 s48, s18, s44
	v_lshl_add_u64 v[182:183], s[0:1], 0, v[146:147]
	s_add_i32 m0, s85, 0xc000
	ds_read_b128 v[178:181], v189
	ds_read_b128 v[192:195], v189 offset:1024
	ds_read_b128 v[196:199], v189 offset:2048
	ds_read_b128 v[200:203], v189 offset:3072
	ds_read_b128 v[204:207], v189 offset:4096
	ds_read_b128 v[208:211], v189 offset:5120
	ds_read_b128 v[212:215], v189 offset:6144
	ds_read_b128 v[216:219], v189 offset:7168
	global_load_lds_dwordx4 v[182:183], off
	v_lshl_add_u64 v[182:183], s[0:1], 0, v[148:149]
	s_add_i32 m0, s85, 0xe000
	s_nop 0
	global_load_lds_dwordx4 v[182:183], off
	s_waitcnt vmcnt(8)
	s_waitcnt lgkmcnt(0)
	s_barrier
; #define PG8_STAGE(bufoff, gbase, voff) do { _Pragma("unroll") for (int _i = 0; _i < 2; ++_i) \
;         __builtin_amdgcn_global_load_lds((const unsigned*)((const char*)(gbase) + (voff)[_i]), (PG8_LAS unsigned*)(lds + (bufoff) + ldsw + _i * 8192), 16, 0, 0); } while (0)
; #define PG8_LDA(dst, b, h) do { _Pragma("unroll") for (int m = 0; m < 4; ++m) _Pragma("unroll") for (int k = 0; k < 2; ++k) dst[m][k] = *(const PG8_LAS bf16x8*)(lds + PG8_SA(b, h) + aoff + m * 2048 + k * 1024); } while (0)
; #define PG8_MMA(ai, bj, At, Bt) do { __builtin_amdgcn_s_setprio(1); _Pragma("unroll") for (int m = 0; m < 4; ++m) _Pragma("unroll") for (int n = 0; n < 2; ++n) _Pragma("unroll") for (int k = 0; k < 2; ++k) \
;         acc[ai][bj][m][n] = __builtin_amdgcn_mfma_f32_16x16x32_bf16(Bt[n][k], At[m][k], acc[ai][bj][m][n], 0, 0, 0); __builtin_amdgcn_s_setprio(0); } while (0)
; #define PG8_WAIT_V(n) asm volatile("s_waitcnt vmcnt(" #n ")" ::: "memory")
; #define PG8_WAIT_L(n) asm volatile("s_waitcnt lgkmcnt(" #n ")" ::: "memory")
; #define PG8_BAR __builtin_amdgcn_s_barrier()
; #define PG8_SCHED __builtin_amdgcn_sched_barrier(0)
; template <class Epi, class Sched, bool ALIGN_EPI = false, bool SP2 = false>
; __device__ __forceinline__ void gemm_phase(PG8_LAS unsigned char* lds, const Gemm g, const Sched& S, const Epi& E) {
;     ...
;             PG8_WAIT_V(8); PG8_WAIT_L(0); PG8_BAR; PG8_MMA(0, 0, At, B0); PG8_MMA(0, 1, At, B1); PG8_BAR; PG8_SCHED;
;             PG8_LDA(At, 0, 1); PG8_STAGE(PG8_SB(0, 0), b2, voffB); PG8_STAGE(PG8_SB(0, 1), b2 + hstep, voffB); PG8_STAGE(PG8_SA(0, 0), a2, voffA);
;             PG8_WAIT_V(8); PG8_WAIT_L(0); PG8_BAR; PG8_MMA(1, 0, At, B0); PG8_MMA(1, 1, At, B1); PG8_BAR; PG8_SCHED;
	s_setprio 1
	v_mfma_f32_16x16x32_bf16 v[120:123], v[128:131], v[178:181], 0
	v_mfma_f32_16x16x32_bf16 v[124:127], v[154:157], v[178:181], 0
	v_mfma_f32_16x16x32_bf16 v[108:111], v[128:131], v[196:199], 0
	v_mfma_f32_16x16x32_bf16 v[104:107], v[154:157], v[196:199], 0
	v_mfma_f32_16x16x32_bf16 v[92:95], v[128:131], v[204:207], 0
	v_mfma_f32_16x16x32_bf16 v[88:91], v[154:157], v[204:207], 0
	v_mfma_f32_16x16x32_bf16 v[76:79], v[128:131], v[212:215], 0
	v_mfma_f32_16x16x32_bf16 v[72:75], v[154:157], v[212:215], 0
	v_mfma_f32_16x16x32_bf16 v[120:123], v[132:135], v[192:195], v[120:123]
	v_mfma_f32_16x16x32_bf16 v[124:127], v[158:161], v[192:195], v[124:127]
	v_mfma_f32_16x16x32_bf16 v[108:111], v[132:135], v[200:203], v[108:111]
	v_mfma_f32_16x16x32_bf16 v[104:107], v[158:161], v[200:203], v[104:107]
	v_mfma_f32_16x16x32_bf16 v[92:95], v[132:135], v[208:211], v[92:95]
	v_mfma_f32_16x16x32_bf16 v[88:91], v[158:161], v[208:211], v[88:91]
	v_mfma_f32_16x16x32_bf16 v[76:79], v[132:135], v[216:219], v[76:79]
	v_mfma_f32_16x16x32_bf16 v[72:75], v[158:161], v[216:219], v[72:75]
	s_setprio 0
	s_setprio 1
	v_mfma_f32_16x16x32_bf16 v[116:119], v[162:165], v[178:181], 0
	v_mfma_f32_16x16x32_bf16 v[112:115], v[170:173], v[178:181], 0
	v_mfma_f32_16x16x32_bf16 v[100:103], v[162:165], v[196:199], 0
	v_mfma_f32_16x16x32_bf16 v[96:99], v[170:173], v[196:199], 0
	v_mfma_f32_16x16x32_bf16 v[84:87], v[162:165], v[204:207], 0
	v_mfma_f32_16x16x32_bf16 v[80:83], v[170:173], v[204:207], 0
	v_mfma_f32_16x16x32_bf16 v[68:71], v[162:165], v[212:215], 0
	v_mfma_f32_16x16x32_bf16 v[64:67], v[170:173], v[212:215], 0
	v_mfma_f32_16x16x32_bf16 v[116:119], v[166:169], v[192:195], v[116:119]
	v_mfma_f32_16x16x32_bf16 v[112:115], v[174:177], v[192:195], v[112:115]
	v_mfma_f32_16x16x32_bf16 v[100:103], v[166:169], v[200:203], v[100:103]
	v_mfma_f32_16x16x32_bf16 v[96:99], v[174:177], v[200:203], v[96:99]
	v_mfma_f32_16x16x32_bf16 v[84:87], v[166:169], v[208:211], v[84:87]
	v_mfma_f32_16x16x32_bf16 v[80:83], v[174:177], v[208:211], v[80:83]
	v_mfma_f32_16x16x32_bf16 v[68:71], v[166:169], v[216:219], v[68:71]
	v_mfma_f32_16x16x32_bf16 v[64:67], v[174:177], v[216:219], v[64:67]
	s_setprio 0
	s_barrier
	s_add_i32 s47, s3, s84
	v_lshl_add_u64 v[182:183], s[48:49], 0, v[138:139]
	s_mov_b32 m0, s47
	ds_read_b128 v[178:181], v189 offset:16384
	ds_read_b128 v[192:195], v189 offset:17408
	ds_read_b128 v[196:199], v189 offset:18432
	ds_read_b128 v[200:203], v189 offset:19456
	ds_read_b128 v[204:207], v189 offset:20480
	ds_read_b128 v[208:211], v189 offset:21504
	ds_read_b128 v[212:215], v189 offset:22528
	ds_read_b128 v[216:219], v189 offset:23552
	global_load_lds_dwordx4 v[182:183], off
	s_add_i32 m0, s47, 0x2000
	v_lshl_add_u64 v[220:221], s[48:49], 0, v[142:143]
	s_add_u32 s48, s48, s10
	s_addc_u32 s49, s49, s11
	s_add_i32 s47, s8, s84
	global_load_lds_dwordx4 v[220:221], off
	v_lshl_add_u64 v[222:223], s[48:49], 0, v[138:139]
	s_mov_b32 m0, s47
	v_lshl_add_u64 v[224:225], s[48:49], 0, v[142:143]
	global_load_lds_dwordx4 v[222:223], off
	s_add_i32 m0, s47, 0x2000
	v_lshl_add_u64 v[226:227], s[6:7], 0, v[136:137]
	global_load_lds_dwordx4 v[224:225], off
	s_mov_b32 m0, s85
	v_lshl_add_u64 v[228:229], s[6:7], 0, v[140:141]
	global_load_lds_dwordx4 v[226:227], off
	s_mov_b32 m0, s86
	s_nop 0
	global_load_lds_dwordx4 v[228:229], off
	s_waitcnt vmcnt(8)
	s_waitcnt lgkmcnt(0)
	s_barrier
	s_setprio 1
	v_mfma_f32_16x16x32_bf16 v[60:63], v[128:131], v[178:181], 0
	v_mfma_f32_16x16x32_bf16 v[56:59], v[154:157], v[178:181], 0
	v_mfma_f32_16x16x32_bf16 v[44:47], v[128:131], v[196:199], 0
	v_mfma_f32_16x16x32_bf16 v[40:43], v[154:157], v[196:199], 0
	v_mfma_f32_16x16x32_bf16 v[28:31], v[128:131], v[204:207], 0
	v_mfma_f32_16x16x32_bf16 v[24:27], v[154:157], v[204:207], 0
	v_mfma_f32_16x16x32_bf16 v[12:15], v[128:131], v[212:215], 0
	v_mfma_f32_16x16x32_bf16 v[8:11], v[154:157], v[212:215], 0
	v_mfma_f32_16x16x32_bf16 v[60:63], v[132:135], v[192:195], v[60:63]
	v_mfma_f32_16x16x32_bf16 v[56:59], v[158:161], v[192:195], v[56:59]
	v_mfma_f32_16x16x32_bf16 v[44:47], v[132:135], v[200:203], v[44:47]
	v_mfma_f32_16x16x32_bf16 v[40:43], v[158:161], v[200:203], v[40:43]
	v_mfma_f32_16x16x32_bf16 v[28:31], v[132:135], v[208:211], v[28:31]
	v_mfma_f32_16x16x32_bf16 v[24:27], v[158:161], v[208:211], v[24:27]
	v_mfma_f32_16x16x32_bf16 v[12:15], v[132:135], v[216:219], v[12:15]
	v_mfma_f32_16x16x32_bf16 v[8:11], v[158:161], v[216:219], v[8:11]
	s_setprio 0
	s_setprio 1
	v_mfma_f32_16x16x32_bf16 v[52:55], v[162:165], v[178:181], 0
	v_mfma_f32_16x16x32_bf16 v[48:51], v[170:173], v[178:181], 0
	v_mfma_f32_16x16x32_bf16 v[36:39], v[162:165], v[196:199], 0
	v_mfma_f32_16x16x32_bf16 v[32:35], v[170:173], v[196:199], 0
	v_mfma_f32_16x16x32_bf16 v[20:23], v[162:165], v[204:207], 0
	v_mfma_f32_16x16x32_bf16 v[16:19], v[170:173], v[204:207], 0
	v_mfma_f32_16x16x32_bf16 v[4:7], v[162:165], v[212:215], 0
	v_mfma_f32_16x16x32_bf16 v[0:3], v[170:173], v[212:215], 0
	v_mfma_f32_16x16x32_bf16 v[52:55], v[166:169], v[192:195], v[52:55]
	v_mfma_f32_16x16x32_bf16 v[48:51], v[174:177], v[192:195], v[48:51]
	v_mfma_f32_16x16x32_bf16 v[36:39], v[166:169], v[200:203], v[36:39]
	v_mfma_f32_16x16x32_bf16 v[32:35], v[174:177], v[200:203], v[32:35]
	v_mfma_f32_16x16x32_bf16 v[20:23], v[166:169], v[208:211], v[20:23]
	v_mfma_f32_16x16x32_bf16 v[16:19], v[174:177], v[208:211], v[16:19]
	v_mfma_f32_16x16x32_bf16 v[4:7], v[166:169], v[216:219], v[4:7]
	v_mfma_f32_16x16x32_bf16 v[0:3], v[174:177], v[216:219], v[0:3]
	s_setprio 0
	s_barrier
; #define PG8_STAGE(bufoff, gbase, voff) do { _Pragma("unroll") for (int _i = 0; _i < 2; ++_i) \
;         __builtin_amdgcn_global_load_lds((const unsigned*)((const char*)(gbase) + (voff)[_i]), (PG8_LAS unsigned*)(lds + (bufoff) + ldsw + _i * 8192), 16, 0, 0); } while (0)
; #define PG8_LDA(dst, b, h) do { _Pragma("unroll") for (int m = 0; m < 4; ++m) _Pragma("unroll") for (int k = 0; k < 2; ++k) dst[m][k] = *(const PG8_LAS bf16x8*)(lds + PG8_SA(b, h) + aoff + m * 2048 + k * 1024); } while (0)
; #define PG8_LDB(dst, b, h) do { _Pragma("unroll") for (int n = 0; n < 2; ++n) _Pragma("unroll") for (int k = 0; k < 2; ++k) dst[n][k] = *(const PG8_LAS bf16x8*)(lds + PG8_SB(b, h) + boff + n * 2048 + k * 1024); } while (0)
; #define PG8_MMA(ai, bj, At, Bt) do { __builtin_amdgcn_s_setprio(1); _Pragma("unroll") for (int m = 0; m < 4; ++m) _Pragma("unroll") for (int n = 0; n < 2; ++n) _Pragma("unroll") for (int k = 0; k < 2; ++k) \
;         acc[ai][bj][m][n] = __builtin_amdgcn_mfma_f32_16x16x32_bf16(Bt[n][k], At[m][k], acc[ai][bj][m][n], 0, 0, 0); __builtin_amdgcn_s_setprio(0); } while (0)
; #define PG8_WAIT_V(n) asm volatile("s_waitcnt vmcnt(" #n ")" ::: "memory")
; #define PG8_WAIT_L(n) asm volatile("s_waitcnt lgkmcnt(" #n ")" ::: "memory")
; #define PG8_BAR __builtin_amdgcn_s_barrier()
; #define PG8_SCHED __builtin_amdgcn_sched_barrier(0)
; template <class Epi, class Sched, bool ALIGN_EPI = false, bool SP2 = false>
; __device__ __forceinline__ void gemm_phase(PG8_LAS unsigned char* lds, const Gemm g, const Sched& S, const Epi& E) {
;     ...
;             PG8_LDB(B0, 1, 0); PG8_LDB(B1, 1, 1); PG8_SCHED; PG8_LDA(At, 1, 0); PG8_STAGE(PG8_SA(0, 1), a2 + hstep, voffA);
;             PG8_WAIT_V(8); PG8_WAIT_L(0); PG8_BAR; PG8_MMA(0, 0, At, B0); PG8_MMA(0, 1, At, B1); PG8_BAR; PG8_SCHED;
;             PG8_LDA(At, 1, 1); PG8_STAGE(PG8_SB(1, 0), b3, voffB); PG8_STAGE(PG8_SB(1, 1), b3 + hstep, voffB); PG8_STAGE(PG8_SA(1, 0), a3, voffA);
;             PG8_WAIT_V(8); PG8_WAIT_L(0); PG8_BAR; PG8_MMA(1, 0, At, B0); PG8_MMA(1, 1, At, B1); PG8_BAR; PG8_SCHED;
	s_add_i32 s47, 0, 0x18000
	s_add_i32 s48, 0, 0x1c000
	v_add_u32_e32 v158, s47, v186
	v_add_u32_e32 v174, s48, v186
	ds_read_b128 v[128:131], v158
	ds_read_b128 v[132:135], v158 offset:1024
	ds_read_b128 v[154:157], v158 offset:2048
	ds_read_b128 v[158:161], v158 offset:3072
	ds_read_b128 v[162:165], v174
	ds_read_b128 v[166:169], v174 offset:1024
	ds_read_b128 v[170:173], v174 offset:2048
	ds_read_b128 v[174:177], v174 offset:3072
	s_add_u32 s6, s6, s10
	s_addc_u32 s7, s7, s11
	s_mov_b32 m0, s87
	v_lshl_add_u64 v[230:231], s[6:7], 0, v[136:137]
	ds_read_b128 v[178:181], v189 offset:32768
	ds_read_b128 v[192:195], v189 offset:33792
	ds_read_b128 v[196:199], v189 offset:34816
	ds_read_b128 v[200:203], v189 offset:35840
	ds_read_b128 v[204:207], v189 offset:36864
	ds_read_b128 v[208:211], v189 offset:37888
	ds_read_b128 v[212:215], v189 offset:38912
	ds_read_b128 v[216:219], v189 offset:39936
	global_load_lds_dwordx4 v[230:231], off
	v_lshl_add_u64 v[230:231], s[6:7], 0, v[140:141]
	s_mov_b32 m0, s88
	s_nop 0
	global_load_lds_dwordx4 v[230:231], off
	s_waitcnt vmcnt(8)
	s_waitcnt lgkmcnt(0)
	s_barrier
	s_setprio 1
	v_mfma_f32_16x16x32_bf16 v[120:123], v[128:131], v[178:181], v[120:123]
	v_mfma_f32_16x16x32_bf16 v[124:127], v[154:157], v[178:181], v[124:127]
	v_mfma_f32_16x16x32_bf16 v[108:111], v[128:131], v[196:199], v[108:111]
	v_mfma_f32_16x16x32_bf16 v[104:107], v[154:157], v[196:199], v[104:107]
	v_mfma_f32_16x16x32_bf16 v[92:95], v[128:131], v[204:207], v[92:95]
	v_mfma_f32_16x16x32_bf16 v[88:91], v[154:157], v[204:207], v[88:91]
	v_mfma_f32_16x16x32_bf16 v[76:79], v[128:131], v[212:215], v[76:79]
	v_mfma_f32_16x16x32_bf16 v[72:75], v[154:157], v[212:215], v[72:75]
	v_mfma_f32_16x16x32_bf16 v[120:123], v[132:135], v[192:195], v[120:123]
	v_mfma_f32_16x16x32_bf16 v[124:127], v[158:161], v[192:195], v[124:127]
	v_mfma_f32_16x16x32_bf16 v[108:111], v[132:135], v[200:203], v[108:111]
	v_mfma_f32_16x16x32_bf16 v[104:107], v[158:161], v[200:203], v[104:107]
	v_mfma_f32_16x16x32_bf16 v[92:95], v[132:135], v[208:211], v[92:95]
	v_mfma_f32_16x16x32_bf16 v[88:91], v[158:161], v[208:211], v[88:91]
	v_mfma_f32_16x16x32_bf16 v[76:79], v[132:135], v[216:219], v[76:79]
	v_mfma_f32_16x16x32_bf16 v[72:75], v[158:161], v[216:219], v[72:75]
	s_setprio 0
	s_setprio 1
	v_mfma_f32_16x16x32_bf16 v[116:119], v[162:165], v[178:181], v[116:119]
	v_mfma_f32_16x16x32_bf16 v[112:115], v[170:173], v[178:181], v[112:115]
	v_mfma_f32_16x16x32_bf16 v[100:103], v[162:165], v[196:199], v[100:103]
	v_mfma_f32_16x16x32_bf16 v[96:99], v[170:173], v[196:199], v[96:99]
	v_mfma_f32_16x16x32_bf16 v[84:87], v[162:165], v[204:207], v[84:87]
	v_mfma_f32_16x16x32_bf16 v[80:83], v[170:173], v[204:207], v[80:83]
	v_mfma_f32_16x16x32_bf16 v[68:71], v[162:165], v[212:215], v[68:71]
	v_mfma_f32_16x16x32_bf16 v[64:67], v[170:173], v[212:215], v[64:67]
	v_mfma_f32_16x16x32_bf16 v[116:119], v[166:169], v[192:195], v[116:119]
	v_mfma_f32_16x16x32_bf16 v[112:115], v[174:177], v[192:195], v[112:115]
	v_mfma_f32_16x16x32_bf16 v[100:103], v[166:169], v[200:203], v[100:103]
	v_mfma_f32_16x16x32_bf16 v[96:99], v[174:177], v[200:203], v[96:99]
	v_mfma_f32_16x16x32_bf16 v[84:87], v[166:169], v[208:211], v[84:87]
	v_mfma_f32_16x16x32_bf16 v[80:83], v[174:177], v[208:211], v[80:83]
	v_mfma_f32_16x16x32_bf16 v[68:71], v[166:169], v[216:219], v[68:71]
	v_mfma_f32_16x16x32_bf16 v[64:67], v[174:177], v[216:219], v[64:67]
	s_setprio 0
	s_barrier
	s_add_i32 s6, s47, s84
	v_lshl_add_u64 v[182:183], v[182:183], 0, s[64:65]
	s_mov_b32 m0, s6
	ds_read_b128 v[178:181], v189 offset:49152
	ds_read_b128 v[192:195], v189 offset:50176
	ds_read_b128 v[196:199], v189 offset:51200
	ds_read_b128 v[200:203], v189 offset:52224
	ds_read_b128 v[204:207], v189 offset:53248
	ds_read_b128 v[208:211], v189 offset:54272
	ds_read_b128 v[212:215], v189 offset:55296
	ds_read_b128 v[216:219], v189 offset:56320
	global_load_lds_dwordx4 v[182:183], off
	v_lshl_add_u64 v[182:183], v[220:221], 0, s[64:65]
	s_add_i32 m0, s6, 0x2000
	s_add_i32 s6, s48, s84
	global_load_lds_dwordx4 v[182:183], off
	v_lshl_add_u64 v[182:183], v[222:223], 0, s[64:65]
	s_mov_b32 m0, s6
	s_nop 0
	global_load_lds_dwordx4 v[182:183], off
	v_lshl_add_u64 v[182:183], v[224:225], 0, s[64:65]
	s_add_i32 m0, s6, 0x2000
	s_nop 0
	global_load_lds_dwordx4 v[182:183], off
	v_lshl_add_u64 v[182:183], v[226:227], 0, s[64:65]
	s_mov_b32 m0, s96
	s_nop 0
	global_load_lds_dwordx4 v[182:183], off
	v_lshl_add_u64 v[182:183], v[228:229], 0, s[64:65]
	s_mov_b32 m0, s97
	s_nop 0
	global_load_lds_dwordx4 v[182:183], off
	s_waitcnt vmcnt(8)
	s_waitcnt lgkmcnt(0)
	s_barrier
	s_setprio 1
	v_mfma_f32_16x16x32_bf16 v[60:63], v[128:131], v[178:181], v[60:63]
	v_mfma_f32_16x16x32_bf16 v[56:59], v[154:157], v[178:181], v[56:59]
	v_mfma_f32_16x16x32_bf16 v[44:47], v[128:131], v[196:199], v[44:47]
	v_mfma_f32_16x16x32_bf16 v[40:43], v[154:157], v[196:199], v[40:43]
	v_mfma_f32_16x16x32_bf16 v[28:31], v[128:131], v[204:207], v[28:31]
	v_mfma_f32_16x16x32_bf16 v[24:27], v[154:157], v[204:207], v[24:27]
	v_mfma_f32_16x16x32_bf16 v[12:15], v[128:131], v[212:215], v[12:15]
	v_mfma_f32_16x16x32_bf16 v[8:11], v[154:157], v[212:215], v[8:11]
	v_mfma_f32_16x16x32_bf16 v[60:63], v[132:135], v[192:195], v[60:63]
	v_mfma_f32_16x16x32_bf16 v[56:59], v[158:161], v[192:195], v[56:59]
	v_mfma_f32_16x16x32_bf16 v[44:47], v[132:135], v[200:203], v[44:47]
	v_mfma_f32_16x16x32_bf16 v[40:43], v[158:161], v[200:203], v[40:43]
	v_mfma_f32_16x16x32_bf16 v[28:31], v[132:135], v[208:211], v[28:31]
	v_mfma_f32_16x16x32_bf16 v[24:27], v[158:161], v[208:211], v[24:27]
	v_mfma_f32_16x16x32_bf16 v[12:15], v[132:135], v[216:219], v[12:15]
	v_mfma_f32_16x16x32_bf16 v[8:11], v[158:161], v[216:219], v[8:11]
	s_setprio 0
	s_setprio 1
	v_mfma_f32_16x16x32_bf16 v[52:55], v[162:165], v[178:181], v[52:55]
	v_mfma_f32_16x16x32_bf16 v[48:51], v[170:173], v[178:181], v[48:51]
	v_mfma_f32_16x16x32_bf16 v[36:39], v[162:165], v[196:199], v[36:39]
	v_mfma_f32_16x16x32_bf16 v[32:35], v[170:173], v[196:199], v[32:35]
	v_mfma_f32_16x16x32_bf16 v[20:23], v[162:165], v[204:207], v[20:23]
	v_mfma_f32_16x16x32_bf16 v[16:19], v[170:173], v[204:207], v[16:19]
	v_mfma_f32_16x16x32_bf16 v[4:7], v[162:165], v[212:215], v[4:7]
	v_mfma_f32_16x16x32_bf16 v[0:3], v[170:173], v[212:215], v[0:3]
	v_mfma_f32_16x16x32_bf16 v[52:55], v[166:169], v[192:195], v[52:55]
	v_mfma_f32_16x16x32_bf16 v[48:51], v[174:177], v[192:195], v[48:51]
	v_mfma_f32_16x16x32_bf16 v[36:39], v[166:169], v[200:203], v[36:39]
	v_mfma_f32_16x16x32_bf16 v[32:35], v[174:177], v[200:203], v[32:35]
	v_mfma_f32_16x16x32_bf16 v[20:23], v[166:169], v[208:211], v[20:23]
	v_mfma_f32_16x16x32_bf16 v[16:19], v[174:177], v[208:211], v[16:19]
	v_mfma_f32_16x16x32_bf16 v[4:7], v[166:169], v[216:219], v[4:7]
	v_mfma_f32_16x16x32_bf16 v[0:3], v[174:177], v[216:219], v[0:3]
	s_setprio 0
	s_barrier
	s_add_u32 s0, s0, 0x100
	s_addc_u32 s1, s1, 0
	s_add_u32 s44, s44, 0x100
	s_addc_u32 s45, s45, 0
	s_cmp_ge_i32 s46, s33
	s_mov_b32 s6, s46

; #define PG8_STAGE(bufoff, gbase, voff) do { _Pragma("unroll") for (int _i = 0; _i < 2; ++_i) \
;         __builtin_amdgcn_global_load_lds((const unsigned*)((const char*)(gbase) + (voff)[_i]), (PG8_LAS unsigned*)(lds + (bufoff) + ldsw + _i * 8192), 16, 0, 0); } while (0)
; #define PG8_LDA(dst, b, h) do { _Pragma("unroll") for (int m = 0; m < 4; ++m) _Pragma("unroll") for (int k = 0; k < 2; ++k) dst[m][k] = *(const PG8_LAS bf16x8*)(lds + PG8_SA(b, h) + aoff + m * 2048 + k * 1024); } while (0)
; #define PG8_LDB(dst, b, h) do { _Pragma("unroll") for (int n = 0; n < 2; ++n) _Pragma("unroll") for (int k = 0; k < 2; ++k) dst[n][k] = *(const PG8_LAS bf16x8*)(lds + PG8_SB(b, h) + boff + n * 2048 + k * 1024); } while (0)
; #define PG8_WAIT_V(n) asm volatile("s_waitcnt vmcnt(" #n ")" ::: "memory")
; #define PG8_WAIT_L(n) asm volatile("s_waitcnt lgkmcnt(" #n ")" ::: "memory")
; #define PG8_BAR __builtin_amdgcn_s_barrier()
; #define PG8_SCHED __builtin_amdgcn_sched_barrier(0)
; template <class Epi, class Sched, bool ALIGN_EPI = false, bool SP2 = false>
; __device__ __forceinline__ void gemm_phase(PG8_LAS unsigned char* lds, const Gemm g, const Sched& S, const Epi& E) {
;     ...
;         const bool has_next = S.next(ui + 1, nxt);
;         const char* nA = has_next ? (const char*)g.A + (size_t)nxt.pm * tstep : cA; const char* nB = has_next ? (const char*)g.Bt + (size_t)nxt.pn * tstep : cB;
;         for (int t = 0; t < nt; t += 2) {
;             const bool last = (t == nt - 2);
;             const char* a1 = cA + (size_t)(t + 1) * kstep;
;             const char* a2 = last ? nA : cA + (size_t)(t + 2) * kstep; const char* b2 = last ? nB : cB + (size_t)(t + 2) * kstep;
;             const char* a3 = a2 + kstep; const char* b3 = b2 + kstep;
;             if (last && has_next) S.a_ready(nxt);
;             if constexpr (SP2) {
;             PG8_LDB(B0, 0, 0); PG8_LDB(B1, 0, 1); PG8_SCHED; PG8_LDA(At, 0, 0); PG8_STAGE(PG8_SA(1, 1), a1 + hstep, voffA);
;             PG8_WAIT_V(8); PG8_WAIT_L(0); PG8_BAR; PG8_MMA(0, 0, At, B0); PG8_MMA(0, 1, At, B1); PG8_BAR; PG8_SCHED;
;             PG8_LDA(At, 0, 1); PG8_STAGE(PG8_SB(0, 0), b2, voffB); PG8_STAGE(PG8_SB(0, 1), b2 + hstep, voffB); PG8_STAGE(PG8_SA(0, 0), a2, voffA);
;             PG8_WAIT_V(8); PG8_WAIT_L(0); PG8_BAR; PG8_MMA(1, 0, At, B0); PG8_MMA(1, 1, At, B1); PG8_BAR; PG8_SCHED;
.LBB0_1439:
	s_ashr_i32 s47, s46, 31
	s_lshl_b64 s[48:49], s[46:47], 20
	s_add_u32 s48, s60, s48
	s_addc_u32 s49, s61, s49
	s_and_b64 s[52:53], s[4:5], exec
	s_cselect_b32 s47, s49, s55
	s_cselect_b32 s83, s48, s54
	s_ashr_i32 s45, s44, 31
	s_lshl_b64 s[52:53], s[44:45], 20
	s_add_u32 s52, s62, s52
	s_addc_u32 s53, s63, s53
	s_and_b64 s[58:59], s[4:5], exec
	s_cselect_b32 s45, s53, s57
	s_cselect_b32 s84, s52, s56
	s_add_u32 s54, s54, 0x80080
	s_addc_u32 s55, s55, 0
	s_add_u32 s85, s56, 0x100
	s_addc_u32 s86, s57, 0
	s_mov_b32 s87, -2
	ds_read_b128 v[146:149], v164
	ds_read_b128 v[168:171], v164 offset:1024
	ds_read_b128 v[172:175], v164 offset:2048
	ds_read_b128 v[176:179], v164 offset:3072
	ds_read_b128 v[180:183], v165
	ds_read_b128 v[184:187], v165 offset:1024
	ds_read_b128 v[188:191], v165 offset:2048
	ds_read_b128 v[192:195], v165 offset:3072
	s_add_u32 s56, s54, 0xfff80080
	s_addc_u32 s57, s55, -1
	s_cmp_eq_u32 s87, 28
	s_cselect_b32 s59, s47, s57
	s_cselect_b32 s58, s83, s56
	s_cselect_b32 s57, s45, s86
	s_cselect_b32 s56, s84, s85
	v_lshl_add_u64 v[228:229], s[54:55], 0, v[136:137]
	s_add_i32 m0, s65, 0xc000
	ds_read_b128 v[196:199], v166
	ds_read_b128 v[200:203], v166 offset:1024
	ds_read_b128 v[204:207], v166 offset:2048
	ds_read_b128 v[208:211], v166 offset:3072
	ds_read_b128 v[212:215], v166 offset:4096
	ds_read_b128 v[216:219], v166 offset:5120
	ds_read_b128 v[220:223], v166 offset:6144
	ds_read_b128 v[224:227], v166 offset:7168
	global_load_lds_dwordx4 v[228:229], off
	v_lshl_add_u64 v[228:229], s[54:55], 0, v[138:139]
	s_add_i32 m0, s65, 0xe000
	s_nop 0
	global_load_lds_dwordx4 v[228:229], off
	s_waitcnt vmcnt(8)
	s_waitcnt lgkmcnt(0)
	s_barrier
	s_setprio 1
	v_mfma_f32_16x16x32_bf16 v[124:127], v[146:149], v[196:199], 0
	v_mfma_f32_16x16x32_bf16 v[120:123], v[172:175], v[196:199], 0
	v_mfma_f32_16x16x32_bf16 v[108:111], v[146:149], v[204:207], 0
	v_mfma_f32_16x16x32_bf16 v[104:107], v[172:175], v[204:207], 0
	v_mfma_f32_16x16x32_bf16 v[92:95], v[146:149], v[212:215], 0
	v_mfma_f32_16x16x32_bf16 v[88:91], v[172:175], v[212:215], 0
	v_mfma_f32_16x16x32_bf16 v[76:79], v[146:149], v[220:223], 0
	v_mfma_f32_16x16x32_bf16 v[72:75], v[172:175], v[220:223], 0
	v_mfma_f32_16x16x32_bf16 v[124:127], v[168:171], v[200:203], v[124:127]
	v_mfma_f32_16x16x32_bf16 v[120:123], v[176:179], v[200:203], v[120:123]
	v_mfma_f32_16x16x32_bf16 v[108:111], v[168:171], v[208:211], v[108:111]
	v_mfma_f32_16x16x32_bf16 v[104:107], v[176:179], v[208:211], v[104:107]
	v_mfma_f32_16x16x32_bf16 v[92:95], v[168:171], v[216:219], v[92:95]
	v_mfma_f32_16x16x32_bf16 v[88:91], v[176:179], v[216:219], v[88:91]
	v_mfma_f32_16x16x32_bf16 v[76:79], v[168:171], v[224:227], v[76:79]
	v_mfma_f32_16x16x32_bf16 v[72:75], v[176:179], v[224:227], v[72:75]
	s_setprio 0
	s_setprio 1
	v_mfma_f32_16x16x32_bf16 v[116:119], v[180:183], v[196:199], 0
	v_mfma_f32_16x16x32_bf16 v[112:115], v[188:191], v[196:199], 0
	v_mfma_f32_16x16x32_bf16 v[100:103], v[180:183], v[204:207], 0
	v_mfma_f32_16x16x32_bf16 v[96:99], v[188:191], v[204:207], 0
	v_mfma_f32_16x16x32_bf16 v[84:87], v[180:183], v[212:215], 0
	v_mfma_f32_16x16x32_bf16 v[80:83], v[188:191], v[212:215], 0
	v_mfma_f32_16x16x32_bf16 v[68:71], v[180:183], v[220:223], 0
	v_mfma_f32_16x16x32_bf16 v[64:67], v[188:191], v[220:223], 0
	v_mfma_f32_16x16x32_bf16 v[116:119], v[184:187], v[200:203], v[116:119]
	v_mfma_f32_16x16x32_bf16 v[112:115], v[192:195], v[200:203], v[112:115]
	v_mfma_f32_16x16x32_bf16 v[100:103], v[184:187], v[208:211], v[100:103]
	v_mfma_f32_16x16x32_bf16 v[96:99], v[192:195], v[208:211], v[96:99]
	v_mfma_f32_16x16x32_bf16 v[84:87], v[184:187], v[216:219], v[84:87]
	v_mfma_f32_16x16x32_bf16 v[80:83], v[192:195], v[216:219], v[80:83]
	v_mfma_f32_16x16x32_bf16 v[68:71], v[184:187], v[224:227], v[68:71]
	v_mfma_f32_16x16x32_bf16 v[64:67], v[192:195], v[224:227], v[64:67]
	s_setprio 0
	s_barrier
	s_add_i32 s88, s74, s64
	v_lshl_add_u64 v[228:229], s[56:57], 0, v[130:131]
	s_mov_b32 m0, s88
	ds_read_b128 v[196:199], v166 offset:16384
	ds_read_b128 v[200:203], v166 offset:17408
	ds_read_b128 v[204:207], v166 offset:18432
	ds_read_b128 v[208:211], v166 offset:19456
	ds_read_b128 v[212:215], v166 offset:20480
	ds_read_b128 v[216:219], v166 offset:21504
	ds_read_b128 v[220:223], v166 offset:22528
	ds_read_b128 v[224:227], v166 offset:23552
	global_load_lds_dwordx4 v[228:229], off
	s_add_i32 m0, s88, 0x2000
	s_add_u32 s88, s56, 0x80000
	v_lshl_add_u64 v[230:231], s[56:57], 0, v[134:135]
	s_addc_u32 s89, s57, 0
	s_add_i32 s90, s75, s64
	global_load_lds_dwordx4 v[230:231], off
	v_lshl_add_u64 v[232:233], s[88:89], 0, v[130:131]
	s_mov_b32 m0, s90
	v_lshl_add_u64 v[234:235], s[58:59], 0, v[132:133]
	global_load_lds_dwordx4 v[232:233], off
	v_lshl_add_u64 v[232:233], s[88:89], 0, v[134:135]
	s_add_i32 m0, s90, 0x2000
	s_nop 0
	global_load_lds_dwordx4 v[232:233], off
	v_lshl_add_u64 v[232:233], s[58:59], 0, v[128:129]
	s_mov_b32 m0, s65
	s_nop 0
	global_load_lds_dwordx4 v[232:233], off
	s_mov_b32 m0, s66
	s_nop 0
	global_load_lds_dwordx4 v[234:235], off
	s_waitcnt vmcnt(8)
	s_waitcnt lgkmcnt(0)
	s_barrier
; #define PG8_STAGE(bufoff, gbase, voff) do { _Pragma("unroll") for (int _i = 0; _i < 2; ++_i) \
;         __builtin_amdgcn_global_load_lds((const unsigned*)((const char*)(gbase) + (voff)[_i]), (PG8_LAS unsigned*)(lds + (bufoff) + ldsw + _i * 8192), 16, 0, 0); } while (0)
; #define PG8_LDA(dst, b, h) do { _Pragma("unroll") for (int m = 0; m < 4; ++m) _Pragma("unroll") for (int k = 0; k < 2; ++k) dst[m][k] = *(const PG8_LAS bf16x8*)(lds + PG8_SA(b, h) + aoff + m * 2048 + k * 1024); } while (0)
; #define PG8_LDB(dst, b, h) do { _Pragma("unroll") for (int n = 0; n < 2; ++n) _Pragma("unroll") for (int k = 0; k < 2; ++k) dst[n][k] = *(const PG8_LAS bf16x8*)(lds + PG8_SB(b, h) + boff + n * 2048 + k * 1024); } while (0)
; #define PG8_MMA(ai, bj, At, Bt) do { __builtin_amdgcn_s_setprio(1); _Pragma("unroll") for (int m = 0; m < 4; ++m) _Pragma("unroll") for (int n = 0; n < 2; ++n) _Pragma("unroll") for (int k = 0; k < 2; ++k) \
;         acc[ai][bj][m][n] = __builtin_amdgcn_mfma_f32_16x16x32_bf16(Bt[n][k], At[m][k], acc[ai][bj][m][n], 0, 0, 0); __builtin_amdgcn_s_setprio(0); } while (0)
; #define PG8_WAIT_V(n) asm volatile("s_waitcnt vmcnt(" #n ")" ::: "memory")
; #define PG8_WAIT_L(n) asm volatile("s_waitcnt lgkmcnt(" #n ")" ::: "memory")
; #define PG8_BAR __builtin_amdgcn_s_barrier()
; #define PG8_SCHED __builtin_amdgcn_sched_barrier(0)
; template <class Epi, class Sched, bool ALIGN_EPI = false, bool SP2 = false>
; __device__ __forceinline__ void gemm_phase(PG8_LAS unsigned char* lds, const Gemm g, const Sched& S, const Epi& E) {
;     ...
;             PG8_WAIT_V(8); PG8_WAIT_L(0); PG8_BAR; PG8_MMA(1, 0, At, B0); PG8_MMA(1, 1, At, B1); PG8_BAR; PG8_SCHED;
;             PG8_LDB(B0, 1, 0); PG8_LDB(B1, 1, 1); PG8_SCHED; PG8_LDA(At, 1, 0); PG8_STAGE(PG8_SA(0, 1), a2 + hstep, voffA);
;             PG8_WAIT_V(8); PG8_WAIT_L(0); PG8_BAR; PG8_MMA(0, 0, At, B0); PG8_MMA(0, 1, At, B1); PG8_BAR; PG8_SCHED;
	s_setprio 1
	v_mfma_f32_16x16x32_bf16 v[60:63], v[146:149], v[196:199], 0
	v_mfma_f32_16x16x32_bf16 v[56:59], v[172:175], v[196:199], 0
	v_mfma_f32_16x16x32_bf16 v[44:47], v[146:149], v[204:207], 0
	v_mfma_f32_16x16x32_bf16 v[40:43], v[172:175], v[204:207], 0
	v_mfma_f32_16x16x32_bf16 v[28:31], v[146:149], v[212:215], 0
	v_mfma_f32_16x16x32_bf16 v[24:27], v[172:175], v[212:215], 0
	v_mfma_f32_16x16x32_bf16 v[12:15], v[146:149], v[220:223], 0
	v_mfma_f32_16x16x32_bf16 v[8:11], v[172:175], v[220:223], 0
	v_mfma_f32_16x16x32_bf16 v[60:63], v[168:171], v[200:203], v[60:63]
	v_mfma_f32_16x16x32_bf16 v[56:59], v[176:179], v[200:203], v[56:59]
	v_mfma_f32_16x16x32_bf16 v[44:47], v[168:171], v[208:211], v[44:47]
	v_mfma_f32_16x16x32_bf16 v[40:43], v[176:179], v[208:211], v[40:43]
	v_mfma_f32_16x16x32_bf16 v[28:31], v[168:171], v[216:219], v[28:31]
	v_mfma_f32_16x16x32_bf16 v[24:27], v[176:179], v[216:219], v[24:27]
	v_mfma_f32_16x16x32_bf16 v[12:15], v[168:171], v[224:227], v[12:15]
	v_mfma_f32_16x16x32_bf16 v[8:11], v[176:179], v[224:227], v[8:11]
	s_setprio 0
	s_setprio 1
	v_mfma_f32_16x16x32_bf16 v[52:55], v[180:183], v[196:199], 0
	v_mfma_f32_16x16x32_bf16 v[48:51], v[188:191], v[196:199], 0
	v_mfma_f32_16x16x32_bf16 v[36:39], v[180:183], v[204:207], 0
	v_mfma_f32_16x16x32_bf16 v[32:35], v[188:191], v[204:207], 0
	v_mfma_f32_16x16x32_bf16 v[20:23], v[180:183], v[212:215], 0
	v_mfma_f32_16x16x32_bf16 v[16:19], v[188:191], v[212:215], 0
	v_mfma_f32_16x16x32_bf16 v[4:7], v[180:183], v[220:223], 0
	v_mfma_f32_16x16x32_bf16 v[0:3], v[188:191], v[220:223], 0
	v_mfma_f32_16x16x32_bf16 v[52:55], v[184:187], v[200:203], v[52:55]
	v_mfma_f32_16x16x32_bf16 v[48:51], v[192:195], v[200:203], v[48:51]
	v_mfma_f32_16x16x32_bf16 v[36:39], v[184:187], v[208:211], v[36:39]
	v_mfma_f32_16x16x32_bf16 v[32:35], v[192:195], v[208:211], v[32:35]
	v_mfma_f32_16x16x32_bf16 v[20:23], v[184:187], v[216:219], v[20:23]
	v_mfma_f32_16x16x32_bf16 v[16:19], v[192:195], v[216:219], v[16:19]
	v_mfma_f32_16x16x32_bf16 v[4:7], v[184:187], v[224:227], v[4:7]
	v_mfma_f32_16x16x32_bf16 v[0:3], v[192:195], v[224:227], v[0:3]
	s_setprio 0
	s_barrier
	s_add_i32 s88, 0, 0x18000
	v_add_u32_e32 v167, s88, v163
	s_add_i32 s89, 0, 0x1c000
	ds_read_b128 v[146:149], v167
	ds_read_b128 v[168:171], v167 offset:1024
	ds_read_b128 v[172:175], v167 offset:2048
	ds_read_b128 v[176:179], v167 offset:3072
	v_add_u32_e32 v167, s89, v163
	ds_read_b128 v[180:183], v167
	ds_read_b128 v[184:187], v167 offset:1024
	ds_read_b128 v[188:191], v167 offset:2048
	ds_read_b128 v[192:195], v167 offset:3072
	s_add_u32 s58, s58, 0x80000
	s_addc_u32 s59, s59, 0
	s_mov_b32 m0, s67
	v_lshl_add_u64 v[236:237], s[58:59], 0, v[128:129]
	ds_read_b128 v[196:199], v166 offset:32768
	ds_read_b128 v[200:203], v166 offset:33792
	ds_read_b128 v[204:207], v166 offset:34816
	ds_read_b128 v[208:211], v166 offset:35840
	ds_read_b128 v[212:215], v166 offset:36864
	ds_read_b128 v[216:219], v166 offset:37888
	ds_read_b128 v[220:223], v166 offset:38912
	ds_read_b128 v[224:227], v166 offset:39936
	global_load_lds_dwordx4 v[236:237], off
	v_lshl_add_u64 v[236:237], s[58:59], 0, v[132:133]
	s_mov_b32 m0, s68
	s_nop 0
	global_load_lds_dwordx4 v[236:237], off
	s_waitcnt vmcnt(8)
	s_waitcnt lgkmcnt(0)
	s_barrier
	s_setprio 1
	v_mfma_f32_16x16x32_bf16 v[124:127], v[146:149], v[196:199], v[124:127]
	v_mfma_f32_16x16x32_bf16 v[120:123], v[172:175], v[196:199], v[120:123]
	v_mfma_f32_16x16x32_bf16 v[108:111], v[146:149], v[204:207], v[108:111]
	v_mfma_f32_16x16x32_bf16 v[104:107], v[172:175], v[204:207], v[104:107]
	v_mfma_f32_16x16x32_bf16 v[92:95], v[146:149], v[212:215], v[92:95]
	v_mfma_f32_16x16x32_bf16 v[88:91], v[172:175], v[212:215], v[88:91]
	v_mfma_f32_16x16x32_bf16 v[76:79], v[146:149], v[220:223], v[76:79]
	v_mfma_f32_16x16x32_bf16 v[72:75], v[172:175], v[220:223], v[72:75]
	v_mfma_f32_16x16x32_bf16 v[124:127], v[168:171], v[200:203], v[124:127]
	v_mfma_f32_16x16x32_bf16 v[120:123], v[176:179], v[200:203], v[120:123]
	v_mfma_f32_16x16x32_bf16 v[108:111], v[168:171], v[208:211], v[108:111]
	v_mfma_f32_16x16x32_bf16 v[104:107], v[176:179], v[208:211], v[104:107]
	v_mfma_f32_16x16x32_bf16 v[92:95], v[168:171], v[216:219], v[92:95]
	v_mfma_f32_16x16x32_bf16 v[88:91], v[176:179], v[216:219], v[88:91]
	v_mfma_f32_16x16x32_bf16 v[76:79], v[168:171], v[224:227], v[76:79]
	v_mfma_f32_16x16x32_bf16 v[72:75], v[176:179], v[224:227], v[72:75]
	s_setprio 0
	s_setprio 1
	v_mfma_f32_16x16x32_bf16 v[116:119], v[180:183], v[196:199], v[116:119]
	v_mfma_f32_16x16x32_bf16 v[112:115], v[188:191], v[196:199], v[112:115]
	v_mfma_f32_16x16x32_bf16 v[100:103], v[180:183], v[204:207], v[100:103]
	v_mfma_f32_16x16x32_bf16 v[96:99], v[188:191], v[204:207], v[96:99]
	v_mfma_f32_16x16x32_bf16 v[84:87], v[180:183], v[212:215], v[84:87]
	v_mfma_f32_16x16x32_bf16 v[80:83], v[188:191], v[212:215], v[80:83]
	v_mfma_f32_16x16x32_bf16 v[68:71], v[180:183], v[220:223], v[68:71]
	v_mfma_f32_16x16x32_bf16 v[64:67], v[188:191], v[220:223], v[64:67]
	v_mfma_f32_16x16x32_bf16 v[116:119], v[184:187], v[200:203], v[116:119]
	v_mfma_f32_16x16x32_bf16 v[112:115], v[192:195], v[200:203], v[112:115]
	v_mfma_f32_16x16x32_bf16 v[100:103], v[184:187], v[208:211], v[100:103]
	v_mfma_f32_16x16x32_bf16 v[96:99], v[192:195], v[208:211], v[96:99]
	v_mfma_f32_16x16x32_bf16 v[84:87], v[184:187], v[216:219], v[84:87]
	v_mfma_f32_16x16x32_bf16 v[80:83], v[192:195], v[216:219], v[80:83]
	v_mfma_f32_16x16x32_bf16 v[68:71], v[184:187], v[224:227], v[68:71]
	v_mfma_f32_16x16x32_bf16 v[64:67], v[192:195], v[224:227], v[64:67]
	s_setprio 0
	s_barrier
; #define PG8_STAGE(bufoff, gbase, voff) do { _Pragma("unroll") for (int _i = 0; _i < 2; ++_i) \
;         __builtin_amdgcn_global_load_lds((const unsigned*)((const char*)(gbase) + (voff)[_i]), (PG8_LAS unsigned*)(lds + (bufoff) + ldsw + _i * 8192), 16, 0, 0); } while (0)
; #define PG8_LDA(dst, b, h) do { _Pragma("unroll") for (int m = 0; m < 4; ++m) _Pragma("unroll") for (int k = 0; k < 2; ++k) dst[m][k] = *(const PG8_LAS bf16x8*)(lds + PG8_SA(b, h) + aoff + m * 2048 + k * 1024); } while (0)
; #define PG8_MMA(ai, bj, At, Bt) do { __builtin_amdgcn_s_setprio(1); _Pragma("unroll") for (int m = 0; m < 4; ++m) _Pragma("unroll") for (int n = 0; n < 2; ++n) _Pragma("unroll") for (int k = 0; k < 2; ++k) \
;         acc[ai][bj][m][n] = __builtin_amdgcn_mfma_f32_16x16x32_bf16(Bt[n][k], At[m][k], acc[ai][bj][m][n], 0, 0, 0); __builtin_amdgcn_s_setprio(0); } while (0)
; #define PG8_WAIT_V(n) asm volatile("s_waitcnt vmcnt(" #n ")" ::: "memory")
; #define PG8_WAIT_L(n) asm volatile("s_waitcnt lgkmcnt(" #n ")" ::: "memory")
; #define PG8_BAR __builtin_amdgcn_s_barrier()
; #define PG8_SCHED __builtin_amdgcn_sched_barrier(0)
; template <class Epi, class Sched, bool ALIGN_EPI = false, bool SP2 = false>
; __device__ __forceinline__ void gemm_phase(PG8_LAS unsigned char* lds, const Gemm g, const Sched& S, const Epi& E) {
;     ...
;         for (int t = 0; t < nt; t += 2) {
;     ...
;             PG8_LDA(At, 1, 1); PG8_STAGE(PG8_SB(1, 0), b3, voffB); PG8_STAGE(PG8_SB(1, 1), b3 + hstep, voffB); PG8_STAGE(PG8_SA(1, 0), a3, voffA);
;             PG8_WAIT_V(8); PG8_WAIT_L(0); PG8_BAR; PG8_MMA(1, 0, At, B0); PG8_MMA(1, 1, At, B1); PG8_BAR; PG8_SCHED;
	s_add_i32 s58, s88, s64
	v_lshl_add_u64 v[228:229], v[228:229], 0, s[12:13]
	s_mov_b32 m0, s58
	ds_read_b128 v[196:199], v166 offset:49152
	ds_read_b128 v[200:203], v166 offset:50176
	ds_read_b128 v[204:207], v166 offset:51200
	ds_read_b128 v[208:211], v166 offset:52224
	ds_read_b128 v[212:215], v166 offset:53248
	ds_read_b128 v[216:219], v166 offset:54272
	ds_read_b128 v[220:223], v166 offset:55296
	ds_read_b128 v[224:227], v166 offset:56320
	global_load_lds_dwordx4 v[228:229], off
	s_add_i32 m0, s58, 0x2000
	s_add_u32 s56, s56, 0x80080
	v_lshl_add_u64 v[228:229], v[230:231], 0, s[12:13]
	s_addc_u32 s57, s57, 0
	s_add_i32 s58, s89, s64
	global_load_lds_dwordx4 v[228:229], off
	v_lshl_add_u64 v[228:229], s[56:57], 0, v[130:131]
	s_mov_b32 m0, s58
	s_nop 0
	global_load_lds_dwordx4 v[228:229], off
	v_lshl_add_u64 v[228:229], s[56:57], 0, v[134:135]
	s_add_i32 m0, s58, 0x2000
	s_nop 0
	global_load_lds_dwordx4 v[228:229], off
	v_lshl_add_u64 v[228:229], v[232:233], 0, s[12:13]
	s_mov_b32 m0, s71
	s_nop 0
	global_load_lds_dwordx4 v[228:229], off
	v_lshl_add_u64 v[228:229], v[234:235], 0, s[12:13]
	s_mov_b32 m0, s72
	s_nop 0
	global_load_lds_dwordx4 v[228:229], off
	s_waitcnt vmcnt(8)
	s_waitcnt lgkmcnt(0)
	s_barrier
	s_setprio 1
	v_mfma_f32_16x16x32_bf16 v[60:63], v[146:149], v[196:199], v[60:63]
	v_mfma_f32_16x16x32_bf16 v[56:59], v[172:175], v[196:199], v[56:59]
	v_mfma_f32_16x16x32_bf16 v[44:47], v[146:149], v[204:207], v[44:47]
	v_mfma_f32_16x16x32_bf16 v[40:43], v[172:175], v[204:207], v[40:43]
	v_mfma_f32_16x16x32_bf16 v[28:31], v[146:149], v[212:215], v[28:31]
	v_mfma_f32_16x16x32_bf16 v[24:27], v[172:175], v[212:215], v[24:27]
	v_mfma_f32_16x16x32_bf16 v[12:15], v[146:149], v[220:223], v[12:15]
	v_mfma_f32_16x16x32_bf16 v[8:11], v[172:175], v[220:223], v[8:11]
	v_mfma_f32_16x16x32_bf16 v[60:63], v[168:171], v[200:203], v[60:63]
	v_mfma_f32_16x16x32_bf16 v[56:59], v[176:179], v[200:203], v[56:59]
	v_mfma_f32_16x16x32_bf16 v[44:47], v[168:171], v[208:211], v[44:47]
	v_mfma_f32_16x16x32_bf16 v[40:43], v[176:179], v[208:211], v[40:43]
	v_mfma_f32_16x16x32_bf16 v[28:31], v[168:171], v[216:219], v[28:31]
	v_mfma_f32_16x16x32_bf16 v[24:27], v[176:179], v[216:219], v[24:27]
	v_mfma_f32_16x16x32_bf16 v[12:15], v[168:171], v[224:227], v[12:15]
	v_mfma_f32_16x16x32_bf16 v[8:11], v[176:179], v[224:227], v[8:11]
	s_setprio 0
	s_setprio 1
	v_mfma_f32_16x16x32_bf16 v[52:55], v[180:183], v[196:199], v[52:55]
	v_mfma_f32_16x16x32_bf16 v[48:51], v[188:191], v[196:199], v[48:51]
	v_mfma_f32_16x16x32_bf16 v[36:39], v[180:183], v[204:207], v[36:39]
	v_mfma_f32_16x16x32_bf16 v[32:35], v[188:191], v[204:207], v[32:35]
	v_mfma_f32_16x16x32_bf16 v[20:23], v[180:183], v[212:215], v[20:23]
	v_mfma_f32_16x16x32_bf16 v[16:19], v[188:191], v[212:215], v[16:19]
	v_mfma_f32_16x16x32_bf16 v[4:7], v[180:183], v[220:223], v[4:7]
	v_mfma_f32_16x16x32_bf16 v[0:3], v[188:191], v[220:223], v[0:3]
	v_mfma_f32_16x16x32_bf16 v[52:55], v[184:187], v[200:203], v[52:55]
	v_mfma_f32_16x16x32_bf16 v[48:51], v[192:195], v[200:203], v[48:51]
	v_mfma_f32_16x16x32_bf16 v[36:39], v[184:187], v[208:211], v[36:39]
	v_mfma_f32_16x16x32_bf16 v[32:35], v[192:195], v[208:211], v[32:35]
	v_mfma_f32_16x16x32_bf16 v[20:23], v[184:187], v[216:219], v[20:23]
	v_mfma_f32_16x16x32_bf16 v[16:19], v[192:195], v[216:219], v[16:19]
	v_mfma_f32_16x16x32_bf16 v[4:7], v[184:187], v[224:227], v[4:7]
	v_mfma_f32_16x16x32_bf16 v[0:3], v[192:195], v[224:227], v[0:3]
	s_setprio 0
	s_barrier
	s_add_i32 s87, s87, 2
	s_add_u32 s54, s54, 0x100
	s_addc_u32 s55, s55, 0
	s_add_u32 s85, s85, 0x100
	s_addc_u32 s86, s86, 0
	s_cmp_gt_u32 s87, 29

; #define PG8_STAGE(bufoff, gbase, voff) do { _Pragma("unroll") for (int _i = 0; _i < 2; ++_i) \
;         __builtin_amdgcn_global_load_lds((const unsigned*)((const char*)(gbase) + (voff)[_i]), (PG8_LAS unsigned*)(lds + (bufoff) + ldsw + _i * 8192), 16, 0, 0); } while (0)
; #define PG8_LDA(dst, b, h) do { _Pragma("unroll") for (int m = 0; m < 4; ++m) _Pragma("unroll") for (int k = 0; k < 2; ++k) dst[m][k] = *(const PG8_LAS bf16x8*)(lds + PG8_SA(b, h) + aoff + m * 2048 + k * 1024); } while (0)
; #define PG8_LDB(dst, b, h) do { _Pragma("unroll") for (int n = 0; n < 2; ++n) _Pragma("unroll") for (int k = 0; k < 2; ++k) dst[n][k] = *(const PG8_LAS bf16x8*)(lds + PG8_SB(b, h) + boff + n * 2048 + k * 1024); } while (0)
; #define PG8_WAIT_V(n) asm volatile("s_waitcnt vmcnt(" #n ")" ::: "memory")
; #define PG8_WAIT_L(n) asm volatile("s_waitcnt lgkmcnt(" #n ")" ::: "memory")
; #define PG8_BAR __builtin_amdgcn_s_barrier()
; #define PG8_SCHED __builtin_amdgcn_sched_barrier(0)
; template <class Epi, class Sched, bool ALIGN_EPI = false, bool SP2 = false>
; __device__ __forceinline__ void gemm_phase(PG8_LAS unsigned char* lds, const Gemm g, const Sched& S, const Epi& E) {
;     ...
;         const bool has_next = S.next(ui + 1, nxt);
;         const char* nA = has_next ? (const char*)g.A + (size_t)nxt.pm * tstep : cA; const char* nB = has_next ? (const char*)g.Bt + (size_t)nxt.pn * tstep : cB;
;         for (int t = 0; t < nt; t += 2) {
;             const bool last = (t == nt - 2);
;             const char* a1 = cA + (size_t)(t + 1) * kstep;
;             const char* a2 = last ? nA : cA + (size_t)(t + 2) * kstep; const char* b2 = last ? nB : cB + (size_t)(t + 2) * kstep;
;             const char* a3 = a2 + kstep; const char* b3 = b2 + kstep;
;             if (last && has_next) S.a_ready(nxt);
;             if constexpr (SP2) {
;             PG8_LDB(B0, 0, 0); PG8_LDB(B1, 0, 1); PG8_SCHED; PG8_LDA(At, 0, 0); PG8_STAGE(PG8_SA(1, 1), a1 + hstep, voffA);
;             PG8_WAIT_V(8); PG8_WAIT_L(0); PG8_BAR; PG8_MMA(0, 0, At, B0); PG8_MMA(0, 1, At, B1); PG8_BAR; PG8_SCHED;
;             PG8_LDA(At, 0, 1); PG8_STAGE(PG8_SB(0, 0), b2, voffB); PG8_STAGE(PG8_SB(0, 1), b2 + hstep, voffB); PG8_STAGE(PG8_SA(0, 0), a2, voffA);
;             PG8_WAIT_V(8); PG8_WAIT_L(0); PG8_BAR; PG8_MMA(1, 0, At, B0); PG8_MMA(1, 1, At, B1); PG8_BAR; PG8_SCHED;
.LBB0_1459:
	s_ashr_i32 s47, s46, 31
	s_lshl_b64 s[48:49], s[46:47], 19
	s_add_u32 s48, s61, s48
	s_addc_u32 s49, s62, s49
	s_and_b64 s[52:53], s[4:5], exec
	s_cselect_b32 s47, s49, s55
	s_cselect_b32 s81, s48, s54
	s_ashr_i32 s45, s44, 31
	s_lshl_b64 s[52:53], s[44:45], 19
	s_add_u32 s52, s63, s52
	s_addc_u32 s53, s64, s53
	s_and_b64 s[58:59], s[4:5], exec
	s_cselect_b32 s45, s53, s57
	s_cselect_b32 s82, s52, s56
	s_add_u32 s54, s54, 0x40080
	s_addc_u32 s55, s55, 0
	s_add_u32 s83, s56, 0x100
	s_addc_u32 s84, s57, 0
	s_mov_b32 s85, -2
	ds_read_b128 v[152:155], v147
	ds_read_b128 v[156:159], v147 offset:1024
	ds_read_b128 v[160:163], v147 offset:2048
	ds_read_b128 v[164:167], v147 offset:3072
	ds_read_b128 v[168:171], v148
	ds_read_b128 v[172:175], v148 offset:1024
	ds_read_b128 v[176:179], v148 offset:2048
	ds_read_b128 v[180:183], v148 offset:3072
	s_add_u32 s56, s54, 0xfffc0080
	s_addc_u32 s57, s55, -1
	s_cmp_eq_u32 s85, 12
	s_cselect_b32 s59, s47, s57
	s_cselect_b32 s58, s81, s56
	s_cselect_b32 s57, s45, s84
	s_cselect_b32 s56, s82, s83
	v_lshl_add_u64 v[216:217], s[54:55], 0, v[136:137]
	s_add_i32 m0, s43, 0xc000
	ds_read_b128 v[184:187], v149
	ds_read_b128 v[188:191], v149 offset:1024
	ds_read_b128 v[192:195], v149 offset:2048
	ds_read_b128 v[196:199], v149 offset:3072
	ds_read_b128 v[200:203], v149 offset:4096
	ds_read_b128 v[204:207], v149 offset:5120
	ds_read_b128 v[208:211], v149 offset:6144
	ds_read_b128 v[212:215], v149 offset:7168
	global_load_lds_dwordx4 v[216:217], off
	v_lshl_add_u64 v[216:217], s[54:55], 0, v[138:139]
	s_add_i32 m0, s43, 0xe000
	s_nop 0
	global_load_lds_dwordx4 v[216:217], off
	s_waitcnt vmcnt(8)
	s_waitcnt lgkmcnt(0)
	s_barrier
	s_setprio 1
	v_mfma_f32_16x16x32_bf16 v[124:127], v[152:155], v[184:187], 0
	v_mfma_f32_16x16x32_bf16 v[120:123], v[160:163], v[184:187], 0
	v_mfma_f32_16x16x32_bf16 v[116:119], v[152:155], v[192:195], 0
	v_mfma_f32_16x16x32_bf16 v[112:115], v[160:163], v[192:195], 0
	v_mfma_f32_16x16x32_bf16 v[100:103], v[152:155], v[200:203], 0
	v_mfma_f32_16x16x32_bf16 v[96:99], v[160:163], v[200:203], 0
	v_mfma_f32_16x16x32_bf16 v[84:87], v[152:155], v[208:211], 0
	v_mfma_f32_16x16x32_bf16 v[80:83], v[160:163], v[208:211], 0
	v_mfma_f32_16x16x32_bf16 v[124:127], v[156:159], v[188:191], v[124:127]
	v_mfma_f32_16x16x32_bf16 v[120:123], v[164:167], v[188:191], v[120:123]
	v_mfma_f32_16x16x32_bf16 v[116:119], v[156:159], v[196:199], v[116:119]
	v_mfma_f32_16x16x32_bf16 v[112:115], v[164:167], v[196:199], v[112:115]
	v_mfma_f32_16x16x32_bf16 v[100:103], v[156:159], v[204:207], v[100:103]
	v_mfma_f32_16x16x32_bf16 v[96:99], v[164:167], v[204:207], v[96:99]
	v_mfma_f32_16x16x32_bf16 v[84:87], v[156:159], v[212:215], v[84:87]
	v_mfma_f32_16x16x32_bf16 v[80:83], v[164:167], v[212:215], v[80:83]
	s_setprio 0
	s_setprio 1
	v_mfma_f32_16x16x32_bf16 v[108:111], v[168:171], v[184:187], 0
	v_mfma_f32_16x16x32_bf16 v[104:107], v[176:179], v[184:187], 0
	v_mfma_f32_16x16x32_bf16 v[92:95], v[168:171], v[192:195], 0
	v_mfma_f32_16x16x32_bf16 v[88:91], v[176:179], v[192:195], 0
	v_mfma_f32_16x16x32_bf16 v[76:79], v[168:171], v[200:203], 0
	v_mfma_f32_16x16x32_bf16 v[72:75], v[176:179], v[200:203], 0
	v_mfma_f32_16x16x32_bf16 v[68:71], v[168:171], v[208:211], 0
	v_mfma_f32_16x16x32_bf16 v[64:67], v[176:179], v[208:211], 0
	v_mfma_f32_16x16x32_bf16 v[108:111], v[172:175], v[188:191], v[108:111]
	v_mfma_f32_16x16x32_bf16 v[104:107], v[180:183], v[188:191], v[104:107]
	v_mfma_f32_16x16x32_bf16 v[92:95], v[172:175], v[196:199], v[92:95]
	v_mfma_f32_16x16x32_bf16 v[88:91], v[180:183], v[196:199], v[88:91]
	v_mfma_f32_16x16x32_bf16 v[76:79], v[172:175], v[204:207], v[76:79]
	v_mfma_f32_16x16x32_bf16 v[72:75], v[180:183], v[204:207], v[72:75]
	v_mfma_f32_16x16x32_bf16 v[68:71], v[172:175], v[212:215], v[68:71]
	v_mfma_f32_16x16x32_bf16 v[64:67], v[180:183], v[212:215], v[64:67]
	s_setprio 0
	s_barrier
	s_add_i32 s86, s72, s60
	v_lshl_add_u64 v[216:217], s[56:57], 0, v[130:131]
	s_mov_b32 m0, s86
	ds_read_b128 v[184:187], v149 offset:16384
	ds_read_b128 v[188:191], v149 offset:17408
	ds_read_b128 v[192:195], v149 offset:18432
	ds_read_b128 v[196:199], v149 offset:19456
	ds_read_b128 v[200:203], v149 offset:20480
	ds_read_b128 v[204:207], v149 offset:21504
	ds_read_b128 v[208:211], v149 offset:22528
	ds_read_b128 v[212:215], v149 offset:23552
	global_load_lds_dwordx4 v[216:217], off
	s_add_i32 m0, s86, 0x2000
	s_add_u32 s86, s56, 0x40000
	v_lshl_add_u64 v[218:219], s[56:57], 0, v[134:135]
	s_addc_u32 s87, s57, 0
	s_add_i32 s88, s73, s60
	global_load_lds_dwordx4 v[218:219], off
	v_lshl_add_u64 v[220:221], s[86:87], 0, v[130:131]
	s_mov_b32 m0, s88
	v_lshl_add_u64 v[222:223], s[58:59], 0, v[132:133]
	global_load_lds_dwordx4 v[220:221], off
	v_lshl_add_u64 v[220:221], s[86:87], 0, v[134:135]
	s_add_i32 m0, s88, 0x2000
	s_nop 0
	global_load_lds_dwordx4 v[220:221], off
	v_lshl_add_u64 v[220:221], s[58:59], 0, v[128:129]
	s_mov_b32 m0, s43
	s_nop 0
	global_load_lds_dwordx4 v[220:221], off
	s_mov_b32 m0, s50
	s_nop 0
	global_load_lds_dwordx4 v[222:223], off
	s_waitcnt vmcnt(8)
	s_waitcnt lgkmcnt(0)
	s_barrier
; #define PG8_STAGE(bufoff, gbase, voff) do { _Pragma("unroll") for (int _i = 0; _i < 2; ++_i) \
;         __builtin_amdgcn_global_load_lds((const unsigned*)((const char*)(gbase) + (voff)[_i]), (PG8_LAS unsigned*)(lds + (bufoff) + ldsw + _i * 8192), 16, 0, 0); } while (0)
; #define PG8_LDA(dst, b, h) do { _Pragma("unroll") for (int m = 0; m < 4; ++m) _Pragma("unroll") for (int k = 0; k < 2; ++k) dst[m][k] = *(const PG8_LAS bf16x8*)(lds + PG8_SA(b, h) + aoff + m * 2048 + k * 1024); } while (0)
; #define PG8_LDB(dst, b, h) do { _Pragma("unroll") for (int n = 0; n < 2; ++n) _Pragma("unroll") for (int k = 0; k < 2; ++k) dst[n][k] = *(const PG8_LAS bf16x8*)(lds + PG8_SB(b, h) + boff + n * 2048 + k * 1024); } while (0)
; #define PG8_MMA(ai, bj, At, Bt) do { __builtin_amdgcn_s_setprio(1); _Pragma("unroll") for (int m = 0; m < 4; ++m) _Pragma("unroll") for (int n = 0; n < 2; ++n) _Pragma("unroll") for (int k = 0; k < 2; ++k) \
;         acc[ai][bj][m][n] = __builtin_amdgcn_mfma_f32_16x16x32_bf16(Bt[n][k], At[m][k], acc[ai][bj][m][n], 0, 0, 0); __builtin_amdgcn_s_setprio(0); } while (0)
; #define PG8_WAIT_V(n) asm volatile("s_waitcnt vmcnt(" #n ")" ::: "memory")
; #define PG8_WAIT_L(n) asm volatile("s_waitcnt lgkmcnt(" #n ")" ::: "memory")
; #define PG8_BAR __builtin_amdgcn_s_barrier()
; #define PG8_SCHED __builtin_amdgcn_sched_barrier(0)
; template <class Epi, class Sched, bool ALIGN_EPI = false, bool SP2 = false>
; __device__ __forceinline__ void gemm_phase(PG8_LAS unsigned char* lds, const Gemm g, const Sched& S, const Epi& E) {
;     ...
;             PG8_WAIT_V(8); PG8_WAIT_L(0); PG8_BAR; PG8_MMA(1, 0, At, B0); PG8_MMA(1, 1, At, B1); PG8_BAR; PG8_SCHED;
;             PG8_LDB(B0, 1, 0); PG8_LDB(B1, 1, 1); PG8_SCHED; PG8_LDA(At, 1, 0); PG8_STAGE(PG8_SA(0, 1), a2 + hstep, voffA);
;             PG8_WAIT_V(8); PG8_WAIT_L(0); PG8_BAR; PG8_MMA(0, 0, At, B0); PG8_MMA(0, 1, At, B1); PG8_BAR; PG8_SCHED;
	s_setprio 1
	v_mfma_f32_16x16x32_bf16 v[60:63], v[152:155], v[184:187], 0
	v_mfma_f32_16x16x32_bf16 v[56:59], v[160:163], v[184:187], 0
	v_mfma_f32_16x16x32_bf16 v[52:55], v[152:155], v[192:195], 0
	v_mfma_f32_16x16x32_bf16 v[48:51], v[160:163], v[192:195], 0
	v_mfma_f32_16x16x32_bf16 v[36:39], v[152:155], v[200:203], 0
	v_mfma_f32_16x16x32_bf16 v[32:35], v[160:163], v[200:203], 0
	v_mfma_f32_16x16x32_bf16 v[20:23], v[152:155], v[208:211], 0
	v_mfma_f32_16x16x32_bf16 v[16:19], v[160:163], v[208:211], 0
	v_mfma_f32_16x16x32_bf16 v[60:63], v[156:159], v[188:191], v[60:63]
	v_mfma_f32_16x16x32_bf16 v[56:59], v[164:167], v[188:191], v[56:59]
	v_mfma_f32_16x16x32_bf16 v[52:55], v[156:159], v[196:199], v[52:55]
	v_mfma_f32_16x16x32_bf16 v[48:51], v[164:167], v[196:199], v[48:51]
	v_mfma_f32_16x16x32_bf16 v[36:39], v[156:159], v[204:207], v[36:39]
	v_mfma_f32_16x16x32_bf16 v[32:35], v[164:167], v[204:207], v[32:35]
	v_mfma_f32_16x16x32_bf16 v[20:23], v[156:159], v[212:215], v[20:23]
	v_mfma_f32_16x16x32_bf16 v[16:19], v[164:167], v[212:215], v[16:19]
	s_setprio 0
	s_setprio 1
	v_mfma_f32_16x16x32_bf16 v[44:47], v[168:171], v[184:187], 0
	v_mfma_f32_16x16x32_bf16 v[40:43], v[176:179], v[184:187], 0
	v_mfma_f32_16x16x32_bf16 v[28:31], v[168:171], v[192:195], 0
	v_mfma_f32_16x16x32_bf16 v[24:27], v[176:179], v[192:195], 0
	v_mfma_f32_16x16x32_bf16 v[12:15], v[168:171], v[200:203], 0
	v_mfma_f32_16x16x32_bf16 v[8:11], v[176:179], v[200:203], 0
	v_mfma_f32_16x16x32_bf16 v[4:7], v[168:171], v[208:211], 0
	v_mfma_f32_16x16x32_bf16 v[0:3], v[176:179], v[208:211], 0
	v_mfma_f32_16x16x32_bf16 v[44:47], v[172:175], v[188:191], v[44:47]
	v_mfma_f32_16x16x32_bf16 v[40:43], v[180:183], v[188:191], v[40:43]
	v_mfma_f32_16x16x32_bf16 v[28:31], v[172:175], v[196:199], v[28:31]
	v_mfma_f32_16x16x32_bf16 v[24:27], v[180:183], v[196:199], v[24:27]
	v_mfma_f32_16x16x32_bf16 v[12:15], v[172:175], v[204:207], v[12:15]
	v_mfma_f32_16x16x32_bf16 v[8:11], v[180:183], v[204:207], v[8:11]
	v_mfma_f32_16x16x32_bf16 v[4:7], v[172:175], v[212:215], v[4:7]
	v_mfma_f32_16x16x32_bf16 v[0:3], v[180:183], v[212:215], v[0:3]
	s_setprio 0
	s_barrier
	s_add_i32 s86, 0, 0x18000
	s_add_i32 s87, 0, 0x1c000
	v_add_u32_e32 v164, s86, v146
	v_add_u32_e32 v180, s87, v146
	ds_read_b128 v[152:155], v164
	ds_read_b128 v[156:159], v164 offset:1024
	ds_read_b128 v[160:163], v164 offset:2048
	ds_read_b128 v[164:167], v164 offset:3072
	ds_read_b128 v[168:171], v180
	ds_read_b128 v[172:175], v180 offset:1024
	ds_read_b128 v[176:179], v180 offset:2048
	ds_read_b128 v[180:183], v180 offset:3072
	s_add_u32 s58, s58, 0x40000
	s_addc_u32 s59, s59, 0
	s_mov_b32 m0, s51
	v_lshl_add_u64 v[224:225], s[58:59], 0, v[128:129]
	ds_read_b128 v[184:187], v149 offset:32768
	ds_read_b128 v[188:191], v149 offset:33792
	ds_read_b128 v[192:195], v149 offset:34816
	ds_read_b128 v[196:199], v149 offset:35840
	ds_read_b128 v[200:203], v149 offset:36864
	ds_read_b128 v[204:207], v149 offset:37888
	ds_read_b128 v[208:211], v149 offset:38912
	ds_read_b128 v[212:215], v149 offset:39936
	global_load_lds_dwordx4 v[224:225], off
	v_lshl_add_u64 v[224:225], s[58:59], 0, v[132:133]
	s_mov_b32 m0, s65
	s_nop 0
	global_load_lds_dwordx4 v[224:225], off
	s_waitcnt vmcnt(8)
	s_waitcnt lgkmcnt(0)
	s_barrier
	s_setprio 1
	v_mfma_f32_16x16x32_bf16 v[124:127], v[152:155], v[184:187], v[124:127]
	v_mfma_f32_16x16x32_bf16 v[120:123], v[160:163], v[184:187], v[120:123]
	v_mfma_f32_16x16x32_bf16 v[116:119], v[152:155], v[192:195], v[116:119]
	v_mfma_f32_16x16x32_bf16 v[112:115], v[160:163], v[192:195], v[112:115]
	v_mfma_f32_16x16x32_bf16 v[100:103], v[152:155], v[200:203], v[100:103]
	v_mfma_f32_16x16x32_bf16 v[96:99], v[160:163], v[200:203], v[96:99]
	v_mfma_f32_16x16x32_bf16 v[84:87], v[152:155], v[208:211], v[84:87]
	v_mfma_f32_16x16x32_bf16 v[80:83], v[160:163], v[208:211], v[80:83]
	v_mfma_f32_16x16x32_bf16 v[124:127], v[156:159], v[188:191], v[124:127]
	v_mfma_f32_16x16x32_bf16 v[120:123], v[164:167], v[188:191], v[120:123]
	v_mfma_f32_16x16x32_bf16 v[116:119], v[156:159], v[196:199], v[116:119]
	v_mfma_f32_16x16x32_bf16 v[112:115], v[164:167], v[196:199], v[112:115]
	v_mfma_f32_16x16x32_bf16 v[100:103], v[156:159], v[204:207], v[100:103]
	v_mfma_f32_16x16x32_bf16 v[96:99], v[164:167], v[204:207], v[96:99]
	v_mfma_f32_16x16x32_bf16 v[84:87], v[156:159], v[212:215], v[84:87]
	v_mfma_f32_16x16x32_bf16 v[80:83], v[164:167], v[212:215], v[80:83]
	s_setprio 0
	s_setprio 1
	v_mfma_f32_16x16x32_bf16 v[108:111], v[168:171], v[184:187], v[108:111]
	v_mfma_f32_16x16x32_bf16 v[104:107], v[176:179], v[184:187], v[104:107]
	v_mfma_f32_16x16x32_bf16 v[92:95], v[168:171], v[192:195], v[92:95]
	v_mfma_f32_16x16x32_bf16 v[88:91], v[176:179], v[192:195], v[88:91]
	v_mfma_f32_16x16x32_bf16 v[76:79], v[168:171], v[200:203], v[76:79]
	v_mfma_f32_16x16x32_bf16 v[72:75], v[176:179], v[200:203], v[72:75]
	v_mfma_f32_16x16x32_bf16 v[68:71], v[168:171], v[208:211], v[68:71]
	v_mfma_f32_16x16x32_bf16 v[64:67], v[176:179], v[208:211], v[64:67]
	v_mfma_f32_16x16x32_bf16 v[108:111], v[172:175], v[188:191], v[108:111]
	v_mfma_f32_16x16x32_bf16 v[104:107], v[180:183], v[188:191], v[104:107]
	v_mfma_f32_16x16x32_bf16 v[92:95], v[172:175], v[196:199], v[92:95]
	v_mfma_f32_16x16x32_bf16 v[88:91], v[180:183], v[196:199], v[88:91]
	v_mfma_f32_16x16x32_bf16 v[76:79], v[172:175], v[204:207], v[76:79]
	v_mfma_f32_16x16x32_bf16 v[72:75], v[180:183], v[204:207], v[72:75]
	v_mfma_f32_16x16x32_bf16 v[68:71], v[172:175], v[212:215], v[68:71]
	v_mfma_f32_16x16x32_bf16 v[64:67], v[180:183], v[212:215], v[64:67]
	s_setprio 0
	s_barrier
; #define PG8_STAGE(bufoff, gbase, voff) do { _Pragma("unroll") for (int _i = 0; _i < 2; ++_i) \
;         __builtin_amdgcn_global_load_lds((const unsigned*)((const char*)(gbase) + (voff)[_i]), (PG8_LAS unsigned*)(lds + (bufoff) + ldsw + _i * 8192), 16, 0, 0); } while (0)
; #define PG8_LDA(dst, b, h) do { _Pragma("unroll") for (int m = 0; m < 4; ++m) _Pragma("unroll") for (int k = 0; k < 2; ++k) dst[m][k] = *(const PG8_LAS bf16x8*)(lds + PG8_SA(b, h) + aoff + m * 2048 + k * 1024); } while (0)
; #define PG8_MMA(ai, bj, At, Bt) do { __builtin_amdgcn_s_setprio(1); _Pragma("unroll") for (int m = 0; m < 4; ++m) _Pragma("unroll") for (int n = 0; n < 2; ++n) _Pragma("unroll") for (int k = 0; k < 2; ++k) \
;         acc[ai][bj][m][n] = __builtin_amdgcn_mfma_f32_16x16x32_bf16(Bt[n][k], At[m][k], acc[ai][bj][m][n], 0, 0, 0); __builtin_amdgcn_s_setprio(0); } while (0)
; #define PG8_WAIT_V(n) asm volatile("s_waitcnt vmcnt(" #n ")" ::: "memory")
; #define PG8_WAIT_L(n) asm volatile("s_waitcnt lgkmcnt(" #n ")" ::: "memory")
; #define PG8_BAR __builtin_amdgcn_s_barrier()
; #define PG8_SCHED __builtin_amdgcn_sched_barrier(0)
; template <class Epi, class Sched, bool ALIGN_EPI = false, bool SP2 = false>
; __device__ __forceinline__ void gemm_phase(PG8_LAS unsigned char* lds, const Gemm g, const Sched& S, const Epi& E) {
;     ...
;         for (int t = 0; t < nt; t += 2) {
;     ...
;             PG8_LDA(At, 1, 1); PG8_STAGE(PG8_SB(1, 0), b3, voffB); PG8_STAGE(PG8_SB(1, 1), b3 + hstep, voffB); PG8_STAGE(PG8_SA(1, 0), a3, voffA);
;             PG8_WAIT_V(8); PG8_WAIT_L(0); PG8_BAR; PG8_MMA(1, 0, At, B0); PG8_MMA(1, 1, At, B1); PG8_BAR; PG8_SCHED;
	s_add_i32 s58, s86, s60
	v_lshl_add_u64 v[216:217], v[216:217], 0, s[10:11]
	s_mov_b32 m0, s58
	ds_read_b128 v[184:187], v149 offset:49152
	ds_read_b128 v[188:191], v149 offset:50176
	ds_read_b128 v[192:195], v149 offset:51200
	ds_read_b128 v[196:199], v149 offset:52224
	ds_read_b128 v[200:203], v149 offset:53248
	ds_read_b128 v[204:207], v149 offset:54272
	ds_read_b128 v[208:211], v149 offset:55296
	ds_read_b128 v[212:215], v149 offset:56320
	global_load_lds_dwordx4 v[216:217], off
	s_add_i32 m0, s58, 0x2000
	s_add_u32 s56, s56, 0x40080
	v_lshl_add_u64 v[216:217], v[218:219], 0, s[10:11]
	s_addc_u32 s57, s57, 0
	s_add_i32 s58, s87, s60
	global_load_lds_dwordx4 v[216:217], off
	v_lshl_add_u64 v[216:217], s[56:57], 0, v[130:131]
	s_mov_b32 m0, s58
	s_nop 0
	global_load_lds_dwordx4 v[216:217], off
	v_lshl_add_u64 v[216:217], s[56:57], 0, v[134:135]
	s_add_i32 m0, s58, 0x2000
	s_nop 0
	global_load_lds_dwordx4 v[216:217], off
	v_lshl_add_u64 v[216:217], v[220:221], 0, s[10:11]
	s_mov_b32 m0, s70
	s_nop 0
	global_load_lds_dwordx4 v[216:217], off
	v_lshl_add_u64 v[216:217], v[222:223], 0, s[10:11]
	s_mov_b32 m0, s71
	s_nop 0
	global_load_lds_dwordx4 v[216:217], off
	s_waitcnt vmcnt(8)
	s_waitcnt lgkmcnt(0)
	s_barrier
	s_setprio 1
	v_mfma_f32_16x16x32_bf16 v[60:63], v[152:155], v[184:187], v[60:63]
	v_mfma_f32_16x16x32_bf16 v[56:59], v[160:163], v[184:187], v[56:59]
	v_mfma_f32_16x16x32_bf16 v[52:55], v[152:155], v[192:195], v[52:55]
	v_mfma_f32_16x16x32_bf16 v[48:51], v[160:163], v[192:195], v[48:51]
	v_mfma_f32_16x16x32_bf16 v[36:39], v[152:155], v[200:203], v[36:39]
	v_mfma_f32_16x16x32_bf16 v[32:35], v[160:163], v[200:203], v[32:35]
	v_mfma_f32_16x16x32_bf16 v[20:23], v[152:155], v[208:211], v[20:23]
	v_mfma_f32_16x16x32_bf16 v[16:19], v[160:163], v[208:211], v[16:19]
	v_mfma_f32_16x16x32_bf16 v[60:63], v[156:159], v[188:191], v[60:63]
	v_mfma_f32_16x16x32_bf16 v[56:59], v[164:167], v[188:191], v[56:59]
	v_mfma_f32_16x16x32_bf16 v[52:55], v[156:159], v[196:199], v[52:55]
	v_mfma_f32_16x16x32_bf16 v[48:51], v[164:167], v[196:199], v[48:51]
	v_mfma_f32_16x16x32_bf16 v[36:39], v[156:159], v[204:207], v[36:39]
	v_mfma_f32_16x16x32_bf16 v[32:35], v[164:167], v[204:207], v[32:35]
	v_mfma_f32_16x16x32_bf16 v[20:23], v[156:159], v[212:215], v[20:23]
	v_mfma_f32_16x16x32_bf16 v[16:19], v[164:167], v[212:215], v[16:19]
	s_setprio 0
	s_setprio 1
	v_mfma_f32_16x16x32_bf16 v[44:47], v[168:171], v[184:187], v[44:47]
	v_mfma_f32_16x16x32_bf16 v[40:43], v[176:179], v[184:187], v[40:43]
	v_mfma_f32_16x16x32_bf16 v[28:31], v[168:171], v[192:195], v[28:31]
	v_mfma_f32_16x16x32_bf16 v[24:27], v[176:179], v[192:195], v[24:27]
	v_mfma_f32_16x16x32_bf16 v[12:15], v[168:171], v[200:203], v[12:15]
	v_mfma_f32_16x16x32_bf16 v[8:11], v[176:179], v[200:203], v[8:11]
	v_mfma_f32_16x16x32_bf16 v[4:7], v[168:171], v[208:211], v[4:7]
	v_mfma_f32_16x16x32_bf16 v[0:3], v[176:179], v[208:211], v[0:3]
	v_mfma_f32_16x16x32_bf16 v[44:47], v[172:175], v[188:191], v[44:47]
	v_mfma_f32_16x16x32_bf16 v[40:43], v[180:183], v[188:191], v[40:43]
	v_mfma_f32_16x16x32_bf16 v[28:31], v[172:175], v[196:199], v[28:31]
	v_mfma_f32_16x16x32_bf16 v[24:27], v[180:183], v[196:199], v[24:27]
	v_mfma_f32_16x16x32_bf16 v[12:15], v[172:175], v[204:207], v[12:15]
	v_mfma_f32_16x16x32_bf16 v[8:11], v[180:183], v[204:207], v[8:11]
	v_mfma_f32_16x16x32_bf16 v[4:7], v[172:175], v[212:215], v[4:7]
	v_mfma_f32_16x16x32_bf16 v[0:3], v[180:183], v[212:215], v[0:3]
	s_setprio 0
	s_barrier
	s_add_i32 s85, s85, 2
	s_add_u32 s54, s54, 0x100
	s_addc_u32 s55, s55, 0
	s_add_u32 s83, s83, 0x100
	s_addc_u32 s84, s84, 0
	s_cmp_gt_u32 s85, 13

; #define PG8_STAGE(bufoff, gbase, voff) do { _Pragma("unroll") for (int _i = 0; _i < 2; ++_i) \
;         __builtin_amdgcn_global_load_lds((const unsigned*)((const char*)(gbase) + (voff)[_i]), (PG8_LAS unsigned*)(lds + (bufoff) + ldsw + _i * 8192), 16, 0, 0); } while (0)
; #define PG8_LDA(dst, b, h) do { _Pragma("unroll") for (int m = 0; m < 4; ++m) _Pragma("unroll") for (int k = 0; k < 2; ++k) dst[m][k] = *(const PG8_LAS bf16x8*)(lds + PG8_SA(b, h) + aoff + m * 2048 + k * 1024); } while (0)
; #define PG8_LDB(dst, b, h) do { _Pragma("unroll") for (int n = 0; n < 2; ++n) _Pragma("unroll") for (int k = 0; k < 2; ++k) dst[n][k] = *(const PG8_LAS bf16x8*)(lds + PG8_SB(b, h) + boff + n * 2048 + k * 1024); } while (0)
; #define PG8_WAIT_V(n) asm volatile("s_waitcnt vmcnt(" #n ")" ::: "memory")
; #define PG8_WAIT_L(n) asm volatile("s_waitcnt lgkmcnt(" #n ")" ::: "memory")
; #define PG8_BAR __builtin_amdgcn_s_barrier()
; #define PG8_SCHED __builtin_amdgcn_sched_barrier(0)
; template <class Epi, class Sched, bool ALIGN_EPI = false, bool SP2 = false>
; __device__ __forceinline__ void gemm_phase(PG8_LAS unsigned char* lds, const Gemm g, const Sched& S, const Epi& E) {
;     ...
;         const bool has_next = S.next(ui + 1, nxt);
;         const char* nA = has_next ? (const char*)g.A + (size_t)nxt.pm * tstep : cA; const char* nB = has_next ? (const char*)g.Bt + (size_t)nxt.pn * tstep : cB;
;         for (int t = 0; t < nt; t += 2) {
;             const bool last = (t == nt - 2);
;             const char* a1 = cA + (size_t)(t + 1) * kstep;
;             const char* a2 = last ? nA : cA + (size_t)(t + 2) * kstep; const char* b2 = last ? nB : cB + (size_t)(t + 2) * kstep;
;             const char* a3 = a2 + kstep; const char* b3 = b2 + kstep;
;             if (last && has_next) S.a_ready(nxt);
;             if constexpr (SP2) {
;             PG8_LDB(B0, 0, 0); PG8_LDB(B1, 0, 1); PG8_SCHED; PG8_LDA(At, 0, 0); PG8_STAGE(PG8_SA(1, 1), a1 + hstep, voffA);
;             PG8_WAIT_V(8); PG8_WAIT_L(0); PG8_BAR; PG8_MMA(0, 0, At, B0); PG8_MMA(0, 1, At, B1); PG8_BAR; PG8_SCHED;
;             PG8_LDA(At, 0, 1); PG8_STAGE(PG8_SB(0, 0), b2, voffB); PG8_STAGE(PG8_SB(0, 1), b2 + hstep, voffB); PG8_STAGE(PG8_SA(0, 0), a2, voffA);
;             PG8_WAIT_V(8); PG8_WAIT_L(0); PG8_BAR; PG8_MMA(1, 0, At, B0); PG8_MMA(1, 1, At, B1); PG8_BAR; PG8_SCHED;
.LBB0_1534:
	s_ashr_i32 s23, s22, 31
	s_lshl_b64 s[36:37], s[22:23], 19
	s_add_u32 s36, s3, s36
	s_addc_u32 s37, s33, s37
	s_and_b64 s[38:39], s[4:5], exec
	s_cselect_b32 s23, s37, s43
	s_cselect_b32 s66, s36, s42
	s_ashr_i32 s19, s18, 31
	s_lshl_b64 s[38:39], s[18:19], 19
	s_add_u32 s38, s48, s38
	s_addc_u32 s39, s49, s39
	s_and_b64 s[46:47], s[4:5], exec
	s_cselect_b32 s19, s39, s45
	s_cselect_b32 s67, s38, s44
	s_add_u32 s42, s42, 0x40080
	s_addc_u32 s43, s43, 0
	s_add_u32 s68, s44, 0x100
	s_addc_u32 s69, s45, 0
	s_mov_b32 s70, -2
	ds_read_b128 v[146:149], v153
	ds_read_b128 v[156:159], v153 offset:1024
	ds_read_b128 v[160:163], v153 offset:2048
	ds_read_b128 v[164:167], v153 offset:3072
	ds_read_b128 v[168:171], v154
	ds_read_b128 v[172:175], v154 offset:1024
	ds_read_b128 v[176:179], v154 offset:2048
	ds_read_b128 v[180:183], v154 offset:3072
	s_add_u32 s44, s42, 0xfffc0080
	s_addc_u32 s45, s43, -1
	s_cmp_eq_u32 s70, 12
	s_cselect_b32 s47, s23, s45
	s_cselect_b32 s46, s66, s44
	s_cselect_b32 s45, s19, s69
	s_cselect_b32 s44, s67, s68
	v_lshl_add_u64 v[216:217], s[42:43], 0, v[136:137]
	s_add_i32 m0, s41, 0xc000
	ds_read_b128 v[184:187], v155
	ds_read_b128 v[188:191], v155 offset:1024
	ds_read_b128 v[192:195], v155 offset:2048
	ds_read_b128 v[196:199], v155 offset:3072
	ds_read_b128 v[200:203], v155 offset:4096
	ds_read_b128 v[204:207], v155 offset:5120
	ds_read_b128 v[208:211], v155 offset:6144
	ds_read_b128 v[212:215], v155 offset:7168
	global_load_lds_dwordx4 v[216:217], off
	v_lshl_add_u64 v[216:217], s[42:43], 0, v[138:139]
	s_add_i32 m0, s41, 0xe000
	s_nop 0
	global_load_lds_dwordx4 v[216:217], off
	s_waitcnt vmcnt(8)
	s_waitcnt lgkmcnt(0)
	s_barrier
	s_setprio 1
	v_mfma_f32_16x16x32_bf16 v[124:127], v[146:149], v[184:187], 0
	v_mfma_f32_16x16x32_bf16 v[120:123], v[160:163], v[184:187], 0
	v_mfma_f32_16x16x32_bf16 v[108:111], v[146:149], v[192:195], 0
	v_mfma_f32_16x16x32_bf16 v[104:107], v[160:163], v[192:195], 0
	v_mfma_f32_16x16x32_bf16 v[92:95], v[146:149], v[200:203], 0
	v_mfma_f32_16x16x32_bf16 v[88:91], v[160:163], v[200:203], 0
	v_mfma_f32_16x16x32_bf16 v[76:79], v[146:149], v[208:211], 0
	v_mfma_f32_16x16x32_bf16 v[72:75], v[160:163], v[208:211], 0
	v_mfma_f32_16x16x32_bf16 v[124:127], v[156:159], v[188:191], v[124:127]
	v_mfma_f32_16x16x32_bf16 v[120:123], v[164:167], v[188:191], v[120:123]
	v_mfma_f32_16x16x32_bf16 v[108:111], v[156:159], v[196:199], v[108:111]
	v_mfma_f32_16x16x32_bf16 v[104:107], v[164:167], v[196:199], v[104:107]
	v_mfma_f32_16x16x32_bf16 v[92:95], v[156:159], v[204:207], v[92:95]
	v_mfma_f32_16x16x32_bf16 v[88:91], v[164:167], v[204:207], v[88:91]
	v_mfma_f32_16x16x32_bf16 v[76:79], v[156:159], v[212:215], v[76:79]
	v_mfma_f32_16x16x32_bf16 v[72:75], v[164:167], v[212:215], v[72:75]
	s_setprio 0
	s_setprio 1
	v_mfma_f32_16x16x32_bf16 v[116:119], v[168:171], v[184:187], 0
	v_mfma_f32_16x16x32_bf16 v[112:115], v[176:179], v[184:187], 0
	v_mfma_f32_16x16x32_bf16 v[100:103], v[168:171], v[192:195], 0
	v_mfma_f32_16x16x32_bf16 v[96:99], v[176:179], v[192:195], 0
	v_mfma_f32_16x16x32_bf16 v[84:87], v[168:171], v[200:203], 0
	v_mfma_f32_16x16x32_bf16 v[80:83], v[176:179], v[200:203], 0
	v_mfma_f32_16x16x32_bf16 v[68:71], v[168:171], v[208:211], 0
	v_mfma_f32_16x16x32_bf16 v[64:67], v[176:179], v[208:211], 0
	v_mfma_f32_16x16x32_bf16 v[116:119], v[172:175], v[188:191], v[116:119]
	v_mfma_f32_16x16x32_bf16 v[112:115], v[180:183], v[188:191], v[112:115]
	v_mfma_f32_16x16x32_bf16 v[100:103], v[172:175], v[196:199], v[100:103]
	v_mfma_f32_16x16x32_bf16 v[96:99], v[180:183], v[196:199], v[96:99]
	v_mfma_f32_16x16x32_bf16 v[84:87], v[172:175], v[204:207], v[84:87]
	v_mfma_f32_16x16x32_bf16 v[80:83], v[180:183], v[204:207], v[80:83]
	v_mfma_f32_16x16x32_bf16 v[68:71], v[172:175], v[212:215], v[68:71]
	v_mfma_f32_16x16x32_bf16 v[64:67], v[180:183], v[212:215], v[64:67]
	s_setprio 0
	s_barrier
	s_add_i32 s71, s62, s50
	v_lshl_add_u64 v[216:217], s[44:45], 0, v[130:131]
	s_mov_b32 m0, s71
	ds_read_b128 v[184:187], v155 offset:16384
	ds_read_b128 v[188:191], v155 offset:17408
	ds_read_b128 v[192:195], v155 offset:18432
	ds_read_b128 v[196:199], v155 offset:19456
	ds_read_b128 v[200:203], v155 offset:20480
	ds_read_b128 v[204:207], v155 offset:21504
	ds_read_b128 v[208:211], v155 offset:22528
	ds_read_b128 v[212:215], v155 offset:23552
	global_load_lds_dwordx4 v[216:217], off
	s_add_i32 m0, s71, 0x2000
	s_add_u32 s72, s44, 0x40000
	v_lshl_add_u64 v[218:219], s[44:45], 0, v[134:135]
	s_addc_u32 s73, s45, 0
	s_add_i32 s71, s63, s50
	global_load_lds_dwordx4 v[218:219], off
	v_lshl_add_u64 v[220:221], s[72:73], 0, v[130:131]
	s_mov_b32 m0, s71
	v_lshl_add_u64 v[222:223], s[46:47], 0, v[132:133]
	global_load_lds_dwordx4 v[220:221], off
	v_lshl_add_u64 v[220:221], s[72:73], 0, v[134:135]
	s_add_i32 m0, s71, 0x2000
	s_nop 0
	global_load_lds_dwordx4 v[220:221], off
	v_lshl_add_u64 v[220:221], s[46:47], 0, v[128:129]
	s_mov_b32 m0, s41
	s_nop 0
	global_load_lds_dwordx4 v[220:221], off
	s_mov_b32 m0, s52
	s_nop 0
	global_load_lds_dwordx4 v[222:223], off
	s_waitcnt vmcnt(8)
	s_waitcnt lgkmcnt(0)
	s_barrier
; #define PG8_STAGE(bufoff, gbase, voff) do { _Pragma("unroll") for (int _i = 0; _i < 2; ++_i) \
;         __builtin_amdgcn_global_load_lds((const unsigned*)((const char*)(gbase) + (voff)[_i]), (PG8_LAS unsigned*)(lds + (bufoff) + ldsw + _i * 8192), 16, 0, 0); } while (0)
; #define PG8_LDA(dst, b, h) do { _Pragma("unroll") for (int m = 0; m < 4; ++m) _Pragma("unroll") for (int k = 0; k < 2; ++k) dst[m][k] = *(const PG8_LAS bf16x8*)(lds + PG8_SA(b, h) + aoff + m * 2048 + k * 1024); } while (0)
; #define PG8_LDB(dst, b, h) do { _Pragma("unroll") for (int n = 0; n < 2; ++n) _Pragma("unroll") for (int k = 0; k < 2; ++k) dst[n][k] = *(const PG8_LAS bf16x8*)(lds + PG8_SB(b, h) + boff + n * 2048 + k * 1024); } while (0)
; #define PG8_MMA(ai, bj, At, Bt) do { __builtin_amdgcn_s_setprio(1); _Pragma("unroll") for (int m = 0; m < 4; ++m) _Pragma("unroll") for (int n = 0; n < 2; ++n) _Pragma("unroll") for (int k = 0; k < 2; ++k) \
;         acc[ai][bj][m][n] = __builtin_amdgcn_mfma_f32_16x16x32_bf16(Bt[n][k], At[m][k], acc[ai][bj][m][n], 0, 0, 0); __builtin_amdgcn_s_setprio(0); } while (0)
; #define PG8_WAIT_V(n) asm volatile("s_waitcnt vmcnt(" #n ")" ::: "memory")
; #define PG8_WAIT_L(n) asm volatile("s_waitcnt lgkmcnt(" #n ")" ::: "memory")
; #define PG8_BAR __builtin_amdgcn_s_barrier()
; #define PG8_SCHED __builtin_amdgcn_sched_barrier(0)
; template <class Epi, class Sched, bool ALIGN_EPI = false, bool SP2 = false>
; __device__ __forceinline__ void gemm_phase(PG8_LAS unsigned char* lds, const Gemm g, const Sched& S, const Epi& E) {
;     ...
;             PG8_WAIT_V(8); PG8_WAIT_L(0); PG8_BAR; PG8_MMA(1, 0, At, B0); PG8_MMA(1, 1, At, B1); PG8_BAR; PG8_SCHED;
;             PG8_LDB(B0, 1, 0); PG8_LDB(B1, 1, 1); PG8_SCHED; PG8_LDA(At, 1, 0); PG8_STAGE(PG8_SA(0, 1), a2 + hstep, voffA);
;             PG8_WAIT_V(8); PG8_WAIT_L(0); PG8_BAR; PG8_MMA(0, 0, At, B0); PG8_MMA(0, 1, At, B1); PG8_BAR; PG8_SCHED;
	s_setprio 1
	v_mfma_f32_16x16x32_bf16 v[60:63], v[146:149], v[184:187], 0
	v_mfma_f32_16x16x32_bf16 v[56:59], v[160:163], v[184:187], 0
	v_mfma_f32_16x16x32_bf16 v[44:47], v[146:149], v[192:195], 0
	v_mfma_f32_16x16x32_bf16 v[40:43], v[160:163], v[192:195], 0
	v_mfma_f32_16x16x32_bf16 v[28:31], v[146:149], v[200:203], 0
	v_mfma_f32_16x16x32_bf16 v[24:27], v[160:163], v[200:203], 0
	v_mfma_f32_16x16x32_bf16 v[12:15], v[146:149], v[208:211], 0
	v_mfma_f32_16x16x32_bf16 v[8:11], v[160:163], v[208:211], 0
	v_mfma_f32_16x16x32_bf16 v[60:63], v[156:159], v[188:191], v[60:63]
	v_mfma_f32_16x16x32_bf16 v[56:59], v[164:167], v[188:191], v[56:59]
	v_mfma_f32_16x16x32_bf16 v[44:47], v[156:159], v[196:199], v[44:47]
	v_mfma_f32_16x16x32_bf16 v[40:43], v[164:167], v[196:199], v[40:43]
	v_mfma_f32_16x16x32_bf16 v[28:31], v[156:159], v[204:207], v[28:31]
	v_mfma_f32_16x16x32_bf16 v[24:27], v[164:167], v[204:207], v[24:27]
	v_mfma_f32_16x16x32_bf16 v[12:15], v[156:159], v[212:215], v[12:15]
	v_mfma_f32_16x16x32_bf16 v[8:11], v[164:167], v[212:215], v[8:11]
	s_setprio 0
	s_setprio 1
	v_mfma_f32_16x16x32_bf16 v[52:55], v[168:171], v[184:187], 0
	v_mfma_f32_16x16x32_bf16 v[48:51], v[176:179], v[184:187], 0
	v_mfma_f32_16x16x32_bf16 v[36:39], v[168:171], v[192:195], 0
	v_mfma_f32_16x16x32_bf16 v[32:35], v[176:179], v[192:195], 0
	v_mfma_f32_16x16x32_bf16 v[20:23], v[168:171], v[200:203], 0
	v_mfma_f32_16x16x32_bf16 v[16:19], v[176:179], v[200:203], 0
	v_mfma_f32_16x16x32_bf16 v[4:7], v[168:171], v[208:211], 0
	v_mfma_f32_16x16x32_bf16 v[0:3], v[176:179], v[208:211], 0
	v_mfma_f32_16x16x32_bf16 v[52:55], v[172:175], v[188:191], v[52:55]
	v_mfma_f32_16x16x32_bf16 v[48:51], v[180:183], v[188:191], v[48:51]
	v_mfma_f32_16x16x32_bf16 v[36:39], v[172:175], v[196:199], v[36:39]
	v_mfma_f32_16x16x32_bf16 v[32:35], v[180:183], v[196:199], v[32:35]
	v_mfma_f32_16x16x32_bf16 v[20:23], v[172:175], v[204:207], v[20:23]
	v_mfma_f32_16x16x32_bf16 v[16:19], v[180:183], v[204:207], v[16:19]
	v_mfma_f32_16x16x32_bf16 v[4:7], v[172:175], v[212:215], v[4:7]
	v_mfma_f32_16x16x32_bf16 v[0:3], v[180:183], v[212:215], v[0:3]
	s_setprio 0
	s_barrier
	s_add_i32 s71, 0, 0x18000
	s_add_i32 s72, 0, 0x1c000
	v_add_u32_e32 v164, s71, v152
	v_add_u32_e32 v180, s72, v152
	ds_read_b128 v[146:149], v164
	ds_read_b128 v[156:159], v164 offset:1024
	ds_read_b128 v[160:163], v164 offset:2048
	ds_read_b128 v[164:167], v164 offset:3072
	ds_read_b128 v[168:171], v180
	ds_read_b128 v[172:175], v180 offset:1024
	ds_read_b128 v[176:179], v180 offset:2048
	ds_read_b128 v[180:183], v180 offset:3072
	s_add_u32 s46, s46, 0x40000
	s_addc_u32 s47, s47, 0
	s_mov_b32 m0, s53
	v_lshl_add_u64 v[224:225], s[46:47], 0, v[128:129]
	ds_read_b128 v[184:187], v155 offset:32768
	ds_read_b128 v[188:191], v155 offset:33792
	ds_read_b128 v[192:195], v155 offset:34816
	ds_read_b128 v[196:199], v155 offset:35840
	ds_read_b128 v[200:203], v155 offset:36864
	ds_read_b128 v[204:207], v155 offset:37888
	ds_read_b128 v[208:211], v155 offset:38912
	ds_read_b128 v[212:215], v155 offset:39936
	global_load_lds_dwordx4 v[224:225], off
	v_lshl_add_u64 v[224:225], s[46:47], 0, v[132:133]
	s_mov_b32 m0, s54
	s_nop 0
	global_load_lds_dwordx4 v[224:225], off
	s_waitcnt vmcnt(8)
	s_waitcnt lgkmcnt(0)
	s_barrier
	s_setprio 1
	v_mfma_f32_16x16x32_bf16 v[124:127], v[146:149], v[184:187], v[124:127]
	v_mfma_f32_16x16x32_bf16 v[120:123], v[160:163], v[184:187], v[120:123]
	v_mfma_f32_16x16x32_bf16 v[108:111], v[146:149], v[192:195], v[108:111]
	v_mfma_f32_16x16x32_bf16 v[104:107], v[160:163], v[192:195], v[104:107]
	v_mfma_f32_16x16x32_bf16 v[92:95], v[146:149], v[200:203], v[92:95]
	v_mfma_f32_16x16x32_bf16 v[88:91], v[160:163], v[200:203], v[88:91]
	v_mfma_f32_16x16x32_bf16 v[76:79], v[146:149], v[208:211], v[76:79]
	v_mfma_f32_16x16x32_bf16 v[72:75], v[160:163], v[208:211], v[72:75]
	v_mfma_f32_16x16x32_bf16 v[124:127], v[156:159], v[188:191], v[124:127]
	v_mfma_f32_16x16x32_bf16 v[120:123], v[164:167], v[188:191], v[120:123]
	v_mfma_f32_16x16x32_bf16 v[108:111], v[156:159], v[196:199], v[108:111]
	v_mfma_f32_16x16x32_bf16 v[104:107], v[164:167], v[196:199], v[104:107]
	v_mfma_f32_16x16x32_bf16 v[92:95], v[156:159], v[204:207], v[92:95]
	v_mfma_f32_16x16x32_bf16 v[88:91], v[164:167], v[204:207], v[88:91]
	v_mfma_f32_16x16x32_bf16 v[76:79], v[156:159], v[212:215], v[76:79]
	v_mfma_f32_16x16x32_bf16 v[72:75], v[164:167], v[212:215], v[72:75]
	s_setprio 0
	s_setprio 1
	v_mfma_f32_16x16x32_bf16 v[116:119], v[168:171], v[184:187], v[116:119]
	v_mfma_f32_16x16x32_bf16 v[112:115], v[176:179], v[184:187], v[112:115]
	v_mfma_f32_16x16x32_bf16 v[100:103], v[168:171], v[192:195], v[100:103]
	v_mfma_f32_16x16x32_bf16 v[96:99], v[176:179], v[192:195], v[96:99]
	v_mfma_f32_16x16x32_bf16 v[84:87], v[168:171], v[200:203], v[84:87]
	v_mfma_f32_16x16x32_bf16 v[80:83], v[176:179], v[200:203], v[80:83]
	v_mfma_f32_16x16x32_bf16 v[68:71], v[168:171], v[208:211], v[68:71]
	v_mfma_f32_16x16x32_bf16 v[64:67], v[176:179], v[208:211], v[64:67]
	v_mfma_f32_16x16x32_bf16 v[116:119], v[172:175], v[188:191], v[116:119]
	v_mfma_f32_16x16x32_bf16 v[112:115], v[180:183], v[188:191], v[112:115]
	v_mfma_f32_16x16x32_bf16 v[100:103], v[172:175], v[196:199], v[100:103]
	v_mfma_f32_16x16x32_bf16 v[96:99], v[180:183], v[196:199], v[96:99]
	v_mfma_f32_16x16x32_bf16 v[84:87], v[172:175], v[204:207], v[84:87]
	v_mfma_f32_16x16x32_bf16 v[80:83], v[180:183], v[204:207], v[80:83]
	v_mfma_f32_16x16x32_bf16 v[68:71], v[172:175], v[212:215], v[68:71]
	v_mfma_f32_16x16x32_bf16 v[64:67], v[180:183], v[212:215], v[64:67]
	s_setprio 0
	s_barrier
; #define PG8_STAGE(bufoff, gbase, voff) do { _Pragma("unroll") for (int _i = 0; _i < 2; ++_i) \
;         __builtin_amdgcn_global_load_lds((const unsigned*)((const char*)(gbase) + (voff)[_i]), (PG8_LAS unsigned*)(lds + (bufoff) + ldsw + _i * 8192), 16, 0, 0); } while (0)
; #define PG8_LDA(dst, b, h) do { _Pragma("unroll") for (int m = 0; m < 4; ++m) _Pragma("unroll") for (int k = 0; k < 2; ++k) dst[m][k] = *(const PG8_LAS bf16x8*)(lds + PG8_SA(b, h) + aoff + m * 2048 + k * 1024); } while (0)
; #define PG8_MMA(ai, bj, At, Bt) do { __builtin_amdgcn_s_setprio(1); _Pragma("unroll") for (int m = 0; m < 4; ++m) _Pragma("unroll") for (int n = 0; n < 2; ++n) _Pragma("unroll") for (int k = 0; k < 2; ++k) \
;         acc[ai][bj][m][n] = __builtin_amdgcn_mfma_f32_16x16x32_bf16(Bt[n][k], At[m][k], acc[ai][bj][m][n], 0, 0, 0); __builtin_amdgcn_s_setprio(0); } while (0)
; #define PG8_WAIT_V(n) asm volatile("s_waitcnt vmcnt(" #n ")" ::: "memory")
; #define PG8_WAIT_L(n) asm volatile("s_waitcnt lgkmcnt(" #n ")" ::: "memory")
; #define PG8_BAR __builtin_amdgcn_s_barrier()
; #define PG8_SCHED __builtin_amdgcn_sched_barrier(0)
; template <class Epi, class Sched, bool ALIGN_EPI = false, bool SP2 = false>
; __device__ __forceinline__ void gemm_phase(PG8_LAS unsigned char* lds, const Gemm g, const Sched& S, const Epi& E) {
;     ...
;         for (int t = 0; t < nt; t += 2) {
;     ...
;             PG8_LDA(At, 1, 1); PG8_STAGE(PG8_SB(1, 0), b3, voffB); PG8_STAGE(PG8_SB(1, 1), b3 + hstep, voffB); PG8_STAGE(PG8_SA(1, 0), a3, voffA);
;             PG8_WAIT_V(8); PG8_WAIT_L(0); PG8_BAR; PG8_MMA(1, 0, At, B0); PG8_MMA(1, 1, At, B1); PG8_BAR; PG8_SCHED;
	s_add_i32 s46, s71, s50
	v_lshl_add_u64 v[216:217], v[216:217], 0, s[12:13]
	s_mov_b32 m0, s46
	ds_read_b128 v[184:187], v155 offset:49152
	ds_read_b128 v[188:191], v155 offset:50176
	ds_read_b128 v[192:195], v155 offset:51200
	ds_read_b128 v[196:199], v155 offset:52224
	ds_read_b128 v[200:203], v155 offset:53248
	ds_read_b128 v[204:207], v155 offset:54272
	ds_read_b128 v[208:211], v155 offset:55296
	ds_read_b128 v[212:215], v155 offset:56320
	global_load_lds_dwordx4 v[216:217], off
	s_add_i32 m0, s46, 0x2000
	s_add_u32 s44, s44, 0x40080
	v_lshl_add_u64 v[216:217], v[218:219], 0, s[12:13]
	s_addc_u32 s45, s45, 0
	s_add_i32 s46, s72, s50
	global_load_lds_dwordx4 v[216:217], off
	v_lshl_add_u64 v[216:217], s[44:45], 0, v[130:131]
	s_mov_b32 m0, s46
	s_nop 0
	global_load_lds_dwordx4 v[216:217], off
	v_lshl_add_u64 v[216:217], s[44:45], 0, v[134:135]
	s_add_i32 m0, s46, 0x2000
	s_nop 0
	global_load_lds_dwordx4 v[216:217], off
	v_lshl_add_u64 v[216:217], v[220:221], 0, s[12:13]
	s_mov_b32 m0, s59
	s_nop 0
	global_load_lds_dwordx4 v[216:217], off
	v_lshl_add_u64 v[216:217], v[222:223], 0, s[12:13]
	s_mov_b32 m0, s60
	s_nop 0
	global_load_lds_dwordx4 v[216:217], off
	s_waitcnt vmcnt(8)
	s_waitcnt lgkmcnt(0)
	s_barrier
	s_setprio 1
	v_mfma_f32_16x16x32_bf16 v[60:63], v[146:149], v[184:187], v[60:63]
	v_mfma_f32_16x16x32_bf16 v[56:59], v[160:163], v[184:187], v[56:59]
	v_mfma_f32_16x16x32_bf16 v[44:47], v[146:149], v[192:195], v[44:47]
	v_mfma_f32_16x16x32_bf16 v[40:43], v[160:163], v[192:195], v[40:43]
	v_mfma_f32_16x16x32_bf16 v[28:31], v[146:149], v[200:203], v[28:31]
	v_mfma_f32_16x16x32_bf16 v[24:27], v[160:163], v[200:203], v[24:27]
	v_mfma_f32_16x16x32_bf16 v[12:15], v[146:149], v[208:211], v[12:15]
	v_mfma_f32_16x16x32_bf16 v[8:11], v[160:163], v[208:211], v[8:11]
	v_mfma_f32_16x16x32_bf16 v[60:63], v[156:159], v[188:191], v[60:63]
	v_mfma_f32_16x16x32_bf16 v[56:59], v[164:167], v[188:191], v[56:59]
	v_mfma_f32_16x16x32_bf16 v[44:47], v[156:159], v[196:199], v[44:47]
	v_mfma_f32_16x16x32_bf16 v[40:43], v[164:167], v[196:199], v[40:43]
	v_mfma_f32_16x16x32_bf16 v[28:31], v[156:159], v[204:207], v[28:31]
	v_mfma_f32_16x16x32_bf16 v[24:27], v[164:167], v[204:207], v[24:27]
	v_mfma_f32_16x16x32_bf16 v[12:15], v[156:159], v[212:215], v[12:15]
	v_mfma_f32_16x16x32_bf16 v[8:11], v[164:167], v[212:215], v[8:11]
	s_setprio 0
	s_setprio 1
	v_mfma_f32_16x16x32_bf16 v[52:55], v[168:171], v[184:187], v[52:55]
	v_mfma_f32_16x16x32_bf16 v[48:51], v[176:179], v[184:187], v[48:51]
	v_mfma_f32_16x16x32_bf16 v[36:39], v[168:171], v[192:195], v[36:39]
	v_mfma_f32_16x16x32_bf16 v[32:35], v[176:179], v[192:195], v[32:35]
	v_mfma_f32_16x16x32_bf16 v[20:23], v[168:171], v[200:203], v[20:23]
	v_mfma_f32_16x16x32_bf16 v[16:19], v[176:179], v[200:203], v[16:19]
	v_mfma_f32_16x16x32_bf16 v[4:7], v[168:171], v[208:211], v[4:7]
	v_mfma_f32_16x16x32_bf16 v[0:3], v[176:179], v[208:211], v[0:3]
	v_mfma_f32_16x16x32_bf16 v[52:55], v[172:175], v[188:191], v[52:55]
	v_mfma_f32_16x16x32_bf16 v[48:51], v[180:183], v[188:191], v[48:51]
	v_mfma_f32_16x16x32_bf16 v[36:39], v[172:175], v[196:199], v[36:39]
	v_mfma_f32_16x16x32_bf16 v[32:35], v[180:183], v[196:199], v[32:35]
	v_mfma_f32_16x16x32_bf16 v[20:23], v[172:175], v[204:207], v[20:23]
	v_mfma_f32_16x16x32_bf16 v[16:19], v[180:183], v[204:207], v[16:19]
	v_mfma_f32_16x16x32_bf16 v[4:7], v[172:175], v[212:215], v[4:7]
	v_mfma_f32_16x16x32_bf16 v[0:3], v[180:183], v[212:215], v[0:3]
	s_setprio 0
	s_barrier
	s_add_i32 s70, s70, 2
	s_add_u32 s42, s42, 0x100
	s_addc_u32 s43, s43, 0
	s_add_u32 s68, s68, 0x100
	s_addc_u32 s69, s69, 0
	s_cmp_gt_u32 s70, 13

; #define PG8_STAGE(bufoff, gbase, voff) do { _Pragma("unroll") for (int _i = 0; _i < 2; ++_i) \
;         __builtin_amdgcn_global_load_lds((const unsigned*)((const char*)(gbase) + (voff)[_i]), (PG8_LAS unsigned*)(lds + (bufoff) + ldsw + _i * 8192), 16, 0, 0); } while (0)
; #define PG8_LDA(dst, b, h) do { _Pragma("unroll") for (int m = 0; m < 4; ++m) _Pragma("unroll") for (int k = 0; k < 2; ++k) dst[m][k] = *(const PG8_LAS bf16x8*)(lds + PG8_SA(b, h) + aoff + m * 2048 + k * 1024); } while (0)
; #define PG8_LDB(dst, b, h) do { _Pragma("unroll") for (int n = 0; n < 2; ++n) _Pragma("unroll") for (int k = 0; k < 2; ++k) dst[n][k] = *(const PG8_LAS bf16x8*)(lds + PG8_SB(b, h) + boff + n * 2048 + k * 1024); } while (0)
; #define PG8_WAIT_V(n) asm volatile("s_waitcnt vmcnt(" #n ")" ::: "memory")
; #define PG8_WAIT_L(n) asm volatile("s_waitcnt lgkmcnt(" #n ")" ::: "memory")
; #define PG8_BAR __builtin_amdgcn_s_barrier()
; #define PG8_SCHED __builtin_amdgcn_sched_barrier(0)
; template <class Epi, class Sched, bool ALIGN_EPI = false, bool SP2 = false>
; __device__ __forceinline__ void gemm_phase(PG8_LAS unsigned char* lds, const Gemm g, const Sched& S, const Epi& E) {
;     ...
;         const bool has_next = S.next(ui + 1, nxt);
;         const char* nA = has_next ? (const char*)g.A + (size_t)nxt.pm * tstep : cA; const char* nB = has_next ? (const char*)g.Bt + (size_t)nxt.pn * tstep : cB;
;         for (int t = 0; t < nt; t += 2) {
;             const bool last = (t == nt - 2);
;             const char* a1 = cA + (size_t)(t + 1) * kstep;
;             const char* a2 = last ? nA : cA + (size_t)(t + 2) * kstep; const char* b2 = last ? nB : cB + (size_t)(t + 2) * kstep;
;             const char* a3 = a2 + kstep; const char* b3 = b2 + kstep;
;             if (last && has_next) S.a_ready(nxt);
;             if constexpr (SP2) {
;             PG8_LDB(B0, 0, 0); PG8_LDB(B1, 0, 1); PG8_SCHED; PG8_LDA(At, 0, 0); PG8_STAGE(PG8_SA(1, 1), a1 + hstep, voffA);
;             PG8_WAIT_V(8); PG8_WAIT_L(0); PG8_BAR; PG8_MMA(0, 0, At, B0); PG8_MMA(0, 1, At, B1); PG8_BAR; PG8_SCHED;
;             PG8_LDA(At, 0, 1); PG8_STAGE(PG8_SB(0, 0), b2, voffB); PG8_STAGE(PG8_SB(0, 1), b2 + hstep, voffB); PG8_STAGE(PG8_SA(0, 0), a2, voffA);
;             PG8_WAIT_V(8); PG8_WAIT_L(0); PG8_BAR; PG8_MMA(1, 0, At, B0); PG8_MMA(1, 1, At, B1); PG8_BAR; PG8_SCHED;
.LBB0_1611:
	s_ashr_i32 s23, s22, 31
	s_lshl_b64 s[36:37], s[22:23], 20
	s_add_u32 s36, s3, s36
	s_addc_u32 s37, s33, s37
	s_and_b64 s[38:39], s[4:5], exec
	s_cselect_b32 s23, s37, s43
	s_cselect_b32 s41, s36, s42
	s_ashr_i32 s19, s18, 31
	s_lshl_b64 s[38:39], s[18:19], 20
	s_add_u32 s38, s48, s38
	s_addc_u32 s39, s49, s39
	s_and_b64 s[46:47], s[4:5], exec
	s_cselect_b32 s19, s39, s45
	s_cselect_b32 s66, s38, s44
	s_add_u32 s42, s42, 0x80080
	s_addc_u32 s43, s43, 0
	s_add_u32 s67, s44, 0x100
	s_addc_u32 s68, s45, 0
	s_mov_b32 s69, -2
	s_waitcnt lgkmcnt(0)
	ds_read_b128 v[146:149], v153
	ds_read_b128 v[158:161], v153 offset:1024
	ds_read_b128 v[162:165], v153 offset:2048
	ds_read_b128 v[166:169], v153 offset:3072
	ds_read_b128 v[170:173], v154
	ds_read_b128 v[174:177], v154 offset:1024
	ds_read_b128 v[178:181], v154 offset:2048
	ds_read_b128 v[182:185], v154 offset:3072
	s_add_u32 s44, s42, 0xfff80080
	s_addc_u32 s45, s43, -1
	s_cmp_eq_u32 s69, 28
	s_cselect_b32 s47, s23, s45
	s_cselect_b32 s46, s41, s44
	s_cselect_b32 s45, s19, s68
	s_cselect_b32 s44, s66, s67
	v_lshl_add_u64 v[218:219], s[42:43], 0, v[136:137]
	s_add_i32 m0, s51, 0xc000
	ds_read_b128 v[186:189], v155
	ds_read_b128 v[190:193], v155 offset:1024
	ds_read_b128 v[194:197], v155 offset:2048
	ds_read_b128 v[198:201], v155 offset:3072
	ds_read_b128 v[202:205], v155 offset:4096
	ds_read_b128 v[206:209], v155 offset:5120
	ds_read_b128 v[210:213], v155 offset:6144
	ds_read_b128 v[214:217], v155 offset:7168
	global_load_lds_dwordx4 v[218:219], off
	v_lshl_add_u64 v[218:219], s[42:43], 0, v[138:139]
	s_add_i32 m0, s51, 0xe000
	s_nop 0
	global_load_lds_dwordx4 v[218:219], off
	s_waitcnt vmcnt(8)
	s_waitcnt lgkmcnt(0)
	s_barrier
	s_setprio 1
	v_mfma_f32_16x16x32_bf16 v[124:127], v[146:149], v[186:189], 0
	v_mfma_f32_16x16x32_bf16 v[120:123], v[162:165], v[186:189], 0
	v_mfma_f32_16x16x32_bf16 v[108:111], v[146:149], v[194:197], 0
	v_mfma_f32_16x16x32_bf16 v[104:107], v[162:165], v[194:197], 0
	v_mfma_f32_16x16x32_bf16 v[92:95], v[146:149], v[202:205], 0
	v_mfma_f32_16x16x32_bf16 v[88:91], v[162:165], v[202:205], 0
	v_mfma_f32_16x16x32_bf16 v[76:79], v[146:149], v[210:213], 0
	v_mfma_f32_16x16x32_bf16 v[72:75], v[162:165], v[210:213], 0
	v_mfma_f32_16x16x32_bf16 v[124:127], v[158:161], v[190:193], v[124:127]
	v_mfma_f32_16x16x32_bf16 v[120:123], v[166:169], v[190:193], v[120:123]
	v_mfma_f32_16x16x32_bf16 v[108:111], v[158:161], v[198:201], v[108:111]
	v_mfma_f32_16x16x32_bf16 v[104:107], v[166:169], v[198:201], v[104:107]
	v_mfma_f32_16x16x32_bf16 v[92:95], v[158:161], v[206:209], v[92:95]
	v_mfma_f32_16x16x32_bf16 v[88:91], v[166:169], v[206:209], v[88:91]
	v_mfma_f32_16x16x32_bf16 v[76:79], v[158:161], v[214:217], v[76:79]
	v_mfma_f32_16x16x32_bf16 v[72:75], v[166:169], v[214:217], v[72:75]
	s_setprio 0
	s_setprio 1
	v_mfma_f32_16x16x32_bf16 v[116:119], v[170:173], v[186:189], 0
	v_mfma_f32_16x16x32_bf16 v[112:115], v[178:181], v[186:189], 0
	v_mfma_f32_16x16x32_bf16 v[100:103], v[170:173], v[194:197], 0
	v_mfma_f32_16x16x32_bf16 v[96:99], v[178:181], v[194:197], 0
	v_mfma_f32_16x16x32_bf16 v[84:87], v[170:173], v[202:205], 0
	v_mfma_f32_16x16x32_bf16 v[80:83], v[178:181], v[202:205], 0
	v_mfma_f32_16x16x32_bf16 v[68:71], v[170:173], v[210:213], 0
	v_mfma_f32_16x16x32_bf16 v[64:67], v[178:181], v[210:213], 0
	v_mfma_f32_16x16x32_bf16 v[116:119], v[174:177], v[190:193], v[116:119]
	v_mfma_f32_16x16x32_bf16 v[112:115], v[182:185], v[190:193], v[112:115]
	v_mfma_f32_16x16x32_bf16 v[100:103], v[174:177], v[198:201], v[100:103]
	v_mfma_f32_16x16x32_bf16 v[96:99], v[182:185], v[198:201], v[96:99]
	v_mfma_f32_16x16x32_bf16 v[84:87], v[174:177], v[206:209], v[84:87]
	v_mfma_f32_16x16x32_bf16 v[80:83], v[182:185], v[206:209], v[80:83]
	v_mfma_f32_16x16x32_bf16 v[68:71], v[174:177], v[214:217], v[68:71]
	v_mfma_f32_16x16x32_bf16 v[64:67], v[182:185], v[214:217], v[64:67]
	s_setprio 0
	s_barrier
	s_add_i32 s70, s63, s50
	v_lshl_add_u64 v[218:219], s[44:45], 0, v[130:131]
	s_mov_b32 m0, s70
	ds_read_b128 v[186:189], v155 offset:16384
	ds_read_b128 v[190:193], v155 offset:17408
	ds_read_b128 v[194:197], v155 offset:18432
	ds_read_b128 v[198:201], v155 offset:19456
	ds_read_b128 v[202:205], v155 offset:20480
	ds_read_b128 v[206:209], v155 offset:21504
	ds_read_b128 v[210:213], v155 offset:22528
	ds_read_b128 v[214:217], v155 offset:23552
	global_load_lds_dwordx4 v[218:219], off
	s_add_i32 m0, s70, 0x2000
	s_add_u32 s70, s44, 0x80000
	v_lshl_add_u64 v[220:221], s[44:45], 0, v[134:135]
	s_addc_u32 s71, s45, 0
	s_add_i32 s72, s64, s50
	global_load_lds_dwordx4 v[220:221], off
	v_lshl_add_u64 v[222:223], s[70:71], 0, v[130:131]
	s_mov_b32 m0, s72
	v_lshl_add_u64 v[224:225], s[46:47], 0, v[132:133]
	global_load_lds_dwordx4 v[222:223], off
	v_lshl_add_u64 v[222:223], s[70:71], 0, v[134:135]
	s_add_i32 m0, s72, 0x2000
	s_nop 0
	global_load_lds_dwordx4 v[222:223], off
	v_lshl_add_u64 v[222:223], s[46:47], 0, v[128:129]
	s_mov_b32 m0, s51
	s_nop 0
	global_load_lds_dwordx4 v[222:223], off
	s_mov_b32 m0, s52
	s_nop 0
	global_load_lds_dwordx4 v[224:225], off
	s_waitcnt vmcnt(8)
	s_waitcnt lgkmcnt(0)
	s_barrier
; #define PG8_STAGE(bufoff, gbase, voff) do { _Pragma("unroll") for (int _i = 0; _i < 2; ++_i) \
;         __builtin_amdgcn_global_load_lds((const unsigned*)((const char*)(gbase) + (voff)[_i]), (PG8_LAS unsigned*)(lds + (bufoff) + ldsw + _i * 8192), 16, 0, 0); } while (0)
; #define PG8_LDA(dst, b, h) do { _Pragma("unroll") for (int m = 0; m < 4; ++m) _Pragma("unroll") for (int k = 0; k < 2; ++k) dst[m][k] = *(const PG8_LAS bf16x8*)(lds + PG8_SA(b, h) + aoff + m * 2048 + k * 1024); } while (0)
; #define PG8_LDB(dst, b, h) do { _Pragma("unroll") for (int n = 0; n < 2; ++n) _Pragma("unroll") for (int k = 0; k < 2; ++k) dst[n][k] = *(const PG8_LAS bf16x8*)(lds + PG8_SB(b, h) + boff + n * 2048 + k * 1024); } while (0)
; #define PG8_MMA(ai, bj, At, Bt) do { __builtin_amdgcn_s_setprio(1); _Pragma("unroll") for (int m = 0; m < 4; ++m) _Pragma("unroll") for (int n = 0; n < 2; ++n) _Pragma("unroll") for (int k = 0; k < 2; ++k) \
;         acc[ai][bj][m][n] = __builtin_amdgcn_mfma_f32_16x16x32_bf16(Bt[n][k], At[m][k], acc[ai][bj][m][n], 0, 0, 0); __builtin_amdgcn_s_setprio(0); } while (0)
; #define PG8_WAIT_V(n) asm volatile("s_waitcnt vmcnt(" #n ")" ::: "memory")
; #define PG8_WAIT_L(n) asm volatile("s_waitcnt lgkmcnt(" #n ")" ::: "memory")
; #define PG8_BAR __builtin_amdgcn_s_barrier()
; #define PG8_SCHED __builtin_amdgcn_sched_barrier(0)
; template <class Epi, class Sched, bool ALIGN_EPI = false, bool SP2 = false>
; __device__ __forceinline__ void gemm_phase(PG8_LAS unsigned char* lds, const Gemm g, const Sched& S, const Epi& E) {
;     ...
;             PG8_WAIT_V(8); PG8_WAIT_L(0); PG8_BAR; PG8_MMA(1, 0, At, B0); PG8_MMA(1, 1, At, B1); PG8_BAR; PG8_SCHED;
;             PG8_LDB(B0, 1, 0); PG8_LDB(B1, 1, 1); PG8_SCHED; PG8_LDA(At, 1, 0); PG8_STAGE(PG8_SA(0, 1), a2 + hstep, voffA);
;             PG8_WAIT_V(8); PG8_WAIT_L(0); PG8_BAR; PG8_MMA(0, 0, At, B0); PG8_MMA(0, 1, At, B1); PG8_BAR; PG8_SCHED;
	s_setprio 1
	v_mfma_f32_16x16x32_bf16 v[60:63], v[146:149], v[186:189], 0
	v_mfma_f32_16x16x32_bf16 v[56:59], v[162:165], v[186:189], 0
	v_mfma_f32_16x16x32_bf16 v[44:47], v[146:149], v[194:197], 0
	v_mfma_f32_16x16x32_bf16 v[40:43], v[162:165], v[194:197], 0
	v_mfma_f32_16x16x32_bf16 v[28:31], v[146:149], v[202:205], 0
	v_mfma_f32_16x16x32_bf16 v[24:27], v[162:165], v[202:205], 0
	v_mfma_f32_16x16x32_bf16 v[12:15], v[146:149], v[210:213], 0
	v_mfma_f32_16x16x32_bf16 v[8:11], v[162:165], v[210:213], 0
	v_mfma_f32_16x16x32_bf16 v[60:63], v[158:161], v[190:193], v[60:63]
	v_mfma_f32_16x16x32_bf16 v[56:59], v[166:169], v[190:193], v[56:59]
	v_mfma_f32_16x16x32_bf16 v[44:47], v[158:161], v[198:201], v[44:47]
	v_mfma_f32_16x16x32_bf16 v[40:43], v[166:169], v[198:201], v[40:43]
	v_mfma_f32_16x16x32_bf16 v[28:31], v[158:161], v[206:209], v[28:31]
	v_mfma_f32_16x16x32_bf16 v[24:27], v[166:169], v[206:209], v[24:27]
	v_mfma_f32_16x16x32_bf16 v[12:15], v[158:161], v[214:217], v[12:15]
	v_mfma_f32_16x16x32_bf16 v[8:11], v[166:169], v[214:217], v[8:11]
	s_setprio 0
	s_setprio 1
	v_mfma_f32_16x16x32_bf16 v[52:55], v[170:173], v[186:189], 0
	v_mfma_f32_16x16x32_bf16 v[48:51], v[178:181], v[186:189], 0
	v_mfma_f32_16x16x32_bf16 v[36:39], v[170:173], v[194:197], 0
	v_mfma_f32_16x16x32_bf16 v[32:35], v[178:181], v[194:197], 0
	v_mfma_f32_16x16x32_bf16 v[20:23], v[170:173], v[202:205], 0
	v_mfma_f32_16x16x32_bf16 v[16:19], v[178:181], v[202:205], 0
	v_mfma_f32_16x16x32_bf16 v[4:7], v[170:173], v[210:213], 0
	v_mfma_f32_16x16x32_bf16 v[0:3], v[178:181], v[210:213], 0
	v_mfma_f32_16x16x32_bf16 v[52:55], v[174:177], v[190:193], v[52:55]
	v_mfma_f32_16x16x32_bf16 v[48:51], v[182:185], v[190:193], v[48:51]
	v_mfma_f32_16x16x32_bf16 v[36:39], v[174:177], v[198:201], v[36:39]
	v_mfma_f32_16x16x32_bf16 v[32:35], v[182:185], v[198:201], v[32:35]
	v_mfma_f32_16x16x32_bf16 v[20:23], v[174:177], v[206:209], v[20:23]
	v_mfma_f32_16x16x32_bf16 v[16:19], v[182:185], v[206:209], v[16:19]
	v_mfma_f32_16x16x32_bf16 v[4:7], v[174:177], v[214:217], v[4:7]
	v_mfma_f32_16x16x32_bf16 v[0:3], v[182:185], v[214:217], v[0:3]
	s_setprio 0
	s_barrier
	s_add_i32 s70, 0, 0x18000
	v_add_u32_e32 v157, s70, v152
	s_add_i32 s71, 0, 0x1c000
	ds_read_b128 v[146:149], v157
	ds_read_b128 v[158:161], v157 offset:1024
	ds_read_b128 v[162:165], v157 offset:2048
	ds_read_b128 v[166:169], v157 offset:3072
	v_add_u32_e32 v157, s71, v152
	ds_read_b128 v[170:173], v157
	ds_read_b128 v[174:177], v157 offset:1024
	ds_read_b128 v[178:181], v157 offset:2048
	ds_read_b128 v[182:185], v157 offset:3072
	s_add_u32 s46, s46, 0x80000
	s_addc_u32 s47, s47, 0
	s_mov_b32 m0, s53
	v_lshl_add_u64 v[226:227], s[46:47], 0, v[128:129]
	ds_read_b128 v[186:189], v155 offset:32768
	ds_read_b128 v[190:193], v155 offset:33792
	ds_read_b128 v[194:197], v155 offset:34816
	ds_read_b128 v[198:201], v155 offset:35840
	ds_read_b128 v[202:205], v155 offset:36864
	ds_read_b128 v[206:209], v155 offset:37888
	ds_read_b128 v[210:213], v155 offset:38912
	ds_read_b128 v[214:217], v155 offset:39936
	global_load_lds_dwordx4 v[226:227], off
	v_lshl_add_u64 v[226:227], s[46:47], 0, v[132:133]
	s_mov_b32 m0, s54
	s_nop 0
	global_load_lds_dwordx4 v[226:227], off
	s_waitcnt vmcnt(8)
	s_waitcnt lgkmcnt(0)
	s_barrier
	s_setprio 1
	v_mfma_f32_16x16x32_bf16 v[124:127], v[146:149], v[186:189], v[124:127]
	v_mfma_f32_16x16x32_bf16 v[120:123], v[162:165], v[186:189], v[120:123]
	v_mfma_f32_16x16x32_bf16 v[108:111], v[146:149], v[194:197], v[108:111]
	v_mfma_f32_16x16x32_bf16 v[104:107], v[162:165], v[194:197], v[104:107]
	v_mfma_f32_16x16x32_bf16 v[92:95], v[146:149], v[202:205], v[92:95]
	v_mfma_f32_16x16x32_bf16 v[88:91], v[162:165], v[202:205], v[88:91]
	v_mfma_f32_16x16x32_bf16 v[76:79], v[146:149], v[210:213], v[76:79]
	v_mfma_f32_16x16x32_bf16 v[72:75], v[162:165], v[210:213], v[72:75]
	v_mfma_f32_16x16x32_bf16 v[124:127], v[158:161], v[190:193], v[124:127]
	v_mfma_f32_16x16x32_bf16 v[120:123], v[166:169], v[190:193], v[120:123]
	v_mfma_f32_16x16x32_bf16 v[108:111], v[158:161], v[198:201], v[108:111]
	v_mfma_f32_16x16x32_bf16 v[104:107], v[166:169], v[198:201], v[104:107]
	v_mfma_f32_16x16x32_bf16 v[92:95], v[158:161], v[206:209], v[92:95]
	v_mfma_f32_16x16x32_bf16 v[88:91], v[166:169], v[206:209], v[88:91]
	v_mfma_f32_16x16x32_bf16 v[76:79], v[158:161], v[214:217], v[76:79]
	v_mfma_f32_16x16x32_bf16 v[72:75], v[166:169], v[214:217], v[72:75]
	s_setprio 0
	s_setprio 1
	v_mfma_f32_16x16x32_bf16 v[116:119], v[170:173], v[186:189], v[116:119]
	v_mfma_f32_16x16x32_bf16 v[112:115], v[178:181], v[186:189], v[112:115]
	v_mfma_f32_16x16x32_bf16 v[100:103], v[170:173], v[194:197], v[100:103]
	v_mfma_f32_16x16x32_bf16 v[96:99], v[178:181], v[194:197], v[96:99]
	v_mfma_f32_16x16x32_bf16 v[84:87], v[170:173], v[202:205], v[84:87]
	v_mfma_f32_16x16x32_bf16 v[80:83], v[178:181], v[202:205], v[80:83]
	v_mfma_f32_16x16x32_bf16 v[68:71], v[170:173], v[210:213], v[68:71]
	v_mfma_f32_16x16x32_bf16 v[64:67], v[178:181], v[210:213], v[64:67]
	v_mfma_f32_16x16x32_bf16 v[116:119], v[174:177], v[190:193], v[116:119]
	v_mfma_f32_16x16x32_bf16 v[112:115], v[182:185], v[190:193], v[112:115]
	v_mfma_f32_16x16x32_bf16 v[100:103], v[174:177], v[198:201], v[100:103]
	v_mfma_f32_16x16x32_bf16 v[96:99], v[182:185], v[198:201], v[96:99]
	v_mfma_f32_16x16x32_bf16 v[84:87], v[174:177], v[206:209], v[84:87]
	v_mfma_f32_16x16x32_bf16 v[80:83], v[182:185], v[206:209], v[80:83]
	v_mfma_f32_16x16x32_bf16 v[68:71], v[174:177], v[214:217], v[68:71]
	v_mfma_f32_16x16x32_bf16 v[64:67], v[182:185], v[214:217], v[64:67]
	s_setprio 0
	s_barrier
; #define PG8_STAGE(bufoff, gbase, voff) do { _Pragma("unroll") for (int _i = 0; _i < 2; ++_i) \
;         __builtin_amdgcn_global_load_lds((const unsigned*)((const char*)(gbase) + (voff)[_i]), (PG8_LAS unsigned*)(lds + (bufoff) + ldsw + _i * 8192), 16, 0, 0); } while (0)
; #define PG8_LDA(dst, b, h) do { _Pragma("unroll") for (int m = 0; m < 4; ++m) _Pragma("unroll") for (int k = 0; k < 2; ++k) dst[m][k] = *(const PG8_LAS bf16x8*)(lds + PG8_SA(b, h) + aoff + m * 2048 + k * 1024); } while (0)
; #define PG8_MMA(ai, bj, At, Bt) do { __builtin_amdgcn_s_setprio(1); _Pragma("unroll") for (int m = 0; m < 4; ++m) _Pragma("unroll") for (int n = 0; n < 2; ++n) _Pragma("unroll") for (int k = 0; k < 2; ++k) \
;         acc[ai][bj][m][n] = __builtin_amdgcn_mfma_f32_16x16x32_bf16(Bt[n][k], At[m][k], acc[ai][bj][m][n], 0, 0, 0); __builtin_amdgcn_s_setprio(0); } while (0)
; #define PG8_WAIT_V(n) asm volatile("s_waitcnt vmcnt(" #n ")" ::: "memory")
; #define PG8_WAIT_L(n) asm volatile("s_waitcnt lgkmcnt(" #n ")" ::: "memory")
; #define PG8_BAR __builtin_amdgcn_s_barrier()
; #define PG8_SCHED __builtin_amdgcn_sched_barrier(0)
; template <class Epi, class Sched, bool ALIGN_EPI = false, bool SP2 = false>
; __device__ __forceinline__ void gemm_phase(PG8_LAS unsigned char* lds, const Gemm g, const Sched& S, const Epi& E) {
;     ...
;         for (int t = 0; t < nt; t += 2) {
;     ...
;             PG8_LDA(At, 1, 1); PG8_STAGE(PG8_SB(1, 0), b3, voffB); PG8_STAGE(PG8_SB(1, 1), b3 + hstep, voffB); PG8_STAGE(PG8_SA(1, 0), a3, voffA);
;             PG8_WAIT_V(8); PG8_WAIT_L(0); PG8_BAR; PG8_MMA(1, 0, At, B0); PG8_MMA(1, 1, At, B1); PG8_BAR; PG8_SCHED;
	s_add_i32 s46, s70, s50
	v_lshl_add_u64 v[218:219], v[218:219], 0, s[14:15]
	s_mov_b32 m0, s46
	ds_read_b128 v[186:189], v155 offset:49152
	ds_read_b128 v[190:193], v155 offset:50176
	ds_read_b128 v[194:197], v155 offset:51200
	ds_read_b128 v[198:201], v155 offset:52224
	ds_read_b128 v[202:205], v155 offset:53248
	ds_read_b128 v[206:209], v155 offset:54272
	ds_read_b128 v[210:213], v155 offset:55296
	ds_read_b128 v[214:217], v155 offset:56320
	global_load_lds_dwordx4 v[218:219], off
	s_add_i32 m0, s46, 0x2000
	s_add_u32 s44, s44, 0x80080
	v_lshl_add_u64 v[218:219], v[220:221], 0, s[14:15]
	s_addc_u32 s45, s45, 0
	s_add_i32 s46, s71, s50
	global_load_lds_dwordx4 v[218:219], off
	v_lshl_add_u64 v[218:219], s[44:45], 0, v[130:131]
	s_mov_b32 m0, s46
	s_nop 0
	global_load_lds_dwordx4 v[218:219], off
	v_lshl_add_u64 v[218:219], s[44:45], 0, v[134:135]
	s_add_i32 m0, s46, 0x2000
	s_nop 0
	global_load_lds_dwordx4 v[218:219], off
	v_lshl_add_u64 v[218:219], v[222:223], 0, s[14:15]
	s_mov_b32 m0, s60
	s_nop 0
	global_load_lds_dwordx4 v[218:219], off
	v_lshl_add_u64 v[218:219], v[224:225], 0, s[14:15]
	s_mov_b32 m0, s61
	s_nop 0
	global_load_lds_dwordx4 v[218:219], off
	s_waitcnt vmcnt(8)
	s_waitcnt lgkmcnt(0)
	s_barrier
	s_setprio 1
	v_mfma_f32_16x16x32_bf16 v[60:63], v[146:149], v[186:189], v[60:63]
	v_mfma_f32_16x16x32_bf16 v[56:59], v[162:165], v[186:189], v[56:59]
	v_mfma_f32_16x16x32_bf16 v[44:47], v[146:149], v[194:197], v[44:47]
	v_mfma_f32_16x16x32_bf16 v[40:43], v[162:165], v[194:197], v[40:43]
	v_mfma_f32_16x16x32_bf16 v[28:31], v[146:149], v[202:205], v[28:31]
	v_mfma_f32_16x16x32_bf16 v[24:27], v[162:165], v[202:205], v[24:27]
	v_mfma_f32_16x16x32_bf16 v[12:15], v[146:149], v[210:213], v[12:15]
	v_mfma_f32_16x16x32_bf16 v[8:11], v[162:165], v[210:213], v[8:11]
	v_mfma_f32_16x16x32_bf16 v[60:63], v[158:161], v[190:193], v[60:63]
	v_mfma_f32_16x16x32_bf16 v[56:59], v[166:169], v[190:193], v[56:59]
	v_mfma_f32_16x16x32_bf16 v[44:47], v[158:161], v[198:201], v[44:47]
	v_mfma_f32_16x16x32_bf16 v[40:43], v[166:169], v[198:201], v[40:43]
	v_mfma_f32_16x16x32_bf16 v[28:31], v[158:161], v[206:209], v[28:31]
	v_mfma_f32_16x16x32_bf16 v[24:27], v[166:169], v[206:209], v[24:27]
	v_mfma_f32_16x16x32_bf16 v[12:15], v[158:161], v[214:217], v[12:15]
	v_mfma_f32_16x16x32_bf16 v[8:11], v[166:169], v[214:217], v[8:11]
	s_setprio 0
	s_setprio 1
	v_mfma_f32_16x16x32_bf16 v[52:55], v[170:173], v[186:189], v[52:55]
	v_mfma_f32_16x16x32_bf16 v[48:51], v[178:181], v[186:189], v[48:51]
	v_mfma_f32_16x16x32_bf16 v[36:39], v[170:173], v[194:197], v[36:39]
	v_mfma_f32_16x16x32_bf16 v[32:35], v[178:181], v[194:197], v[32:35]
	v_mfma_f32_16x16x32_bf16 v[20:23], v[170:173], v[202:205], v[20:23]
	v_mfma_f32_16x16x32_bf16 v[16:19], v[178:181], v[202:205], v[16:19]
	v_mfma_f32_16x16x32_bf16 v[4:7], v[170:173], v[210:213], v[4:7]
	v_mfma_f32_16x16x32_bf16 v[0:3], v[178:181], v[210:213], v[0:3]
	v_mfma_f32_16x16x32_bf16 v[52:55], v[174:177], v[190:193], v[52:55]
	v_mfma_f32_16x16x32_bf16 v[48:51], v[182:185], v[190:193], v[48:51]
	v_mfma_f32_16x16x32_bf16 v[36:39], v[174:177], v[198:201], v[36:39]
	v_mfma_f32_16x16x32_bf16 v[32:35], v[182:185], v[198:201], v[32:35]
	v_mfma_f32_16x16x32_bf16 v[20:23], v[174:177], v[206:209], v[20:23]
	v_mfma_f32_16x16x32_bf16 v[16:19], v[182:185], v[206:209], v[16:19]
	v_mfma_f32_16x16x32_bf16 v[4:7], v[174:177], v[214:217], v[4:7]
	v_mfma_f32_16x16x32_bf16 v[0:3], v[182:185], v[214:217], v[0:3]
	s_setprio 0
	s_barrier
	s_add_i32 s69, s69, 2
	s_add_u32 s42, s42, 0x100
	s_addc_u32 s43, s43, 0
	s_add_u32 s67, s67, 0x100
	s_addc_u32 s68, s68, 0
	s_cmp_gt_u32 s69, 29

; #define PG8_STAGE(bufoff, gbase, voff) do { _Pragma("unroll") for (int _i = 0; _i < 2; ++_i) \
;         __builtin_amdgcn_global_load_lds((const unsigned*)((const char*)(gbase) + (voff)[_i]), (PG8_LAS unsigned*)(lds + (bufoff) + ldsw + _i * 8192), 16, 0, 0); } while (0)
; #define PG8_LDA(dst, b, h) do { _Pragma("unroll") for (int m = 0; m < 4; ++m) _Pragma("unroll") for (int k = 0; k < 2; ++k) dst[m][k] = *(const PG8_LAS bf16x8*)(lds + PG8_SA(b, h) + aoff + m * 2048 + k * 1024); } while (0)
; #define PG8_LDB(dst, b, h) do { _Pragma("unroll") for (int n = 0; n < 2; ++n) _Pragma("unroll") for (int k = 0; k < 2; ++k) dst[n][k] = *(const PG8_LAS bf16x8*)(lds + PG8_SB(b, h) + boff + n * 2048 + k * 1024); } while (0)
; #define PG8_WAIT_V(n) asm volatile("s_waitcnt vmcnt(" #n ")" ::: "memory")
; #define PG8_WAIT_L(n) asm volatile("s_waitcnt lgkmcnt(" #n ")" ::: "memory")
; #define PG8_BAR __builtin_amdgcn_s_barrier()
; #define PG8_SCHED __builtin_amdgcn_sched_barrier(0)
; template <class Epi, class Sched, bool ALIGN_EPI = false, bool SP2 = false>
; __device__ __forceinline__ void gemm_phase(PG8_LAS unsigned char* lds, const Gemm g, const Sched& S, const Epi& E) {
;     ...
;         const bool has_next = S.next(ui + 1, nxt);
;         const char* nA = has_next ? (const char*)g.A + (size_t)nxt.pm * tstep : cA; const char* nB = has_next ? (const char*)g.Bt + (size_t)nxt.pn * tstep : cB;
;         for (int t = 0; t < nt; t += 2) {
;             const bool last = (t == nt - 2);
;             const char* a1 = cA + (size_t)(t + 1) * kstep;
;             const char* a2 = last ? nA : cA + (size_t)(t + 2) * kstep; const char* b2 = last ? nB : cB + (size_t)(t + 2) * kstep;
;             const char* a3 = a2 + kstep; const char* b3 = b2 + kstep;
;             if (last && has_next) S.a_ready(nxt);
;             if constexpr (SP2) {
;             PG8_LDB(B0, 0, 0); PG8_LDB(B1, 0, 1); PG8_SCHED; PG8_LDA(At, 0, 0); PG8_STAGE(PG8_SA(1, 1), a1 + hstep, voffA);
;             PG8_WAIT_V(8); PG8_WAIT_L(0); PG8_BAR; PG8_MMA(0, 0, At, B0); PG8_MMA(0, 1, At, B1); PG8_BAR; PG8_SCHED;
;             PG8_LDA(At, 0, 1); PG8_STAGE(PG8_SB(0, 0), b2, voffB); PG8_STAGE(PG8_SB(0, 1), b2 + hstep, voffB); PG8_STAGE(PG8_SA(0, 0), a2, voffA);
;             PG8_WAIT_V(8); PG8_WAIT_L(0); PG8_BAR; PG8_MMA(1, 0, At, B0); PG8_MMA(1, 1, At, B1); PG8_BAR; PG8_SCHED;
.LBB0_1700:
	s_ashr_i32 s49, s48, 31
	s_lshl_b64 s[10:11], s[48:49], 20
	v_readlane_b32 s0, v244, 38
	s_add_u32 s40, s0, s10
	v_readlane_b32 s0, v244, 22
	s_addc_u32 s41, s0, s11
	s_and_b64 s[10:11], s[4:5], exec
	s_cselect_b32 s7, s41, s75
	s_cselect_b32 s12, s40, s74
	s_ashr_i32 s35, s34, 31
	s_lshl_b64 s[10:11], s[34:35], 20
	s_add_u32 s2, s92, s10
	s_addc_u32 s3, s51, s11
	s_and_b64 s[10:11], s[4:5], exec
	s_cselect_b32 s13, s3, s77
	s_cselect_b32 s16, s2, s76
	s_add_u32 s0, s74, 0x80080
	s_addc_u32 s1, s75, 0
	s_add_u32 s37, s76, 0x100
	s_addc_u32 s71, s77, 0
	s_mov_b32 s73, -2
	ds_read_b128 v[128:131], v220
	ds_read_b128 v[132:135], v220 offset:1024
	ds_read_b128 v[136:139], v220 offset:2048
	ds_read_b128 v[140:143], v220 offset:3072
	ds_read_b128 v[164:167], v221
	ds_read_b128 v[168:171], v221 offset:1024
	ds_read_b128 v[172:175], v221 offset:2048
	ds_read_b128 v[176:179], v221 offset:3072
	s_add_u32 s8, s0, 0xfff80080
	s_addc_u32 s9, s1, -1
	s_cmp_eq_u32 s73, 28
	s_cselect_b32 s11, s7, s9
	s_cselect_b32 s10, s12, s8
	s_cselect_b32 s9, s13, s71
	s_cselect_b32 s8, s16, s37
	v_lshl_add_u64 v[212:213], s[0:1], 0, v[156:157]
	s_add_i32 m0, s61, 0xc000
	ds_read_b128 v[180:183], v222
	ds_read_b128 v[184:187], v222 offset:1024
	ds_read_b128 v[188:191], v222 offset:2048
	ds_read_b128 v[192:195], v222 offset:3072
	ds_read_b128 v[196:199], v222 offset:4096
	ds_read_b128 v[200:203], v222 offset:5120
	ds_read_b128 v[204:207], v222 offset:6144
	ds_read_b128 v[208:211], v222 offset:7168
	global_load_lds_dwordx4 v[212:213], off
	v_lshl_add_u64 v[212:213], s[0:1], 0, v[158:159]
	s_add_i32 m0, s61, 0xe000
	s_nop 0
	global_load_lds_dwordx4 v[212:213], off
	s_waitcnt vmcnt(8)
	s_waitcnt lgkmcnt(0)
	s_barrier
	s_setprio 1
	v_mfma_f32_16x16x32_bf16 v[124:127], v[128:131], v[180:183], 0
	v_mfma_f32_16x16x32_bf16 v[116:119], v[136:139], v[180:183], 0
	v_mfma_f32_16x16x32_bf16 v[120:123], v[128:131], v[188:191], 0
	v_mfma_f32_16x16x32_bf16 v[112:115], v[136:139], v[188:191], 0
	v_mfma_f32_16x16x32_bf16 v[104:107], v[128:131], v[196:199], 0
	v_mfma_f32_16x16x32_bf16 v[108:111], v[136:139], v[196:199], 0
	v_mfma_f32_16x16x32_bf16 v[80:83], v[128:131], v[204:207], 0
	v_mfma_f32_16x16x32_bf16 v[92:95], v[136:139], v[204:207], 0
	v_mfma_f32_16x16x32_bf16 v[124:127], v[132:135], v[184:187], v[124:127]
	v_mfma_f32_16x16x32_bf16 v[116:119], v[140:143], v[184:187], v[116:119]
	v_mfma_f32_16x16x32_bf16 v[120:123], v[132:135], v[192:195], v[120:123]
	v_mfma_f32_16x16x32_bf16 v[112:115], v[140:143], v[192:195], v[112:115]
	v_mfma_f32_16x16x32_bf16 v[104:107], v[132:135], v[200:203], v[104:107]
	v_mfma_f32_16x16x32_bf16 v[108:111], v[140:143], v[200:203], v[108:111]
	v_mfma_f32_16x16x32_bf16 v[80:83], v[132:135], v[208:211], v[80:83]
	v_mfma_f32_16x16x32_bf16 v[92:95], v[140:143], v[208:211], v[92:95]
	s_setprio 0
	s_setprio 1
	v_mfma_f32_16x16x32_bf16 v[100:103], v[164:167], v[180:183], 0
	v_mfma_f32_16x16x32_bf16 v[76:79], v[172:175], v[180:183], 0
	v_mfma_f32_16x16x32_bf16 v[96:99], v[164:167], v[188:191], 0
	v_mfma_f32_16x16x32_bf16 v[72:75], v[172:175], v[188:191], 0
	v_mfma_f32_16x16x32_bf16 v[88:91], v[164:167], v[196:199], 0
	v_mfma_f32_16x16x32_bf16 v[68:71], v[172:175], v[196:199], 0
	v_mfma_f32_16x16x32_bf16 v[84:87], v[164:167], v[204:207], 0
	v_mfma_f32_16x16x32_bf16 v[64:67], v[172:175], v[204:207], 0
	v_mfma_f32_16x16x32_bf16 v[100:103], v[168:171], v[184:187], v[100:103]
	v_mfma_f32_16x16x32_bf16 v[76:79], v[176:179], v[184:187], v[76:79]
	v_mfma_f32_16x16x32_bf16 v[96:99], v[168:171], v[192:195], v[96:99]
	v_mfma_f32_16x16x32_bf16 v[72:75], v[176:179], v[192:195], v[72:75]
	v_mfma_f32_16x16x32_bf16 v[88:91], v[168:171], v[200:203], v[88:91]
	v_mfma_f32_16x16x32_bf16 v[68:71], v[176:179], v[200:203], v[68:71]
	v_mfma_f32_16x16x32_bf16 v[84:87], v[168:171], v[208:211], v[84:87]
	v_mfma_f32_16x16x32_bf16 v[64:67], v[176:179], v[208:211], v[64:67]
	s_setprio 0
	s_barrier
	s_add_i32 s79, s15, s59
	v_lshl_add_u64 v[212:213], s[8:9], 0, v[148:149]
	s_mov_b32 m0, s79
	ds_read_b128 v[180:183], v222 offset:16384
	ds_read_b128 v[184:187], v222 offset:17408
	ds_read_b128 v[188:191], v222 offset:18432
	ds_read_b128 v[192:195], v222 offset:19456
	ds_read_b128 v[196:199], v222 offset:20480
	ds_read_b128 v[200:203], v222 offset:21504
	ds_read_b128 v[204:207], v222 offset:22528
	ds_read_b128 v[208:211], v222 offset:23552
	global_load_lds_dwordx4 v[212:213], off
	s_add_i32 m0, s79, 0x2000
	s_add_u32 vcc_lo, s8, 0x80000
	v_lshl_add_u64 v[214:215], s[8:9], 0, v[152:153]
	s_addc_u32 vcc_hi, s9, 0
	s_add_i32 s79, s87, s59
	global_load_lds_dwordx4 v[214:215], off
	v_lshl_add_u64 v[226:227], vcc, 0, v[148:149]
	s_mov_b32 m0, s79
	v_lshl_add_u64 v[228:229], s[10:11], 0, v[150:151]
	global_load_lds_dwordx4 v[226:227], off
	v_lshl_add_u64 v[226:227], vcc, 0, v[152:153]
	s_add_i32 m0, s79, 0x2000
	s_nop 0
	global_load_lds_dwordx4 v[226:227], off
	v_lshl_add_u64 v[226:227], s[10:11], 0, v[146:147]
	s_mov_b32 m0, s61
	s_nop 0
	global_load_lds_dwordx4 v[226:227], off
	s_mov_b32 m0, s63
	s_nop 0
	global_load_lds_dwordx4 v[228:229], off
	s_waitcnt vmcnt(8)
	s_waitcnt lgkmcnt(0)
	s_barrier
; #define PG8_STAGE(bufoff, gbase, voff) do { _Pragma("unroll") for (int _i = 0; _i < 2; ++_i) \
;         __builtin_amdgcn_global_load_lds((const unsigned*)((const char*)(gbase) + (voff)[_i]), (PG8_LAS unsigned*)(lds + (bufoff) + ldsw + _i * 8192), 16, 0, 0); } while (0)
; #define PG8_LDA(dst, b, h) do { _Pragma("unroll") for (int m = 0; m < 4; ++m) _Pragma("unroll") for (int k = 0; k < 2; ++k) dst[m][k] = *(const PG8_LAS bf16x8*)(lds + PG8_SA(b, h) + aoff + m * 2048 + k * 1024); } while (0)
; #define PG8_LDB(dst, b, h) do { _Pragma("unroll") for (int n = 0; n < 2; ++n) _Pragma("unroll") for (int k = 0; k < 2; ++k) dst[n][k] = *(const PG8_LAS bf16x8*)(lds + PG8_SB(b, h) + boff + n * 2048 + k * 1024); } while (0)
; #define PG8_MMA(ai, bj, At, Bt) do { __builtin_amdgcn_s_setprio(1); _Pragma("unroll") for (int m = 0; m < 4; ++m) _Pragma("unroll") for (int n = 0; n < 2; ++n) _Pragma("unroll") for (int k = 0; k < 2; ++k) \
;         acc[ai][bj][m][n] = __builtin_amdgcn_mfma_f32_16x16x32_bf16(Bt[n][k], At[m][k], acc[ai][bj][m][n], 0, 0, 0); __builtin_amdgcn_s_setprio(0); } while (0)
; #define PG8_WAIT_V(n) asm volatile("s_waitcnt vmcnt(" #n ")" ::: "memory")
; #define PG8_WAIT_L(n) asm volatile("s_waitcnt lgkmcnt(" #n ")" ::: "memory")
; #define PG8_BAR __builtin_amdgcn_s_barrier()
; #define PG8_SCHED __builtin_amdgcn_sched_barrier(0)
; template <class Epi, class Sched, bool ALIGN_EPI = false, bool SP2 = false>
; __device__ __forceinline__ void gemm_phase(PG8_LAS unsigned char* lds, const Gemm g, const Sched& S, const Epi& E) {
;     ...
;             PG8_WAIT_V(8); PG8_WAIT_L(0); PG8_BAR; PG8_MMA(1, 0, At, B0); PG8_MMA(1, 1, At, B1); PG8_BAR; PG8_SCHED;
;             PG8_LDB(B0, 1, 0); PG8_LDB(B1, 1, 1); PG8_SCHED; PG8_LDA(At, 1, 0); PG8_STAGE(PG8_SA(0, 1), a2 + hstep, voffA);
;             PG8_WAIT_V(8); PG8_WAIT_L(0); PG8_BAR; PG8_MMA(0, 0, At, B0); PG8_MMA(0, 1, At, B1); PG8_BAR; PG8_SCHED;
	s_setprio 1
	v_mfma_f32_16x16x32_bf16 v[60:63], v[128:131], v[180:183], 0
	v_mfma_f32_16x16x32_bf16 v[44:47], v[136:139], v[180:183], 0
	v_mfma_f32_16x16x32_bf16 v[56:59], v[128:131], v[188:191], 0
	v_mfma_f32_16x16x32_bf16 v[40:43], v[136:139], v[188:191], 0
	v_mfma_f32_16x16x32_bf16 v[52:55], v[128:131], v[196:199], 0
	v_mfma_f32_16x16x32_bf16 v[36:39], v[136:139], v[196:199], 0
	v_mfma_f32_16x16x32_bf16 v[48:51], v[128:131], v[204:207], 0
	v_mfma_f32_16x16x32_bf16 v[32:35], v[136:139], v[204:207], 0
	v_mfma_f32_16x16x32_bf16 v[60:63], v[132:135], v[184:187], v[60:63]
	v_mfma_f32_16x16x32_bf16 v[44:47], v[140:143], v[184:187], v[44:47]
	v_mfma_f32_16x16x32_bf16 v[56:59], v[132:135], v[192:195], v[56:59]
	v_mfma_f32_16x16x32_bf16 v[40:43], v[140:143], v[192:195], v[40:43]
	v_mfma_f32_16x16x32_bf16 v[52:55], v[132:135], v[200:203], v[52:55]
	v_mfma_f32_16x16x32_bf16 v[36:39], v[140:143], v[200:203], v[36:39]
	v_mfma_f32_16x16x32_bf16 v[48:51], v[132:135], v[208:211], v[48:51]
	v_mfma_f32_16x16x32_bf16 v[32:35], v[140:143], v[208:211], v[32:35]
	s_setprio 0
	s_setprio 1
	v_mfma_f32_16x16x32_bf16 v[28:31], v[164:167], v[180:183], 0
	v_mfma_f32_16x16x32_bf16 v[12:15], v[172:175], v[180:183], 0
	v_mfma_f32_16x16x32_bf16 v[24:27], v[164:167], v[188:191], 0
	v_mfma_f32_16x16x32_bf16 v[8:11], v[172:175], v[188:191], 0
	v_mfma_f32_16x16x32_bf16 v[20:23], v[164:167], v[196:199], 0
	v_mfma_f32_16x16x32_bf16 v[4:7], v[172:175], v[196:199], 0
	v_mfma_f32_16x16x32_bf16 v[16:19], v[164:167], v[204:207], 0
	v_mfma_f32_16x16x32_bf16 v[0:3], v[172:175], v[204:207], 0
	v_mfma_f32_16x16x32_bf16 v[28:31], v[168:171], v[184:187], v[28:31]
	v_mfma_f32_16x16x32_bf16 v[12:15], v[176:179], v[184:187], v[12:15]
	v_mfma_f32_16x16x32_bf16 v[24:27], v[168:171], v[192:195], v[24:27]
	v_mfma_f32_16x16x32_bf16 v[8:11], v[176:179], v[192:195], v[8:11]
	v_mfma_f32_16x16x32_bf16 v[20:23], v[168:171], v[200:203], v[20:23]
	v_mfma_f32_16x16x32_bf16 v[4:7], v[176:179], v[200:203], v[4:7]
	v_mfma_f32_16x16x32_bf16 v[16:19], v[168:171], v[208:211], v[16:19]
	v_mfma_f32_16x16x32_bf16 v[0:3], v[176:179], v[208:211], v[0:3]
	s_setprio 0
	s_barrier
	s_add_i32 s79, 0, 0x18000
	s_add_i32 vcc_lo, 0, 0x1c000
	v_add_u32_e32 v140, s79, v219
	v_add_u32_e32 v154, vcc_lo, v219
	ds_read_b128 v[128:131], v140
	ds_read_b128 v[132:135], v140 offset:1024
	ds_read_b128 v[136:139], v140 offset:2048
	ds_read_b128 v[140:143], v140 offset:3072
	ds_read_b128 v[164:167], v154
	ds_read_b128 v[168:171], v154 offset:1024
	ds_read_b128 v[172:175], v154 offset:2048
	ds_read_b128 v[176:179], v154 offset:3072
	s_add_u32 s10, s10, 0x80000
	s_addc_u32 s11, s11, 0
	s_mov_b32 m0, s65
	v_lshl_add_u64 v[230:231], s[10:11], 0, v[146:147]
	ds_read_b128 v[180:183], v222 offset:32768
	ds_read_b128 v[184:187], v222 offset:33792
	ds_read_b128 v[188:191], v222 offset:34816
	ds_read_b128 v[192:195], v222 offset:35840
	ds_read_b128 v[196:199], v222 offset:36864
	ds_read_b128 v[200:203], v222 offset:37888
	ds_read_b128 v[204:207], v222 offset:38912
	ds_read_b128 v[208:211], v222 offset:39936
	global_load_lds_dwordx4 v[230:231], off
	v_lshl_add_u64 v[230:231], s[10:11], 0, v[150:151]
	s_mov_b32 m0, s67
	s_nop 0
	global_load_lds_dwordx4 v[230:231], off
	s_waitcnt vmcnt(8)
	s_waitcnt lgkmcnt(0)
	s_barrier
	s_setprio 1
	v_mfma_f32_16x16x32_bf16 v[124:127], v[128:131], v[180:183], v[124:127]
	v_mfma_f32_16x16x32_bf16 v[116:119], v[136:139], v[180:183], v[116:119]
	v_mfma_f32_16x16x32_bf16 v[120:123], v[128:131], v[188:191], v[120:123]
	v_mfma_f32_16x16x32_bf16 v[112:115], v[136:139], v[188:191], v[112:115]
	v_mfma_f32_16x16x32_bf16 v[104:107], v[128:131], v[196:199], v[104:107]
	v_mfma_f32_16x16x32_bf16 v[108:111], v[136:139], v[196:199], v[108:111]
	v_mfma_f32_16x16x32_bf16 v[80:83], v[128:131], v[204:207], v[80:83]
	v_mfma_f32_16x16x32_bf16 v[92:95], v[136:139], v[204:207], v[92:95]
	v_mfma_f32_16x16x32_bf16 v[124:127], v[132:135], v[184:187], v[124:127]
	v_mfma_f32_16x16x32_bf16 v[116:119], v[140:143], v[184:187], v[116:119]
	v_mfma_f32_16x16x32_bf16 v[120:123], v[132:135], v[192:195], v[120:123]
	v_mfma_f32_16x16x32_bf16 v[112:115], v[140:143], v[192:195], v[112:115]
	v_mfma_f32_16x16x32_bf16 v[104:107], v[132:135], v[200:203], v[104:107]
	v_mfma_f32_16x16x32_bf16 v[108:111], v[140:143], v[200:203], v[108:111]
	v_mfma_f32_16x16x32_bf16 v[80:83], v[132:135], v[208:211], v[80:83]
	v_mfma_f32_16x16x32_bf16 v[92:95], v[140:143], v[208:211], v[92:95]
	s_setprio 0
	s_setprio 1
	v_mfma_f32_16x16x32_bf16 v[100:103], v[164:167], v[180:183], v[100:103]
	v_mfma_f32_16x16x32_bf16 v[76:79], v[172:175], v[180:183], v[76:79]
	v_mfma_f32_16x16x32_bf16 v[96:99], v[164:167], v[188:191], v[96:99]
	v_mfma_f32_16x16x32_bf16 v[72:75], v[172:175], v[188:191], v[72:75]
	v_mfma_f32_16x16x32_bf16 v[88:91], v[164:167], v[196:199], v[88:91]
	v_mfma_f32_16x16x32_bf16 v[68:71], v[172:175], v[196:199], v[68:71]
	v_mfma_f32_16x16x32_bf16 v[84:87], v[164:167], v[204:207], v[84:87]
	v_mfma_f32_16x16x32_bf16 v[64:67], v[172:175], v[204:207], v[64:67]
	v_mfma_f32_16x16x32_bf16 v[100:103], v[168:171], v[184:187], v[100:103]
	v_mfma_f32_16x16x32_bf16 v[76:79], v[176:179], v[184:187], v[76:79]
	v_mfma_f32_16x16x32_bf16 v[96:99], v[168:171], v[192:195], v[96:99]
	v_mfma_f32_16x16x32_bf16 v[72:75], v[176:179], v[192:195], v[72:75]
	v_mfma_f32_16x16x32_bf16 v[88:91], v[168:171], v[200:203], v[88:91]
	v_mfma_f32_16x16x32_bf16 v[68:71], v[176:179], v[200:203], v[68:71]
	v_mfma_f32_16x16x32_bf16 v[84:87], v[168:171], v[208:211], v[84:87]
	v_mfma_f32_16x16x32_bf16 v[64:67], v[176:179], v[208:211], v[64:67]
	s_setprio 0
	s_barrier
; #define PG8_STAGE(bufoff, gbase, voff) do { _Pragma("unroll") for (int _i = 0; _i < 2; ++_i) \
;         __builtin_amdgcn_global_load_lds((const unsigned*)((const char*)(gbase) + (voff)[_i]), (PG8_LAS unsigned*)(lds + (bufoff) + ldsw + _i * 8192), 16, 0, 0); } while (0)
; #define PG8_LDA(dst, b, h) do { _Pragma("unroll") for (int m = 0; m < 4; ++m) _Pragma("unroll") for (int k = 0; k < 2; ++k) dst[m][k] = *(const PG8_LAS bf16x8*)(lds + PG8_SA(b, h) + aoff + m * 2048 + k * 1024); } while (0)
; #define PG8_MMA(ai, bj, At, Bt) do { __builtin_amdgcn_s_setprio(1); _Pragma("unroll") for (int m = 0; m < 4; ++m) _Pragma("unroll") for (int n = 0; n < 2; ++n) _Pragma("unroll") for (int k = 0; k < 2; ++k) \
;         acc[ai][bj][m][n] = __builtin_amdgcn_mfma_f32_16x16x32_bf16(Bt[n][k], At[m][k], acc[ai][bj][m][n], 0, 0, 0); __builtin_amdgcn_s_setprio(0); } while (0)
; #define PG8_WAIT_V(n) asm volatile("s_waitcnt vmcnt(" #n ")" ::: "memory")
; #define PG8_WAIT_L(n) asm volatile("s_waitcnt lgkmcnt(" #n ")" ::: "memory")
; #define PG8_BAR __builtin_amdgcn_s_barrier()
; #define PG8_SCHED __builtin_amdgcn_sched_barrier(0)
; template <class Epi, class Sched, bool ALIGN_EPI = false, bool SP2 = false>
; __device__ __forceinline__ void gemm_phase(PG8_LAS unsigned char* lds, const Gemm g, const Sched& S, const Epi& E) {
;     ...
;         for (int t = 0; t < nt; t += 2) {
;     ...
;             PG8_LDA(At, 1, 1); PG8_STAGE(PG8_SB(1, 0), b3, voffB); PG8_STAGE(PG8_SB(1, 1), b3 + hstep, voffB); PG8_STAGE(PG8_SA(1, 0), a3, voffA);
;             PG8_WAIT_V(8); PG8_WAIT_L(0); PG8_BAR; PG8_MMA(1, 0, At, B0); PG8_MMA(1, 1, At, B1); PG8_BAR; PG8_SCHED;
	s_add_i32 s10, s79, s59
	v_lshl_add_u64 v[212:213], v[212:213], 0, s[46:47]
	s_mov_b32 m0, s10
	ds_read_b128 v[180:183], v222 offset:49152
	ds_read_b128 v[184:187], v222 offset:50176
	ds_read_b128 v[188:191], v222 offset:51200
	ds_read_b128 v[192:195], v222 offset:52224
	ds_read_b128 v[196:199], v222 offset:53248
	ds_read_b128 v[200:203], v222 offset:54272
	ds_read_b128 v[204:207], v222 offset:55296
	ds_read_b128 v[208:211], v222 offset:56320
	global_load_lds_dwordx4 v[212:213], off
	s_add_i32 m0, s10, 0x2000
	s_add_u32 s8, s8, 0x80080
	v_lshl_add_u64 v[212:213], v[214:215], 0, s[46:47]
	s_addc_u32 s9, s9, 0
	s_add_i32 s10, vcc_lo, s59
	global_load_lds_dwordx4 v[212:213], off
	v_lshl_add_u64 v[212:213], s[8:9], 0, v[148:149]
	s_mov_b32 m0, s10
	s_nop 0
	global_load_lds_dwordx4 v[212:213], off
	v_lshl_add_u64 v[212:213], s[8:9], 0, v[152:153]
	s_add_i32 m0, s10, 0x2000
	s_nop 0
	global_load_lds_dwordx4 v[212:213], off
	v_lshl_add_u64 v[212:213], v[226:227], 0, s[46:47]
	s_mov_b32 m0, s84
	s_nop 0
	global_load_lds_dwordx4 v[212:213], off
	v_lshl_add_u64 v[212:213], v[228:229], 0, s[46:47]
	s_mov_b32 m0, s85
	s_nop 0
	global_load_lds_dwordx4 v[212:213], off
	s_waitcnt vmcnt(8)
	s_waitcnt lgkmcnt(0)
	s_barrier
	s_setprio 1
	v_mfma_f32_16x16x32_bf16 v[60:63], v[128:131], v[180:183], v[60:63]
	v_mfma_f32_16x16x32_bf16 v[44:47], v[136:139], v[180:183], v[44:47]
	v_mfma_f32_16x16x32_bf16 v[56:59], v[128:131], v[188:191], v[56:59]
	v_mfma_f32_16x16x32_bf16 v[40:43], v[136:139], v[188:191], v[40:43]
	v_mfma_f32_16x16x32_bf16 v[52:55], v[128:131], v[196:199], v[52:55]
	v_mfma_f32_16x16x32_bf16 v[36:39], v[136:139], v[196:199], v[36:39]
	v_mfma_f32_16x16x32_bf16 v[48:51], v[128:131], v[204:207], v[48:51]
	v_mfma_f32_16x16x32_bf16 v[32:35], v[136:139], v[204:207], v[32:35]
	v_mfma_f32_16x16x32_bf16 v[60:63], v[132:135], v[184:187], v[60:63]
	v_mfma_f32_16x16x32_bf16 v[44:47], v[140:143], v[184:187], v[44:47]
	v_mfma_f32_16x16x32_bf16 v[56:59], v[132:135], v[192:195], v[56:59]
	v_mfma_f32_16x16x32_bf16 v[40:43], v[140:143], v[192:195], v[40:43]
	v_mfma_f32_16x16x32_bf16 v[52:55], v[132:135], v[200:203], v[52:55]
	v_mfma_f32_16x16x32_bf16 v[36:39], v[140:143], v[200:203], v[36:39]
	v_mfma_f32_16x16x32_bf16 v[48:51], v[132:135], v[208:211], v[48:51]
	v_mfma_f32_16x16x32_bf16 v[32:35], v[140:143], v[208:211], v[32:35]
	s_setprio 0
	s_setprio 1
	v_mfma_f32_16x16x32_bf16 v[28:31], v[164:167], v[180:183], v[28:31]
	v_mfma_f32_16x16x32_bf16 v[12:15], v[172:175], v[180:183], v[12:15]
	v_mfma_f32_16x16x32_bf16 v[24:27], v[164:167], v[188:191], v[24:27]
	v_mfma_f32_16x16x32_bf16 v[8:11], v[172:175], v[188:191], v[8:11]
	v_mfma_f32_16x16x32_bf16 v[20:23], v[164:167], v[196:199], v[20:23]
	v_mfma_f32_16x16x32_bf16 v[4:7], v[172:175], v[196:199], v[4:7]
	v_mfma_f32_16x16x32_bf16 v[16:19], v[164:167], v[204:207], v[16:19]
	v_mfma_f32_16x16x32_bf16 v[0:3], v[172:175], v[204:207], v[0:3]
	v_mfma_f32_16x16x32_bf16 v[28:31], v[168:171], v[184:187], v[28:31]
	v_mfma_f32_16x16x32_bf16 v[12:15], v[176:179], v[184:187], v[12:15]
	v_mfma_f32_16x16x32_bf16 v[24:27], v[168:171], v[192:195], v[24:27]
	v_mfma_f32_16x16x32_bf16 v[8:11], v[176:179], v[192:195], v[8:11]
	v_mfma_f32_16x16x32_bf16 v[20:23], v[168:171], v[200:203], v[20:23]
	v_mfma_f32_16x16x32_bf16 v[4:7], v[176:179], v[200:203], v[4:7]
	v_mfma_f32_16x16x32_bf16 v[16:19], v[168:171], v[208:211], v[16:19]
	v_mfma_f32_16x16x32_bf16 v[0:3], v[176:179], v[208:211], v[0:3]
	s_setprio 0
	s_barrier
	s_add_i32 s73, s73, 2
	s_add_u32 s0, s0, 0x100
	s_addc_u32 s1, s1, 0
	s_add_u32 s37, s37, 0x100
	s_addc_u32 s71, s71, 0
	s_cmp_gt_u32 s73, 29

; #define PG8_STAGE(bufoff, gbase, voff) do { _Pragma("unroll") for (int _i = 0; _i < 2; ++_i) \
;         __builtin_amdgcn_global_load_lds((const unsigned*)((const char*)(gbase) + (voff)[_i]), (PG8_LAS unsigned*)(lds + (bufoff) + ldsw + _i * 8192), 16, 0, 0); } while (0)
; #define PG8_LDA(dst, b, h) do { _Pragma("unroll") for (int m = 0; m < 4; ++m) _Pragma("unroll") for (int k = 0; k < 2; ++k) dst[m][k] = *(const PG8_LAS bf16x8*)(lds + PG8_SA(b, h) + aoff + m * 2048 + k * 1024); } while (0)
; #define PG8_LDB(dst, b, h) do { _Pragma("unroll") for (int n = 0; n < 2; ++n) _Pragma("unroll") for (int k = 0; k < 2; ++k) dst[n][k] = *(const PG8_LAS bf16x8*)(lds + PG8_SB(b, h) + boff + n * 2048 + k * 1024); } while (0)
; #define PG8_WAIT_V(n) asm volatile("s_waitcnt vmcnt(" #n ")" ::: "memory")
; #define PG8_WAIT_L(n) asm volatile("s_waitcnt lgkmcnt(" #n ")" ::: "memory")
; #define PG8_BAR __builtin_amdgcn_s_barrier()
; #define PG8_SCHED __builtin_amdgcn_sched_barrier(0)
; template <class Epi, class Sched, bool ALIGN_EPI = false, bool SP2 = false>
; __device__ __forceinline__ void gemm_phase(PG8_LAS unsigned char* lds, const Gemm g, const Sched& S, const Epi& E) {
;     ...
;         const bool has_next = S.next(ui + 1, nxt);
;         const char* nA = has_next ? (const char*)g.A + (size_t)nxt.pm * tstep : cA; const char* nB = has_next ? (const char*)g.Bt + (size_t)nxt.pn * tstep : cB;
;         for (int t = 0; t < nt; t += 2) {
;             const bool last = (t == nt - 2);
;             const char* a1 = cA + (size_t)(t + 1) * kstep;
;             const char* a2 = last ? nA : cA + (size_t)(t + 2) * kstep; const char* b2 = last ? nB : cB + (size_t)(t + 2) * kstep;
;             const char* a3 = a2 + kstep; const char* b3 = b2 + kstep;
;             if (last && has_next) S.a_ready(nxt);
;             if constexpr (SP2) {
;             PG8_LDB(B0, 0, 0); PG8_LDB(B1, 0, 1); PG8_SCHED; PG8_LDA(At, 0, 0); PG8_STAGE(PG8_SA(1, 1), a1 + hstep, voffA);
;             PG8_WAIT_V(8); PG8_WAIT_L(0); PG8_BAR; PG8_MMA(0, 0, At, B0); PG8_MMA(0, 1, At, B1); PG8_BAR; PG8_SCHED;
;             PG8_LDA(At, 0, 1); PG8_STAGE(PG8_SB(0, 0), b2, voffB); PG8_STAGE(PG8_SB(0, 1), b2 + hstep, voffB); PG8_STAGE(PG8_SA(0, 0), a2, voffA);
;             PG8_WAIT_V(8); PG8_WAIT_L(0); PG8_BAR; PG8_MMA(1, 0, At, B0); PG8_MMA(1, 1, At, B1); PG8_BAR; PG8_SCHED;
.LBB0_1923:
	s_add_u32 s22, s22, 0x160080
	s_addc_u32 s23, s23, 0
	s_add_u32 s61, s36, 0x100
	s_addc_u32 s62, s37, 0
	s_mov_b32 s63, -2
	s_waitcnt lgkmcnt(0)
	ds_read_b128 v[146:149], v153
	ds_read_b128 v[158:161], v153 offset:1024
	ds_read_b128 v[162:165], v153 offset:2048
	ds_read_b128 v[166:169], v153 offset:3072
	ds_read_b128 v[170:173], v154
	ds_read_b128 v[174:177], v154 offset:1024
	ds_read_b128 v[178:181], v154 offset:2048
	ds_read_b128 v[182:185], v154 offset:3072
	s_add_u32 s36, s22, 0xffea0080
	s_addc_u32 s37, s23, -1
	s_cmpk_eq_i32 s63, 0x54
	s_cselect_b32 s39, s5, s37
	s_cselect_b32 s38, s4, s36
	s_cselect_b32 s37, s21, s62
	s_cselect_b32 s36, s20, s61
	v_lshl_add_u64 v[218:219], s[22:23], 0, v[136:137]
	s_add_i32 m0, s43, 0xc000
	ds_read_b128 v[186:189], v155
	ds_read_b128 v[190:193], v155 offset:1024
	ds_read_b128 v[194:197], v155 offset:2048
	ds_read_b128 v[198:201], v155 offset:3072
	ds_read_b128 v[202:205], v155 offset:4096
	ds_read_b128 v[206:209], v155 offset:5120
	ds_read_b128 v[210:213], v155 offset:6144
	ds_read_b128 v[214:217], v155 offset:7168
	global_load_lds_dwordx4 v[218:219], off
	v_lshl_add_u64 v[218:219], s[22:23], 0, v[138:139]
	s_add_i32 m0, s43, 0xe000
	s_nop 0
	global_load_lds_dwordx4 v[218:219], off
	s_waitcnt vmcnt(8)
	s_waitcnt lgkmcnt(0)
	s_barrier
	s_setprio 1
	v_mfma_f32_16x16x32_bf16 v[124:127], v[146:149], v[186:189], 0
	v_mfma_f32_16x16x32_bf16 v[120:123], v[162:165], v[186:189], 0
	v_mfma_f32_16x16x32_bf16 v[108:111], v[146:149], v[194:197], 0
	v_mfma_f32_16x16x32_bf16 v[104:107], v[162:165], v[194:197], 0
	v_mfma_f32_16x16x32_bf16 v[92:95], v[146:149], v[202:205], 0
	v_mfma_f32_16x16x32_bf16 v[88:91], v[162:165], v[202:205], 0
	v_mfma_f32_16x16x32_bf16 v[76:79], v[146:149], v[210:213], 0
	v_mfma_f32_16x16x32_bf16 v[72:75], v[162:165], v[210:213], 0
	v_mfma_f32_16x16x32_bf16 v[124:127], v[158:161], v[190:193], v[124:127]
	v_mfma_f32_16x16x32_bf16 v[120:123], v[166:169], v[190:193], v[120:123]
	v_mfma_f32_16x16x32_bf16 v[108:111], v[158:161], v[198:201], v[108:111]
	v_mfma_f32_16x16x32_bf16 v[104:107], v[166:169], v[198:201], v[104:107]
	v_mfma_f32_16x16x32_bf16 v[92:95], v[158:161], v[206:209], v[92:95]
	v_mfma_f32_16x16x32_bf16 v[88:91], v[166:169], v[206:209], v[88:91]
	v_mfma_f32_16x16x32_bf16 v[76:79], v[158:161], v[214:217], v[76:79]
	v_mfma_f32_16x16x32_bf16 v[72:75], v[166:169], v[214:217], v[72:75]
	s_setprio 0
	s_setprio 1
	v_mfma_f32_16x16x32_bf16 v[116:119], v[170:173], v[186:189], 0
	v_mfma_f32_16x16x32_bf16 v[112:115], v[178:181], v[186:189], 0
	v_mfma_f32_16x16x32_bf16 v[100:103], v[170:173], v[194:197], 0
	v_mfma_f32_16x16x32_bf16 v[96:99], v[178:181], v[194:197], 0
	v_mfma_f32_16x16x32_bf16 v[84:87], v[170:173], v[202:205], 0
	v_mfma_f32_16x16x32_bf16 v[80:83], v[178:181], v[202:205], 0
	v_mfma_f32_16x16x32_bf16 v[68:71], v[170:173], v[210:213], 0
	v_mfma_f32_16x16x32_bf16 v[64:67], v[178:181], v[210:213], 0
	v_mfma_f32_16x16x32_bf16 v[116:119], v[174:177], v[190:193], v[116:119]
	v_mfma_f32_16x16x32_bf16 v[112:115], v[182:185], v[190:193], v[112:115]
	v_mfma_f32_16x16x32_bf16 v[100:103], v[174:177], v[198:201], v[100:103]
	v_mfma_f32_16x16x32_bf16 v[96:99], v[182:185], v[198:201], v[96:99]
	v_mfma_f32_16x16x32_bf16 v[84:87], v[174:177], v[206:209], v[84:87]
	v_mfma_f32_16x16x32_bf16 v[80:83], v[182:185], v[206:209], v[80:83]
	v_mfma_f32_16x16x32_bf16 v[68:71], v[174:177], v[214:217], v[68:71]
	v_mfma_f32_16x16x32_bf16 v[64:67], v[182:185], v[214:217], v[64:67]
	s_setprio 0
	s_barrier
	s_add_i32 s64, s55, s42
	v_lshl_add_u64 v[218:219], s[36:37], 0, v[130:131]
	s_mov_b32 m0, s64
	ds_read_b128 v[186:189], v155 offset:16384
	ds_read_b128 v[190:193], v155 offset:17408
	ds_read_b128 v[194:197], v155 offset:18432
	ds_read_b128 v[198:201], v155 offset:19456
	ds_read_b128 v[202:205], v155 offset:20480
	ds_read_b128 v[206:209], v155 offset:21504
	ds_read_b128 v[210:213], v155 offset:22528
	ds_read_b128 v[214:217], v155 offset:23552
	global_load_lds_dwordx4 v[218:219], off
	s_add_i32 m0, s64, 0x2000
	s_add_u32 s64, s36, 0x160000
	v_lshl_add_u64 v[220:221], s[36:37], 0, v[134:135]
	s_addc_u32 s65, s37, 0
	s_add_i32 s66, s56, s42
	global_load_lds_dwordx4 v[220:221], off
	v_lshl_add_u64 v[222:223], s[64:65], 0, v[130:131]
	s_mov_b32 m0, s66
	v_lshl_add_u64 v[224:225], s[38:39], 0, v[132:133]
	global_load_lds_dwordx4 v[222:223], off
	v_lshl_add_u64 v[222:223], s[64:65], 0, v[134:135]
	s_add_i32 m0, s66, 0x2000
	s_nop 0
	global_load_lds_dwordx4 v[222:223], off
	v_lshl_add_u64 v[222:223], s[38:39], 0, v[128:129]
	s_mov_b32 m0, s43
	s_nop 0
	global_load_lds_dwordx4 v[222:223], off
	s_mov_b32 m0, s44
	s_nop 0
	global_load_lds_dwordx4 v[224:225], off
	s_waitcnt vmcnt(8)
	s_waitcnt lgkmcnt(0)
	s_barrier
; #define PG8_STAGE(bufoff, gbase, voff) do { _Pragma("unroll") for (int _i = 0; _i < 2; ++_i) \
;         __builtin_amdgcn_global_load_lds((const unsigned*)((const char*)(gbase) + (voff)[_i]), (PG8_LAS unsigned*)(lds + (bufoff) + ldsw + _i * 8192), 16, 0, 0); } while (0)
; #define PG8_LDA(dst, b, h) do { _Pragma("unroll") for (int m = 0; m < 4; ++m) _Pragma("unroll") for (int k = 0; k < 2; ++k) dst[m][k] = *(const PG8_LAS bf16x8*)(lds + PG8_SA(b, h) + aoff + m * 2048 + k * 1024); } while (0)
; #define PG8_LDB(dst, b, h) do { _Pragma("unroll") for (int n = 0; n < 2; ++n) _Pragma("unroll") for (int k = 0; k < 2; ++k) dst[n][k] = *(const PG8_LAS bf16x8*)(lds + PG8_SB(b, h) + boff + n * 2048 + k * 1024); } while (0)
; #define PG8_MMA(ai, bj, At, Bt) do { __builtin_amdgcn_s_setprio(1); _Pragma("unroll") for (int m = 0; m < 4; ++m) _Pragma("unroll") for (int n = 0; n < 2; ++n) _Pragma("unroll") for (int k = 0; k < 2; ++k) \
;         acc[ai][bj][m][n] = __builtin_amdgcn_mfma_f32_16x16x32_bf16(Bt[n][k], At[m][k], acc[ai][bj][m][n], 0, 0, 0); __builtin_amdgcn_s_setprio(0); } while (0)
; #define PG8_WAIT_V(n) asm volatile("s_waitcnt vmcnt(" #n ")" ::: "memory")
; #define PG8_WAIT_L(n) asm volatile("s_waitcnt lgkmcnt(" #n ")" ::: "memory")
; #define PG8_BAR __builtin_amdgcn_s_barrier()
; #define PG8_SCHED __builtin_amdgcn_sched_barrier(0)
; template <class Epi, class Sched, bool ALIGN_EPI = false, bool SP2 = false>
; __device__ __forceinline__ void gemm_phase(PG8_LAS unsigned char* lds, const Gemm g, const Sched& S, const Epi& E) {
;     ...
;             PG8_WAIT_V(8); PG8_WAIT_L(0); PG8_BAR; PG8_MMA(1, 0, At, B0); PG8_MMA(1, 1, At, B1); PG8_BAR; PG8_SCHED;
;             PG8_LDB(B0, 1, 0); PG8_LDB(B1, 1, 1); PG8_SCHED; PG8_LDA(At, 1, 0); PG8_STAGE(PG8_SA(0, 1), a2 + hstep, voffA);
;             PG8_WAIT_V(8); PG8_WAIT_L(0); PG8_BAR; PG8_MMA(0, 0, At, B0); PG8_MMA(0, 1, At, B1); PG8_BAR; PG8_SCHED;
;             PG8_LDA(At, 1, 1); PG8_STAGE(PG8_SB(1, 0), b3, voffB); PG8_STAGE(PG8_SB(1, 1), b3 + hstep, voffB); PG8_STAGE(PG8_SA(1, 0), a3, voffA);
;             PG8_WAIT_V(8); PG8_WAIT_L(0); PG8_BAR; PG8_MMA(1, 0, At, B0); PG8_MMA(1, 1, At, B1); PG8_BAR; PG8_SCHED;
	s_setprio 1
	v_mfma_f32_16x16x32_bf16 v[60:63], v[146:149], v[186:189], 0
	v_mfma_f32_16x16x32_bf16 v[56:59], v[162:165], v[186:189], 0
	v_mfma_f32_16x16x32_bf16 v[44:47], v[146:149], v[194:197], 0
	v_mfma_f32_16x16x32_bf16 v[40:43], v[162:165], v[194:197], 0
	v_mfma_f32_16x16x32_bf16 v[28:31], v[146:149], v[202:205], 0
	v_mfma_f32_16x16x32_bf16 v[24:27], v[162:165], v[202:205], 0
	v_mfma_f32_16x16x32_bf16 v[12:15], v[146:149], v[210:213], 0
	v_mfma_f32_16x16x32_bf16 v[8:11], v[162:165], v[210:213], 0
	v_mfma_f32_16x16x32_bf16 v[60:63], v[158:161], v[190:193], v[60:63]
	v_mfma_f32_16x16x32_bf16 v[56:59], v[166:169], v[190:193], v[56:59]
	v_mfma_f32_16x16x32_bf16 v[44:47], v[158:161], v[198:201], v[44:47]
	v_mfma_f32_16x16x32_bf16 v[40:43], v[166:169], v[198:201], v[40:43]
	v_mfma_f32_16x16x32_bf16 v[28:31], v[158:161], v[206:209], v[28:31]
	v_mfma_f32_16x16x32_bf16 v[24:27], v[166:169], v[206:209], v[24:27]
	v_mfma_f32_16x16x32_bf16 v[12:15], v[158:161], v[214:217], v[12:15]
	v_mfma_f32_16x16x32_bf16 v[8:11], v[166:169], v[214:217], v[8:11]
	s_setprio 0
	s_setprio 1
	v_mfma_f32_16x16x32_bf16 v[52:55], v[170:173], v[186:189], 0
	v_mfma_f32_16x16x32_bf16 v[48:51], v[178:181], v[186:189], 0
	v_mfma_f32_16x16x32_bf16 v[36:39], v[170:173], v[194:197], 0
	v_mfma_f32_16x16x32_bf16 v[32:35], v[178:181], v[194:197], 0
	v_mfma_f32_16x16x32_bf16 v[20:23], v[170:173], v[202:205], 0
	v_mfma_f32_16x16x32_bf16 v[16:19], v[178:181], v[202:205], 0
	v_mfma_f32_16x16x32_bf16 v[4:7], v[170:173], v[210:213], 0
	v_mfma_f32_16x16x32_bf16 v[0:3], v[178:181], v[210:213], 0
	v_mfma_f32_16x16x32_bf16 v[52:55], v[174:177], v[190:193], v[52:55]
	v_mfma_f32_16x16x32_bf16 v[48:51], v[182:185], v[190:193], v[48:51]
	v_mfma_f32_16x16x32_bf16 v[36:39], v[174:177], v[198:201], v[36:39]
	v_mfma_f32_16x16x32_bf16 v[32:35], v[182:185], v[198:201], v[32:35]
	v_mfma_f32_16x16x32_bf16 v[20:23], v[174:177], v[206:209], v[20:23]
	v_mfma_f32_16x16x32_bf16 v[16:19], v[182:185], v[206:209], v[16:19]
	v_mfma_f32_16x16x32_bf16 v[4:7], v[174:177], v[214:217], v[4:7]
	v_mfma_f32_16x16x32_bf16 v[0:3], v[182:185], v[214:217], v[0:3]
	s_setprio 0
	s_barrier
	s_add_i32 s64, 0, 0x18000
	v_add_u32_e32 v157, s64, v152
	s_add_i32 s65, 0, 0x1c000
	ds_read_b128 v[146:149], v157
	ds_read_b128 v[158:161], v157 offset:1024
	ds_read_b128 v[162:165], v157 offset:2048
	ds_read_b128 v[166:169], v157 offset:3072
	v_add_u32_e32 v157, s65, v152
	ds_read_b128 v[170:173], v157
	ds_read_b128 v[174:177], v157 offset:1024
	ds_read_b128 v[178:181], v157 offset:2048
	ds_read_b128 v[182:185], v157 offset:3072
	s_add_u32 s38, s38, 0x160000
	s_addc_u32 s39, s39, 0
	s_mov_b32 m0, s45
	v_lshl_add_u64 v[226:227], s[38:39], 0, v[128:129]
	ds_read_b128 v[186:189], v155 offset:32768
	ds_read_b128 v[190:193], v155 offset:33792
	ds_read_b128 v[194:197], v155 offset:34816
	ds_read_b128 v[198:201], v155 offset:35840
	ds_read_b128 v[202:205], v155 offset:36864
	ds_read_b128 v[206:209], v155 offset:37888
	ds_read_b128 v[210:213], v155 offset:38912
	ds_read_b128 v[214:217], v155 offset:39936
	global_load_lds_dwordx4 v[226:227], off
	v_lshl_add_u64 v[226:227], s[38:39], 0, v[132:133]
	s_mov_b32 m0, s46
	s_nop 0
	global_load_lds_dwordx4 v[226:227], off
	s_waitcnt vmcnt(8)
	s_waitcnt lgkmcnt(0)
	s_barrier
	s_setprio 1
	v_mfma_f32_16x16x32_bf16 v[124:127], v[146:149], v[186:189], v[124:127]
	v_mfma_f32_16x16x32_bf16 v[120:123], v[162:165], v[186:189], v[120:123]
	v_mfma_f32_16x16x32_bf16 v[108:111], v[146:149], v[194:197], v[108:111]
	v_mfma_f32_16x16x32_bf16 v[104:107], v[162:165], v[194:197], v[104:107]
	v_mfma_f32_16x16x32_bf16 v[92:95], v[146:149], v[202:205], v[92:95]
	v_mfma_f32_16x16x32_bf16 v[88:91], v[162:165], v[202:205], v[88:91]
	v_mfma_f32_16x16x32_bf16 v[76:79], v[146:149], v[210:213], v[76:79]
	v_mfma_f32_16x16x32_bf16 v[72:75], v[162:165], v[210:213], v[72:75]
	v_mfma_f32_16x16x32_bf16 v[124:127], v[158:161], v[190:193], v[124:127]
	v_mfma_f32_16x16x32_bf16 v[120:123], v[166:169], v[190:193], v[120:123]
	v_mfma_f32_16x16x32_bf16 v[108:111], v[158:161], v[198:201], v[108:111]
	v_mfma_f32_16x16x32_bf16 v[104:107], v[166:169], v[198:201], v[104:107]
	v_mfma_f32_16x16x32_bf16 v[92:95], v[158:161], v[206:209], v[92:95]
	v_mfma_f32_16x16x32_bf16 v[88:91], v[166:169], v[206:209], v[88:91]
	v_mfma_f32_16x16x32_bf16 v[76:79], v[158:161], v[214:217], v[76:79]
	v_mfma_f32_16x16x32_bf16 v[72:75], v[166:169], v[214:217], v[72:75]
	s_setprio 0
	s_setprio 1
	v_mfma_f32_16x16x32_bf16 v[116:119], v[170:173], v[186:189], v[116:119]
	v_mfma_f32_16x16x32_bf16 v[112:115], v[178:181], v[186:189], v[112:115]
	v_mfma_f32_16x16x32_bf16 v[100:103], v[170:173], v[194:197], v[100:103]
	v_mfma_f32_16x16x32_bf16 v[96:99], v[178:181], v[194:197], v[96:99]
	v_mfma_f32_16x16x32_bf16 v[84:87], v[170:173], v[202:205], v[84:87]
	v_mfma_f32_16x16x32_bf16 v[80:83], v[178:181], v[202:205], v[80:83]
	v_mfma_f32_16x16x32_bf16 v[68:71], v[170:173], v[210:213], v[68:71]
	v_mfma_f32_16x16x32_bf16 v[64:67], v[178:181], v[210:213], v[64:67]
	v_mfma_f32_16x16x32_bf16 v[116:119], v[174:177], v[190:193], v[116:119]
	v_mfma_f32_16x16x32_bf16 v[112:115], v[182:185], v[190:193], v[112:115]
	v_mfma_f32_16x16x32_bf16 v[100:103], v[174:177], v[198:201], v[100:103]
	v_mfma_f32_16x16x32_bf16 v[96:99], v[182:185], v[198:201], v[96:99]
	v_mfma_f32_16x16x32_bf16 v[84:87], v[174:177], v[206:209], v[84:87]
	v_mfma_f32_16x16x32_bf16 v[80:83], v[182:185], v[206:209], v[80:83]
	v_mfma_f32_16x16x32_bf16 v[68:71], v[174:177], v[214:217], v[68:71]
	v_mfma_f32_16x16x32_bf16 v[64:67], v[182:185], v[214:217], v[64:67]
	s_setprio 0
	s_barrier
; #define PG8_STAGE(bufoff, gbase, voff) do { _Pragma("unroll") for (int _i = 0; _i < 2; ++_i) \
;         __builtin_amdgcn_global_load_lds((const unsigned*)((const char*)(gbase) + (voff)[_i]), (PG8_LAS unsigned*)(lds + (bufoff) + ldsw + _i * 8192), 16, 0, 0); } while (0)
; #define PG8_LDA(dst, b, h) do { _Pragma("unroll") for (int m = 0; m < 4; ++m) _Pragma("unroll") for (int k = 0; k < 2; ++k) dst[m][k] = *(const PG8_LAS bf16x8*)(lds + PG8_SA(b, h) + aoff + m * 2048 + k * 1024); } while (0)
; #define PG8_MMA(ai, bj, At, Bt) do { __builtin_amdgcn_s_setprio(1); _Pragma("unroll") for (int m = 0; m < 4; ++m) _Pragma("unroll") for (int n = 0; n < 2; ++n) _Pragma("unroll") for (int k = 0; k < 2; ++k) \
;         acc[ai][bj][m][n] = __builtin_amdgcn_mfma_f32_16x16x32_bf16(Bt[n][k], At[m][k], acc[ai][bj][m][n], 0, 0, 0); __builtin_amdgcn_s_setprio(0); } while (0)
; #define PG8_WAIT_V(n) asm volatile("s_waitcnt vmcnt(" #n ")" ::: "memory")
; #define PG8_WAIT_L(n) asm volatile("s_waitcnt lgkmcnt(" #n ")" ::: "memory")
; #define PG8_BAR __builtin_amdgcn_s_barrier()
; #define PG8_SCHED __builtin_amdgcn_sched_barrier(0)
; template <class Epi, class Sched, bool ALIGN_EPI = false, bool SP2 = false>
; __device__ __forceinline__ void gemm_phase(PG8_LAS unsigned char* lds, const Gemm g, const Sched& S, const Epi& E) {
;     ...
;         for (int t = 0; t < nt; t += 2) {
;             const bool last = (t == nt - 2);
;             const char* a1 = cA + (size_t)(t + 1) * kstep;
;             const char* a2 = last ? nA : cA + (size_t)(t + 2) * kstep; const char* b2 = last ? nB : cB + (size_t)(t + 2) * kstep;
;             const char* a3 = a2 + kstep; const char* b3 = b2 + kstep;
;             if (last && has_next) S.a_ready(nxt);
;     ...
;             PG8_LDA(At, 1, 1); PG8_STAGE(PG8_SB(1, 0), b3, voffB); PG8_STAGE(PG8_SB(1, 1), b3 + hstep, voffB); PG8_STAGE(PG8_SA(1, 0), a3, voffA);
;             PG8_WAIT_V(8); PG8_WAIT_L(0); PG8_BAR; PG8_MMA(1, 0, At, B0); PG8_MMA(1, 1, At, B1); PG8_BAR; PG8_SCHED;
	s_add_i32 s38, s64, s42
	v_lshl_add_u64 v[218:219], v[218:219], 0, s[16:17]
	s_mov_b32 m0, s38
	ds_read_b128 v[186:189], v155 offset:49152
	ds_read_b128 v[190:193], v155 offset:50176
	ds_read_b128 v[194:197], v155 offset:51200
	ds_read_b128 v[198:201], v155 offset:52224
	ds_read_b128 v[202:205], v155 offset:53248
	ds_read_b128 v[206:209], v155 offset:54272
	ds_read_b128 v[210:213], v155 offset:55296
	ds_read_b128 v[214:217], v155 offset:56320
	global_load_lds_dwordx4 v[218:219], off
	s_add_i32 m0, s38, 0x2000
	s_add_u32 s36, s36, 0x160080
	v_lshl_add_u64 v[218:219], v[220:221], 0, s[16:17]
	s_addc_u32 s37, s37, 0
	s_add_i32 s38, s65, s42
	global_load_lds_dwordx4 v[218:219], off
	v_lshl_add_u64 v[218:219], s[36:37], 0, v[130:131]
	s_mov_b32 m0, s38
	s_nop 0
	global_load_lds_dwordx4 v[218:219], off
	v_lshl_add_u64 v[218:219], s[36:37], 0, v[134:135]
	s_add_i32 m0, s38, 0x2000
	s_nop 0
	global_load_lds_dwordx4 v[218:219], off
	v_lshl_add_u64 v[218:219], v[222:223], 0, s[16:17]
	s_mov_b32 m0, s52
	s_nop 0
	global_load_lds_dwordx4 v[218:219], off
	v_lshl_add_u64 v[218:219], v[224:225], 0, s[16:17]
	s_mov_b32 m0, s53
	s_nop 0
	global_load_lds_dwordx4 v[218:219], off
	s_waitcnt vmcnt(8)
	s_waitcnt lgkmcnt(0)
	s_barrier
	s_setprio 1
	v_mfma_f32_16x16x32_bf16 v[60:63], v[146:149], v[186:189], v[60:63]
	v_mfma_f32_16x16x32_bf16 v[56:59], v[162:165], v[186:189], v[56:59]
	v_mfma_f32_16x16x32_bf16 v[44:47], v[146:149], v[194:197], v[44:47]
	v_mfma_f32_16x16x32_bf16 v[40:43], v[162:165], v[194:197], v[40:43]
	v_mfma_f32_16x16x32_bf16 v[28:31], v[146:149], v[202:205], v[28:31]
	v_mfma_f32_16x16x32_bf16 v[24:27], v[162:165], v[202:205], v[24:27]
	v_mfma_f32_16x16x32_bf16 v[12:15], v[146:149], v[210:213], v[12:15]
	v_mfma_f32_16x16x32_bf16 v[8:11], v[162:165], v[210:213], v[8:11]
	v_mfma_f32_16x16x32_bf16 v[60:63], v[158:161], v[190:193], v[60:63]
	v_mfma_f32_16x16x32_bf16 v[56:59], v[166:169], v[190:193], v[56:59]
	v_mfma_f32_16x16x32_bf16 v[44:47], v[158:161], v[198:201], v[44:47]
	v_mfma_f32_16x16x32_bf16 v[40:43], v[166:169], v[198:201], v[40:43]
	v_mfma_f32_16x16x32_bf16 v[28:31], v[158:161], v[206:209], v[28:31]
	v_mfma_f32_16x16x32_bf16 v[24:27], v[166:169], v[206:209], v[24:27]
	v_mfma_f32_16x16x32_bf16 v[12:15], v[158:161], v[214:217], v[12:15]
	v_mfma_f32_16x16x32_bf16 v[8:11], v[166:169], v[214:217], v[8:11]
	s_setprio 0
	s_setprio 1
	v_mfma_f32_16x16x32_bf16 v[52:55], v[170:173], v[186:189], v[52:55]
	v_mfma_f32_16x16x32_bf16 v[48:51], v[178:181], v[186:189], v[48:51]
	v_mfma_f32_16x16x32_bf16 v[36:39], v[170:173], v[194:197], v[36:39]
	v_mfma_f32_16x16x32_bf16 v[32:35], v[178:181], v[194:197], v[32:35]
	v_mfma_f32_16x16x32_bf16 v[20:23], v[170:173], v[202:205], v[20:23]
	v_mfma_f32_16x16x32_bf16 v[16:19], v[178:181], v[202:205], v[16:19]
	v_mfma_f32_16x16x32_bf16 v[4:7], v[170:173], v[210:213], v[4:7]
	v_mfma_f32_16x16x32_bf16 v[0:3], v[178:181], v[210:213], v[0:3]
	v_mfma_f32_16x16x32_bf16 v[52:55], v[174:177], v[190:193], v[52:55]
	v_mfma_f32_16x16x32_bf16 v[48:51], v[182:185], v[190:193], v[48:51]
	v_mfma_f32_16x16x32_bf16 v[36:39], v[174:177], v[198:201], v[36:39]
	v_mfma_f32_16x16x32_bf16 v[32:35], v[182:185], v[198:201], v[32:35]
	v_mfma_f32_16x16x32_bf16 v[20:23], v[174:177], v[206:209], v[20:23]
	v_mfma_f32_16x16x32_bf16 v[16:19], v[182:185], v[206:209], v[16:19]
	v_mfma_f32_16x16x32_bf16 v[4:7], v[174:177], v[214:217], v[4:7]
	v_mfma_f32_16x16x32_bf16 v[0:3], v[182:185], v[214:217], v[0:3]
	s_setprio 0
	s_barrier
	s_add_i32 s63, s63, 2
	s_add_u32 s22, s22, 0x100
	s_addc_u32 s23, s23, 0
	s_add_u32 s61, s61, 0x100
	s_addc_u32 s62, s62, 0
	s_cmpk_gt_u32 s63, 0x55
